# combo26: combo23 + the remaining xor-16 / xor-32 butterfly steps of wave reductions (pass C, prenorm, bias_rows, EpiQN/EpiQR/EpiKV row sums) done with v_permlane16_swap / v_permlane32_swap instead of
# speedup vs baseline: 1.0023x; 1.0023x over previous
; __device__ __forceinline__ void prenorm_rows(const float* __restrict__ xin, bf16_t* __restrict__ an, float* __restrict__ rss, const float* __restrict__ modl, int coff) {
;     ...
;     for (int t = gw; t < T; t += NGW) {
;         const f32x4* xr = (const f32x4*)(xin + (size_t)t * DM) + lane; f32x4 v[4]; float ss = 0.f;
; #pragma unroll
;         for (int j = 0; j < 4; ++j) { v[j] = xr[64 * j]; ss += (v[j][0] * v[j][0] + v[j][1] * v[j][1]) + (v[j][2] * v[j][2] + v[j][3] * v[j][3]); }
;         ss = wave_sum(ss); if (lane == 0) rss[t] = ss;
.LBB0_117:
	global_load_dwordx4 v[0:3], v[24:25], off
	global_load_dwordx4 v[4:7], v[24:25], off offset:1024
	global_load_dwordx4 v[8:11], v[24:25], off offset:2048
	global_load_dwordx4 v[12:15], v[24:25], off offset:3072
	v_ashrrev_i32_e32 v76, 13, v16
	v_mul_i32_i24_e32 v78, 0x1800, v76
	v_ashrrev_i32_e32 v79, 31, v78
	v_lshl_add_u64 v[78:79], v[78:79], 2, s[76:77]
	v_lshl_add_u64 v[80:81], v[78:79], 0, s[12:13]
	v_lshl_add_u64 v[82:83], v[80:81], 0, v[26:27]
	global_load_dwordx4 v[60:63], v[82:83], off
	v_lshl_add_u64 v[82:83], v[80:81], 0, v[28:29]
	global_load_dwordx4 v[64:67], v[82:83], off
	v_lshl_add_u64 v[82:83], v[80:81], 0, v[18:19]
	global_load_dwordx4 v[68:71], v[82:83], off
	v_mov_b32_e32 v84, v30
	v_mov_b32_e32 v85, v19
	v_lshl_add_u64 v[82:83], v[80:81], 0, v[84:85]
	global_load_dwordx4 v[72:75], v[82:83], off
	s_waitcnt vmcnt(7)
	v_mul_f32_e32 v17, v1, v1
	v_mul_f32_e32 v31, v3, v3
	s_waitcnt vmcnt(6)
	v_mul_f32_e32 v38, v5, v5
	v_mul_f32_e32 v39, v7, v7
	s_waitcnt vmcnt(5)
	v_mul_f32_e32 v40, v9, v9
	v_mul_f32_e32 v41, v11, v11
	v_fmac_f32_e32 v17, v0, v0
	v_fmac_f32_e32 v31, v2, v2
	v_fmac_f32_e32 v38, v4, v4
	v_fmac_f32_e32 v39, v6, v6
	s_waitcnt vmcnt(4)
	v_mul_f32_e32 v43, v13, v13
	v_mul_f32_e32 v44, v15, v15
	v_fmac_f32_e32 v40, v8, v8
	v_fmac_f32_e32 v41, v10, v10
	v_add_f32_e32 v17, v17, v31
	v_add_f32_e32 v31, v38, v39
	v_fmac_f32_e32 v43, v12, v12
	v_fmac_f32_e32 v44, v14, v14
	v_add_f32_e32 v38, v40, v41
	v_add_f32_e32 v17, v17, v31
	v_add_f32_e32 v17, v17, v38
	v_add_f32_e32 v31, v43, v44
	v_add_f32_e32 v17, v17, v31
	s_nop 1
	v_add_f32_dpp v17, v17, v17 quad_perm:[1,0,3,2] row_mask:0xf bank_mask:0xf
	s_nop 1
	v_add_f32_dpp v17, v17, v17 quad_perm:[2,3,0,1] row_mask:0xf bank_mask:0xf
	s_nop 1
	v_add_f32_dpp v17, v17, v17 row_half_mirror row_mask:0xf bank_mask:0xf
	s_nop 1
	v_add_f32_dpp v17, v17, v17 row_mirror row_mask:0xf bank_mask:0xf
	s_waitcnt lgkmcnt(0)
	v_mov_b32_e32 v31, v17
	s_nop 1
	v_permlane16_swap_b32_e32 v17, v31
	v_add_f32_e32 v17, v17, v31
	v_mov_b32_e32 v31, v17
	s_nop 1
	v_permlane32_swap_b32_e32 v17, v31
	v_add_f32_e32 v77, v17, v31
	v_lshl_add_u64 v[86:87], s[90:91], 0, v[20:21]
	s_branch .LBB0_116

; __device__ __forceinline__ void bias_rows(const bf16_t* __restrict__ Wt, int N, const float* __restrict__ modl, int soff, float* __restrict__ bias) {
;     ...
;     for (int n = gw; n < N; n += NGW) {
;         const u32x4 w0 = *(const u32x4*)(Wt + (size_t)n * 1024 + 16 * lane), w1 = *(const u32x4*)(Wt + (size_t)n * 1024 + 16 * lane + 8);
;         float wf[16];
; #pragma unroll
;         for (int e2 = 0; e2 < 4; ++e2) { wf[2 * e2] = __uint_as_float(w0[e2] << 16); wf[2 * e2 + 1] = __uint_as_float(w0[e2] & 0xffff0000u);
;                                          wf[8 + 2 * e2] = __uint_as_float(w1[e2] << 16); wf[8 + 2 * e2 + 1] = __uint_as_float(w1[e2] & 0xffff0000u); }
; #pragma unroll
;         for (int b = 0; b < 4; ++b) { const float* sp = modl + (size_t)b * NMOD + soff + 16 * lane; float s = 0.f;
; #pragma unroll
;             for (int q = 0; q < 4; ++q) { const f32x4 sv = *(const f32x4*)(sp + 4 * q); s += (sv[0] * wf[4 * q] + sv[1] * wf[4 * q + 1]) + (sv[2] * wf[4 * q + 2] + sv[3] * wf[4 * q + 3]); }
;             s = wave_sum(s); if (lane == 0) bias[(size_t)b * N + n] = s; }
.LBB0_124:
	v_lshl_add_u64 v[70:71], s[90:91], 0, v[68:69]
	global_load_dwordx4 v[92:95], v[70:71], off offset:-16
	global_load_dwordx4 v[96:99], v[70:71], off
	s_waitcnt vmcnt(1)
	v_lshlrev_b32_e32 v86, 16, v92
	v_and_b32_e32 v90, 0xffff0000, v92
	v_and_b32_e32 v92, 0xffff0000, v93
	v_lshlrev_b32_e32 v88, 16, v93
	v_and_b32_e32 v91, 0xffff0000, v94
	v_and_b32_e32 v93, 0xffff0000, v95
	v_mul_f32_e32 v70, v1, v90
	v_mul_f32_e32 v71, v3, v92
	s_waitcnt vmcnt(0)
	v_and_b32_e32 v82, 0xffff0000, v96
	v_and_b32_e32 v84, 0xffff0000, v97
	v_lshlrev_b32_e32 v87, 16, v94
	v_lshlrev_b32_e32 v89, 16, v95
	v_mul_f32_e32 v94, v5, v91
	v_mul_f32_e32 v95, v7, v93
	v_fmac_f32_e32 v70, v0, v86
	v_fmac_f32_e32 v71, v2, v88
	v_lshlrev_b32_e32 v64, 16, v96
	v_lshlrev_b32_e32 v80, 16, v97
	v_and_b32_e32 v83, 0xffff0000, v98
	v_and_b32_e32 v85, 0xffff0000, v99
	v_mul_f32_e32 v96, v9, v82
	v_mul_f32_e32 v97, v11, v84
	v_fmac_f32_e32 v94, v4, v87
	v_fmac_f32_e32 v95, v6, v89
	v_add_f32_e32 v70, v70, v71
	s_waitcnt lgkmcnt(0)
	v_lshlrev_b32_e32 v79, 16, v98
	v_lshlrev_b32_e32 v81, 16, v99
	v_mul_f32_e32 v98, v13, v83
	v_mul_f32_e32 v99, v15, v85
	v_fmac_f32_e32 v96, v8, v64
	v_fmac_f32_e32 v97, v10, v80
	v_add_f32_e32 v71, v94, v95
	v_add_f32_e32 v70, 0, v70
	v_fmac_f32_e32 v98, v12, v79
	v_fmac_f32_e32 v99, v14, v81
	v_add_f32_e32 v94, v96, v97
	v_add_f32_e32 v70, v71, v70
	v_add_f32_e32 v70, v94, v70
	v_add_f32_e32 v71, v98, v99
	v_add_f32_e32 v70, v71, v70
	s_nop 1
	v_add_f32_dpp v70, v70, v70 quad_perm:[1,0,3,2] row_mask:0xf bank_mask:0xf
	s_nop 1
	v_add_f32_dpp v70, v70, v70 quad_perm:[2,3,0,1] row_mask:0xf bank_mask:0xf
	s_nop 1
	v_add_f32_dpp v70, v70, v70 row_half_mirror row_mask:0xf bank_mask:0xf
	s_nop 1
	v_add_f32_dpp v70, v70, v70 row_mirror row_mask:0xf bank_mask:0xf
	s_waitcnt lgkmcnt(0)
	v_mov_b32_e32 v71, v70
	s_nop 1
	v_permlane16_swap_b32_e32 v70, v71
	v_add_f32_e32 v94, v70, v71
	v_mov_b32_e32 v95, v94
	s_nop 1
	v_permlane32_swap_b32_e32 v94, v95
	v_lshl_add_u64 v[70:71], s[90:91], 0, v[66:67]
	s_and_saveexec_b64 s[40:41], s[2:3]
	s_cbranch_execz .LBB0_126
	s_waitcnt lgkmcnt(0)
	v_add_f32_e32 v96, v94, v95
	v_add_co_u32_e32 v94, vcc, 0x1f100000, v70
	s_nop 1
	v_addc_co_u32_e32 v95, vcc, 0, v71, vcc
	global_store_dword v[94:95], v96, off
.LBB0_126:
	s_or_b64 exec, exec, s[40:41]
	v_mul_f32_e32 v94, v25, v90
	s_waitcnt lgkmcnt(0)
	v_mul_f32_e32 v95, v27, v92
	v_fmac_f32_e32 v94, v24, v86
	v_fmac_f32_e32 v95, v26, v88
	v_add_f32_e32 v94, v94, v95
	v_mul_f32_e32 v95, v17, v91
	v_mul_f32_e32 v96, v19, v93
	v_fmac_f32_e32 v95, v16, v87
	v_fmac_f32_e32 v96, v18, v89
	v_add_f32_e32 v94, 0, v94
	v_add_f32_e32 v95, v95, v96
	v_add_f32_e32 v94, v95, v94
	v_mul_f32_e32 v95, v21, v82
	v_mul_f32_e32 v96, v23, v84
	v_fmac_f32_e32 v95, v20, v64
	v_fmac_f32_e32 v96, v22, v80
	v_add_f32_e32 v95, v95, v96
	v_add_f32_e32 v94, v95, v94
	v_mul_f32_e32 v95, v29, v83
	v_mul_f32_e32 v96, v31, v85
	v_fmac_f32_e32 v95, v28, v79
	v_fmac_f32_e32 v96, v30, v81
	v_add_f32_e32 v95, v95, v96
	v_add_f32_e32 v94, v95, v94
	s_nop 1
	v_add_f32_dpp v94, v94, v94 quad_perm:[1,0,3,2] row_mask:0xf bank_mask:0xf
	s_nop 1
	v_add_f32_dpp v94, v94, v94 quad_perm:[2,3,0,1] row_mask:0xf bank_mask:0xf
	s_nop 1
	v_add_f32_dpp v94, v94, v94 row_half_mirror row_mask:0xf bank_mask:0xf
	s_nop 1
	v_add_f32_dpp v94, v94, v94 row_mirror row_mask:0xf bank_mask:0xf
	s_waitcnt lgkmcnt(0)
	v_mov_b32_e32 v95, v94
	s_nop 1
	v_permlane16_swap_b32_e32 v94, v95
	v_add_f32_e32 v94, v94, v95
	v_mov_b32_e32 v95, v94
	s_nop 1
	v_permlane32_swap_b32_e32 v94, v95
	s_and_saveexec_b64 s[40:41], s[2:3]
	s_cbranch_execz .LBB0_128
	s_waitcnt lgkmcnt(0)
	v_add_f32_e32 v96, v94, v95
	v_add_co_u32_e32 v94, vcc, 0x1f102000, v70
	s_nop 1
	v_addc_co_u32_e32 v95, vcc, 0, v71, vcc
	global_store_dword v[94:95], v96, off
.LBB0_128:
	s_or_b64 exec, exec, s[40:41]
	v_mul_f32_e32 v94, v41, v90
	s_waitcnt lgkmcnt(0)
	v_mul_f32_e32 v95, v43, v92
	v_fmac_f32_e32 v94, v40, v86
	v_fmac_f32_e32 v95, v42, v88
	v_add_f32_e32 v94, v94, v95
	v_mul_f32_e32 v95, v33, v91
	v_mul_f32_e32 v96, v35, v93
	v_fmac_f32_e32 v95, v32, v87
	v_fmac_f32_e32 v96, v34, v89
	v_add_f32_e32 v94, 0, v94
	v_add_f32_e32 v95, v95, v96
	v_add_f32_e32 v94, v95, v94
	v_mul_f32_e32 v95, v37, v82
	v_mul_f32_e32 v96, v39, v84
	v_fmac_f32_e32 v95, v36, v64
	v_fmac_f32_e32 v96, v38, v80
	v_add_f32_e32 v95, v95, v96
	v_add_f32_e32 v94, v95, v94
	v_mul_f32_e32 v95, v45, v83
	v_mul_f32_e32 v96, v47, v85
	v_fmac_f32_e32 v95, v44, v79
	v_fmac_f32_e32 v96, v46, v81
	v_add_f32_e32 v95, v95, v96
	v_add_f32_e32 v94, v95, v94
	s_nop 1
	v_add_f32_dpp v94, v94, v94 quad_perm:[1,0,3,2] row_mask:0xf bank_mask:0xf
	s_nop 1
	v_add_f32_dpp v94, v94, v94 quad_perm:[2,3,0,1] row_mask:0xf bank_mask:0xf
	s_nop 1
	v_add_f32_dpp v94, v94, v94 row_half_mirror row_mask:0xf bank_mask:0xf
	s_nop 1
	v_add_f32_dpp v94, v94, v94 row_mirror row_mask:0xf bank_mask:0xf
	s_waitcnt lgkmcnt(0)
	v_mov_b32_e32 v95, v94
	s_nop 1
	v_permlane16_swap_b32_e32 v94, v95
	v_add_f32_e32 v94, v94, v95
	v_mov_b32_e32 v95, v94
	s_nop 1
	v_permlane32_swap_b32_e32 v94, v95
	s_and_saveexec_b64 s[40:41], s[2:3]
	s_cbranch_execz .LBB0_130
	s_waitcnt lgkmcnt(0)
	v_add_f32_e32 v96, v94, v95
	v_add_co_u32_e32 v94, vcc, 0x1f104000, v70
	s_nop 1
	v_addc_co_u32_e32 v95, vcc, 0, v71, vcc
	global_store_dword v[94:95], v96, off
.LBB0_130:
	s_or_b64 exec, exec, s[40:41]
	v_mul_f32_e32 v90, v57, v90
	v_fmac_f32_e32 v90, v56, v86
	v_mul_f32_e32 v86, v59, v92
	v_fmac_f32_e32 v86, v58, v88
	v_mul_f32_e32 v88, v49, v91
	v_mul_f32_e32 v82, v53, v82
	v_fmac_f32_e32 v88, v48, v87
	v_mul_f32_e32 v87, v51, v93
	v_fmac_f32_e32 v82, v52, v64
	v_mul_f32_e32 v64, v55, v84
	v_add_f32_e32 v86, v90, v86
	v_fmac_f32_e32 v87, v50, v89
	v_fmac_f32_e32 v64, v54, v80
	v_mul_f32_e32 v80, v61, v83
	v_add_f32_e32 v86, 0, v86
	v_add_f32_e32 v87, v88, v87
	v_fmac_f32_e32 v80, v60, v79
	v_mul_f32_e32 v79, v63, v85
	v_add_f32_e32 v86, v87, v86
	v_add_f32_e32 v64, v82, v64
	v_fmac_f32_e32 v79, v62, v81
	v_add_f32_e32 v64, v64, v86
	v_add_f32_e32 v79, v80, v79
	v_add_f32_e32 v64, v79, v64
	s_nop 1
	v_add_f32_dpp v64, v64, v64 quad_perm:[1,0,3,2] row_mask:0xf bank_mask:0xf
	s_nop 1
	v_add_f32_dpp v64, v64, v64 quad_perm:[2,3,0,1] row_mask:0xf bank_mask:0xf
	s_nop 1
	v_add_f32_dpp v64, v64, v64 row_half_mirror row_mask:0xf bank_mask:0xf
	s_nop 1
	v_add_f32_dpp v64, v64, v64 row_mirror row_mask:0xf bank_mask:0xf
	s_waitcnt lgkmcnt(0)
	v_mov_b32_e32 v79, v64
	s_nop 1
	v_permlane16_swap_b32_e32 v64, v79
	v_add_f32_e32 v64, v64, v79
	v_mov_b32_e32 v79, v64
	s_nop 1
	v_permlane32_swap_b32_e32 v64, v79
	s_and_saveexec_b64 s[40:41], s[2:3]
	s_cbranch_execz .LBB0_123
	v_add_co_u32_e32 v70, vcc, 0x1f106000, v70
	s_waitcnt lgkmcnt(0)
	v_add_f32_e32 v64, v64, v79
	v_addc_co_u32_e32 v71, vcc, 0, v71, vcc
	global_store_dword v[70:71], v64, off
	s_branch .LBB0_123

; __device__ __forceinline__ void bias_rows(const bf16_t* __restrict__ Wt, int N, const float* __restrict__ modl, int soff, float* __restrict__ bias) {
;     ...
;     for (int n = gw; n < N; n += NGW) {
;         const u32x4 w0 = *(const u32x4*)(Wt + (size_t)n * 1024 + 16 * lane), w1 = *(const u32x4*)(Wt + (size_t)n * 1024 + 16 * lane + 8);
;         float wf[16];
; #pragma unroll
;         for (int e2 = 0; e2 < 4; ++e2) { wf[2 * e2] = __uint_as_float(w0[e2] << 16); wf[2 * e2 + 1] = __uint_as_float(w0[e2] & 0xffff0000u);
;                                          wf[8 + 2 * e2] = __uint_as_float(w1[e2] << 16); wf[8 + 2 * e2 + 1] = __uint_as_float(w1[e2] & 0xffff0000u); }
; #pragma unroll
;         for (int b = 0; b < 4; ++b) { const float* sp = modl + (size_t)b * NMOD + soff + 16 * lane; float s = 0.f;
; #pragma unroll
;             for (int q = 0; q < 4; ++q) { const f32x4 sv = *(const f32x4*)(sp + 4 * q); s += (sv[0] * wf[4 * q] + sv[1] * wf[4 * q + 1]) + (sv[2] * wf[4 * q + 2] + sv[3] * wf[4 * q + 3]); }
;             s = wave_sum(s); if (lane == 0) bias[(size_t)b * N + n] = s; }
.LBB0_135:
	v_lshl_add_u64 v[70:71], s[90:91], 0, v[68:69]
	v_add_co_u32_e32 v80, vcc, 0x6a0000, v70
	s_nop 1
	v_addc_co_u32_e32 v81, vcc, 0, v71, vcc
	global_load_dwordx4 v[92:95], v[80:81], off
	v_lshl_add_u64 v[70:71], v[70:71], 0, s[26:27]
	global_load_dwordx4 v[96:99], v[70:71], off offset:16
	s_waitcnt vmcnt(1)
	v_lshlrev_b32_e32 v86, 16, v92
	v_and_b32_e32 v90, 0xffff0000, v92
	v_and_b32_e32 v92, 0xffff0000, v93
	v_lshlrev_b32_e32 v88, 16, v93
	v_and_b32_e32 v91, 0xffff0000, v94
	v_and_b32_e32 v93, 0xffff0000, v95
	v_mul_f32_e32 v70, v9, v90
	v_mul_f32_e32 v71, v11, v92
	s_waitcnt vmcnt(0)
	v_and_b32_e32 v82, 0xffff0000, v96
	v_and_b32_e32 v84, 0xffff0000, v97
	v_lshlrev_b32_e32 v87, 16, v94
	v_lshlrev_b32_e32 v89, 16, v95
	v_mul_f32_e32 v94, v1, v91
	v_mul_f32_e32 v95, v3, v93
	v_fmac_f32_e32 v70, v8, v86
	v_fmac_f32_e32 v71, v10, v88
	v_lshlrev_b32_e32 v64, 16, v96
	v_lshlrev_b32_e32 v80, 16, v97
	v_and_b32_e32 v83, 0xffff0000, v98
	v_and_b32_e32 v85, 0xffff0000, v99
	v_mul_f32_e32 v96, v5, v82
	v_mul_f32_e32 v97, v7, v84
	v_fmac_f32_e32 v94, v0, v87
	v_fmac_f32_e32 v95, v2, v89
	v_add_f32_e32 v70, v70, v71
	s_waitcnt lgkmcnt(0)
	v_lshlrev_b32_e32 v79, 16, v98
	v_lshlrev_b32_e32 v81, 16, v99
	v_mul_f32_e32 v98, v13, v83
	v_mul_f32_e32 v99, v15, v85
	v_fmac_f32_e32 v96, v4, v64
	v_fmac_f32_e32 v97, v6, v80
	v_add_f32_e32 v71, v94, v95
	v_add_f32_e32 v70, 0, v70
	v_fmac_f32_e32 v98, v12, v79
	v_fmac_f32_e32 v99, v14, v81
	v_add_f32_e32 v94, v96, v97
	v_add_f32_e32 v70, v71, v70
	v_add_f32_e32 v70, v94, v70
	v_add_f32_e32 v71, v98, v99
	v_add_f32_e32 v70, v71, v70
	s_nop 1
	v_add_f32_dpp v70, v70, v70 quad_perm:[1,0,3,2] row_mask:0xf bank_mask:0xf
	s_nop 1
	v_add_f32_dpp v70, v70, v70 quad_perm:[2,3,0,1] row_mask:0xf bank_mask:0xf
	s_nop 1
	v_add_f32_dpp v70, v70, v70 row_half_mirror row_mask:0xf bank_mask:0xf
	s_nop 1
	v_add_f32_dpp v70, v70, v70 row_mirror row_mask:0xf bank_mask:0xf
	s_waitcnt lgkmcnt(0)
	v_mov_b32_e32 v71, v70
	s_nop 1
	v_permlane16_swap_b32_e32 v70, v71
	v_add_f32_e32 v94, v70, v71
	v_mov_b32_e32 v95, v94
	s_nop 1
	v_permlane32_swap_b32_e32 v94, v95
	v_lshl_add_u64 v[70:71], s[90:91], 0, v[66:67]
	s_and_saveexec_b64 s[34:35], s[2:3]
	s_cbranch_execz .LBB0_137
	s_waitcnt lgkmcnt(0)
	v_add_f32_e32 v96, v94, v95
	v_add_co_u32_e32 v94, vcc, 0x1f110000, v70
	s_nop 1
	v_addc_co_u32_e32 v95, vcc, 0, v71, vcc
	global_store_dword v[94:95], v96, off
.LBB0_137:
	s_or_b64 exec, exec, s[34:35]
	v_mul_f32_e32 v94, v25, v90
	s_waitcnt lgkmcnt(0)
	v_mul_f32_e32 v95, v27, v92
	v_fmac_f32_e32 v94, v24, v86
	v_fmac_f32_e32 v95, v26, v88
	v_add_f32_e32 v94, v94, v95
	v_mul_f32_e32 v95, v17, v91
	v_mul_f32_e32 v96, v19, v93
	v_fmac_f32_e32 v95, v16, v87
	v_fmac_f32_e32 v96, v18, v89
	v_add_f32_e32 v94, 0, v94
	v_add_f32_e32 v95, v95, v96
	v_add_f32_e32 v94, v95, v94
	v_mul_f32_e32 v95, v21, v82
	v_mul_f32_e32 v96, v23, v84
	v_fmac_f32_e32 v95, v20, v64
	v_fmac_f32_e32 v96, v22, v80
	v_add_f32_e32 v95, v95, v96
	v_add_f32_e32 v94, v95, v94
	v_mul_f32_e32 v95, v29, v83
	v_mul_f32_e32 v96, v31, v85
	v_fmac_f32_e32 v95, v28, v79
	v_fmac_f32_e32 v96, v30, v81
	v_add_f32_e32 v95, v95, v96
	v_add_f32_e32 v94, v95, v94
	s_nop 1
	v_add_f32_dpp v94, v94, v94 quad_perm:[1,0,3,2] row_mask:0xf bank_mask:0xf
	s_nop 1
	v_add_f32_dpp v94, v94, v94 quad_perm:[2,3,0,1] row_mask:0xf bank_mask:0xf
	s_nop 1
	v_add_f32_dpp v94, v94, v94 row_half_mirror row_mask:0xf bank_mask:0xf
	s_nop 1
	v_add_f32_dpp v94, v94, v94 row_mirror row_mask:0xf bank_mask:0xf
	s_waitcnt lgkmcnt(0)
	v_mov_b32_e32 v95, v94
	s_nop 1
	v_permlane16_swap_b32_e32 v94, v95
	v_add_f32_e32 v94, v94, v95
	v_mov_b32_e32 v95, v94
	s_nop 1
	v_permlane32_swap_b32_e32 v94, v95
	s_and_saveexec_b64 s[34:35], s[2:3]
	s_cbranch_execz .LBB0_139
	s_waitcnt lgkmcnt(0)
	v_add_f32_e32 v96, v94, v95
	v_add_co_u32_e32 v94, vcc, 0x1f114000, v70
	s_nop 1
	v_addc_co_u32_e32 v95, vcc, 0, v71, vcc
	global_store_dword v[94:95], v96, off
.LBB0_139:
	s_or_b64 exec, exec, s[34:35]
	v_mul_f32_e32 v94, v41, v90
	s_waitcnt lgkmcnt(0)
	v_mul_f32_e32 v95, v43, v92
	v_fmac_f32_e32 v94, v40, v86
	v_fmac_f32_e32 v95, v42, v88
	v_add_f32_e32 v94, v94, v95
	v_mul_f32_e32 v95, v33, v91
	v_mul_f32_e32 v96, v35, v93
	v_fmac_f32_e32 v95, v32, v87
	v_fmac_f32_e32 v96, v34, v89
	v_add_f32_e32 v94, 0, v94
	v_add_f32_e32 v95, v95, v96
	v_add_f32_e32 v94, v95, v94
	v_mul_f32_e32 v95, v37, v82
	v_mul_f32_e32 v96, v39, v84
	v_fmac_f32_e32 v95, v36, v64
	v_fmac_f32_e32 v96, v38, v80
	v_add_f32_e32 v95, v95, v96
	v_add_f32_e32 v94, v95, v94
	v_mul_f32_e32 v95, v45, v83
	v_mul_f32_e32 v96, v47, v85
	v_fmac_f32_e32 v95, v44, v79
	v_fmac_f32_e32 v96, v46, v81
	v_add_f32_e32 v95, v95, v96
	v_add_f32_e32 v94, v95, v94
	s_nop 1
	v_add_f32_dpp v94, v94, v94 quad_perm:[1,0,3,2] row_mask:0xf bank_mask:0xf
	s_nop 1
	v_add_f32_dpp v94, v94, v94 quad_perm:[2,3,0,1] row_mask:0xf bank_mask:0xf
	s_nop 1
	v_add_f32_dpp v94, v94, v94 row_half_mirror row_mask:0xf bank_mask:0xf
	s_nop 1
	v_add_f32_dpp v94, v94, v94 row_mirror row_mask:0xf bank_mask:0xf
	s_waitcnt lgkmcnt(0)
	v_mov_b32_e32 v95, v94
	s_nop 1
	v_permlane16_swap_b32_e32 v94, v95
	v_add_f32_e32 v94, v94, v95
	v_mov_b32_e32 v95, v94
	s_nop 1
	v_permlane32_swap_b32_e32 v94, v95
	s_and_saveexec_b64 s[34:35], s[2:3]
	s_cbranch_execz .LBB0_141
	s_waitcnt lgkmcnt(0)
	v_add_f32_e32 v96, v94, v95
	v_add_co_u32_e32 v94, vcc, 0x1f118000, v70
	s_nop 1
	v_addc_co_u32_e32 v95, vcc, 0, v71, vcc
	global_store_dword v[94:95], v96, off
.LBB0_141:
	s_or_b64 exec, exec, s[34:35]
	v_mul_f32_e32 v90, v57, v90
	v_fmac_f32_e32 v90, v56, v86
	v_mul_f32_e32 v86, v59, v92
	v_fmac_f32_e32 v86, v58, v88
	v_mul_f32_e32 v88, v49, v91
	v_mul_f32_e32 v82, v53, v82
	v_fmac_f32_e32 v88, v48, v87
	v_mul_f32_e32 v87, v51, v93
	v_fmac_f32_e32 v82, v52, v64
	v_mul_f32_e32 v64, v55, v84
	v_add_f32_e32 v86, v90, v86
	v_fmac_f32_e32 v87, v50, v89
	v_fmac_f32_e32 v64, v54, v80
	v_mul_f32_e32 v80, v61, v83
	v_add_f32_e32 v86, 0, v86
	v_add_f32_e32 v87, v88, v87
	v_fmac_f32_e32 v80, v60, v79
	v_mul_f32_e32 v79, v63, v85
	v_add_f32_e32 v86, v87, v86
	v_add_f32_e32 v64, v82, v64
	v_fmac_f32_e32 v79, v62, v81
	v_add_f32_e32 v64, v64, v86
	v_add_f32_e32 v79, v80, v79
	v_add_f32_e32 v64, v79, v64
	s_nop 1
	v_add_f32_dpp v64, v64, v64 quad_perm:[1,0,3,2] row_mask:0xf bank_mask:0xf
	s_nop 1
	v_add_f32_dpp v64, v64, v64 quad_perm:[2,3,0,1] row_mask:0xf bank_mask:0xf
	s_nop 1
	v_add_f32_dpp v64, v64, v64 row_half_mirror row_mask:0xf bank_mask:0xf
	s_nop 1
	v_add_f32_dpp v64, v64, v64 row_mirror row_mask:0xf bank_mask:0xf
	s_waitcnt lgkmcnt(0)
	v_mov_b32_e32 v79, v64
	s_nop 1
	v_permlane16_swap_b32_e32 v64, v79
	v_add_f32_e32 v64, v64, v79
	v_mov_b32_e32 v79, v64
	s_nop 1
	v_permlane32_swap_b32_e32 v64, v79
	s_and_saveexec_b64 s[34:35], s[2:3]
	s_cbranch_execz .LBB0_134
	v_add_co_u32_e32 v70, vcc, 0x1f11c000, v70
	s_waitcnt lgkmcnt(0)
	v_add_f32_e32 v64, v64, v79
	v_addc_co_u32_e32 v71, vcc, 0, v71, vcc
	global_store_dword v[70:71], v64, off
	s_branch .LBB0_134

;     __device__ __forceinline__ void operator()(const f32x4 (&acc)[2][2][4][2], const Unit& u, int wr_, int wc_, int fr_, int fq_) const {
;     ...
;             for (int ai = 0; ai < 2; ++ai)
; #pragma unroll
;                 for (int m = 0; m < 4; ++m)
; #pragma unroll
;                     for (int bj = 0; bj < 2; ++bj) { float s = 0.f;
; #pragma unroll
;                         for (int n = 0; n < 2; ++n) { const f32x4 x = acc[ai][bj][m][n]; s += (x[0] * x[0] + x[1] * x[1]) + (x[2] * x[2] + x[3] * x[3]); }
;                         s += __shfl_xor(s, 16); s += __shfl_xor(s, 32);
;                         if (fq == 0) P[((ai * HALF + wr * 64 + m * 16 + fr) * 2 + bj) * 4 + wc] = s; }
.LBB0_377:
	v_mul_f32_e32 v148, v125, v125
	v_mul_f32_e32 v149, v127, v127
	v_fmac_f32_e32 v148, v124, v124
	v_fmac_f32_e32 v149, v126, v126
	v_add_f32_e32 v148, v148, v149
	v_mul_f32_e32 v149, v121, v121
	v_mul_f32_e32 v150, v123, v123
	v_cmp_lt_i32_e32 vcc, v200, v192
	v_fmac_f32_e32 v149, v120, v120
	v_fmac_f32_e32 v150, v122, v122
	v_cndmask_b32_e32 v146, v191, v200, vcc
	v_add_f32_e32 v149, v149, v150
	v_lshlrev_b32_e32 v146, 2, v146
	v_add_f32_e32 v150, v149, v148
	v_mov_b32_e32 v151, v150
	s_nop 1
	v_permlane16_swap_b32_e32 v150, v151
	v_cmp_lt_i32_e32 vcc, v198, v192
	v_mov_b32_e32 v144, v190
	s_add_i32 s24, 0, 0x20000
	v_cndmask_b32_e32 v147, v191, v198, vcc
	v_lshlrev_b32_e32 v147, 2, v147
	s_waitcnt lgkmcnt(0)
	v_add_f32_e32 v152, v150, v151
	v_mov_b32_e32 v153, v152
	s_nop 1
	v_permlane32_swap_b32_e32 v152, v153
	v_and_b32_e32 v140, 15, v144
	v_bfe_u32 v142, v144, 4, 2
	v_bfe_u32 v143, v144, 6, 2
	v_ashrrev_i32_e32 v144, 8, v144
	v_lshlrev_b32_e32 v148, 11, v144
	v_lshlrev_b32_e32 v149, 5, v140
	v_add_u32_e32 v151, s24, v148
	v_lshlrev_b32_e32 v150, 2, v143
	v_cmp_eq_u32_e32 vcc, 0, v142
	v_add3_u32 v151, v151, v149, v150
	s_and_saveexec_b64 s[0:1], vcc
	s_cbranch_execz .LBB0_379
	s_waitcnt lgkmcnt(0)
	v_add_f32_e32 v152, v152, v153
	ds_write_b32 v151, v152
.LBB0_379:
	s_or_b64 exec, exec, s[0:1]
	v_mul_f32_e32 v152, v117, v117
	s_waitcnt lgkmcnt(0)
	v_mul_f32_e32 v153, v119, v119
	v_fmac_f32_e32 v152, v116, v116
	v_fmac_f32_e32 v153, v118, v118
	v_add_f32_e32 v152, v152, v153
	v_mul_f32_e32 v153, v113, v113
	v_mul_f32_e32 v154, v115, v115
	v_fmac_f32_e32 v153, v112, v112
	v_fmac_f32_e32 v154, v114, v114
	v_add_f32_e32 v153, v153, v154
	v_add_f32_e32 v152, v153, v152
	v_mov_b32_e32 v153, v152
	s_nop 1
	v_permlane16_swap_b32_e32 v152, v153
	v_add_f32_e32 v152, v152, v153
	v_mov_b32_e32 v153, v152
	s_nop 1
	v_permlane32_swap_b32_e32 v152, v153
	s_and_saveexec_b64 s[0:1], vcc
	s_cbranch_execz .LBB0_381
	s_waitcnt lgkmcnt(0)
	v_add_f32_e32 v152, v152, v153
	ds_write_b32 v151, v152 offset:16
.LBB0_381:
	s_or_b64 exec, exec, s[0:1]
	v_mul_f32_e32 v151, v109, v109
	v_mul_f32_e32 v152, v111, v111
	v_fmac_f32_e32 v151, v108, v108
	v_fmac_f32_e32 v152, v110, v110
	v_add_f32_e32 v151, v151, v152
	v_mul_f32_e32 v152, v105, v105
	s_waitcnt lgkmcnt(0)
	v_mul_f32_e32 v153, v107, v107
	v_fmac_f32_e32 v152, v104, v104
	v_fmac_f32_e32 v153, v106, v106
	v_add_f32_e32 v152, v152, v153
	v_add_f32_e32 v151, v152, v151
	v_mov_b32_e32 v152, v151
	s_nop 1
	v_permlane16_swap_b32_e32 v151, v152
	v_readlane_b32 s0, v253, 60
	s_waitcnt lgkmcnt(0)
	v_add_f32_e32 v152, v151, v152
	v_mov_b32_e32 v153, v152
	s_nop 1
	v_permlane32_swap_b32_e32 v152, v153
	v_add_u32_e32 v151, s0, v148
	v_add3_u32 v151, v151, v149, v150
	s_and_saveexec_b64 s[0:1], vcc
	s_cbranch_execz .LBB0_383
	s_waitcnt lgkmcnt(0)
	v_add_f32_e32 v152, v152, v153
	ds_write_b32 v151, v152
.LBB0_383:
	s_or_b64 exec, exec, s[0:1]
	v_mul_f32_e32 v152, v101, v101
	s_waitcnt lgkmcnt(0)
	v_mul_f32_e32 v153, v103, v103
	v_fmac_f32_e32 v152, v100, v100
	v_fmac_f32_e32 v153, v102, v102
	v_add_f32_e32 v152, v152, v153
	v_mul_f32_e32 v153, v97, v97
	v_mul_f32_e32 v154, v99, v99
	v_fmac_f32_e32 v153, v96, v96
	v_fmac_f32_e32 v154, v98, v98
	v_add_f32_e32 v153, v153, v154
	v_add_f32_e32 v152, v153, v152
	v_mov_b32_e32 v153, v152
	s_nop 1
	v_permlane16_swap_b32_e32 v152, v153
	v_add_f32_e32 v152, v152, v153
	v_mov_b32_e32 v153, v152
	s_nop 1
	v_permlane32_swap_b32_e32 v152, v153
	s_and_saveexec_b64 s[0:1], vcc
	s_cbranch_execz .LBB0_385
	s_waitcnt lgkmcnt(0)
	v_add_f32_e32 v152, v152, v153
	ds_write_b32 v151, v152 offset:16
.LBB0_385:
	s_or_b64 exec, exec, s[0:1]
	v_mul_f32_e32 v151, v93, v93
	v_mul_f32_e32 v152, v95, v95
	v_fmac_f32_e32 v151, v92, v92
	v_fmac_f32_e32 v152, v94, v94
	v_add_f32_e32 v151, v151, v152
	v_mul_f32_e32 v152, v89, v89
	s_waitcnt lgkmcnt(0)
	v_mul_f32_e32 v153, v91, v91
	v_fmac_f32_e32 v152, v88, v88
	v_fmac_f32_e32 v153, v90, v90
	v_add_f32_e32 v152, v152, v153
	v_add_f32_e32 v151, v152, v151
	v_mov_b32_e32 v152, v151
	s_nop 1
	v_permlane16_swap_b32_e32 v151, v152
	v_readlane_b32 s0, v253, 61
	s_waitcnt lgkmcnt(0)
	v_add_f32_e32 v152, v151, v152
	v_mov_b32_e32 v153, v152
	s_nop 1
	v_permlane32_swap_b32_e32 v152, v153
	v_add_u32_e32 v151, s0, v148
	v_add3_u32 v151, v151, v149, v150
	s_and_saveexec_b64 s[0:1], vcc
	s_cbranch_execz .LBB0_387
	s_waitcnt lgkmcnt(0)
	v_add_f32_e32 v152, v152, v153
	ds_write_b32 v151, v152
.LBB0_387:
	s_or_b64 exec, exec, s[0:1]
	v_mul_f32_e32 v152, v85, v85
	s_waitcnt lgkmcnt(0)
	v_mul_f32_e32 v153, v87, v87
	v_fmac_f32_e32 v152, v84, v84
	v_fmac_f32_e32 v153, v86, v86
	v_add_f32_e32 v152, v152, v153
	v_mul_f32_e32 v153, v81, v81
	v_mul_f32_e32 v154, v83, v83
	v_fmac_f32_e32 v153, v80, v80
	v_fmac_f32_e32 v154, v82, v82
	v_add_f32_e32 v153, v153, v154
	v_add_f32_e32 v152, v153, v152
	v_mov_b32_e32 v153, v152
	s_nop 1
	v_permlane16_swap_b32_e32 v152, v153
	v_add_f32_e32 v152, v152, v153
	v_mov_b32_e32 v153, v152
	s_nop 1
	v_permlane32_swap_b32_e32 v152, v153
	s_and_saveexec_b64 s[0:1], vcc
	s_cbranch_execz .LBB0_389
	s_waitcnt lgkmcnt(0)
	v_add_f32_e32 v152, v152, v153
	ds_write_b32 v151, v152 offset:16
.LBB0_389:
	s_or_b64 exec, exec, s[0:1]
	v_mul_f32_e32 v151, v77, v77
	v_mul_f32_e32 v152, v79, v79
	v_fmac_f32_e32 v151, v76, v76
	v_fmac_f32_e32 v152, v78, v78
	v_add_f32_e32 v151, v151, v152
	v_mul_f32_e32 v152, v73, v73
	s_waitcnt lgkmcnt(0)
	v_mul_f32_e32 v153, v75, v75
	v_fmac_f32_e32 v152, v72, v72
	v_fmac_f32_e32 v153, v74, v74
	v_add_f32_e32 v152, v152, v153
	v_add_f32_e32 v151, v152, v151
	v_mov_b32_e32 v152, v151
	s_nop 1
	v_permlane16_swap_b32_e32 v151, v152
	v_readlane_b32 s0, v253, 62
	s_waitcnt lgkmcnt(0)
	v_add_f32_e32 v152, v151, v152
	v_mov_b32_e32 v153, v152
	s_nop 1
	v_permlane32_swap_b32_e32 v152, v153
	v_add_u32_e32 v151, s0, v148
	v_add3_u32 v151, v151, v149, v150
	s_and_saveexec_b64 s[0:1], vcc
	s_cbranch_execz .LBB0_391
	s_waitcnt lgkmcnt(0)
	v_add_f32_e32 v152, v152, v153
	ds_write_b32 v151, v152
;     __device__ __forceinline__ void operator()(const f32x4 (&acc)[2][2][4][2], const Unit& u, int wr_, int wc_, int fr_, int fq_) const {
;     ...
;             for (int ai = 0; ai < 2; ++ai)
; #pragma unroll
;                 for (int m = 0; m < 4; ++m)
; #pragma unroll
;                     for (int bj = 0; bj < 2; ++bj) { float s = 0.f;
; #pragma unroll
;                         for (int n = 0; n < 2; ++n) { const f32x4 x = acc[ai][bj][m][n]; s += (x[0] * x[0] + x[1] * x[1]) + (x[2] * x[2] + x[3] * x[3]); }
;                         s += __shfl_xor(s, 16); s += __shfl_xor(s, 32);
;                         if (fq == 0) P[((ai * HALF + wr * 64 + m * 16 + fr) * 2 + bj) * 4 + wc] = s; }
.LBB0_391:
	s_or_b64 exec, exec, s[0:1]
	v_mul_f32_e32 v152, v69, v69
	s_waitcnt lgkmcnt(0)
	v_mul_f32_e32 v153, v71, v71
	v_fmac_f32_e32 v152, v68, v68
	v_fmac_f32_e32 v153, v70, v70
	v_add_f32_e32 v152, v152, v153
	v_mul_f32_e32 v153, v65, v65
	v_mul_f32_e32 v154, v67, v67
	v_fmac_f32_e32 v153, v64, v64
	v_fmac_f32_e32 v154, v66, v66
	v_add_f32_e32 v153, v153, v154
	v_add_f32_e32 v152, v153, v152
	v_mov_b32_e32 v153, v152
	s_nop 1
	v_permlane16_swap_b32_e32 v152, v153
	v_add_f32_e32 v152, v152, v153
	v_mov_b32_e32 v153, v152
	s_nop 1
	v_permlane32_swap_b32_e32 v152, v153
	s_and_saveexec_b64 s[0:1], vcc
	s_cbranch_execz .LBB0_393
	s_waitcnt lgkmcnt(0)
	v_add_f32_e32 v152, v152, v153
	ds_write_b32 v151, v152 offset:16
.LBB0_393:
	s_or_b64 exec, exec, s[0:1]
	v_mul_f32_e32 v151, v61, v61
	v_mul_f32_e32 v152, v63, v63
	v_fmac_f32_e32 v151, v60, v60
	v_fmac_f32_e32 v152, v62, v62
	v_add_f32_e32 v151, v151, v152
	v_mul_f32_e32 v152, v57, v57
	s_waitcnt lgkmcnt(0)
	v_mul_f32_e32 v153, v59, v59
	v_fmac_f32_e32 v152, v56, v56
	v_fmac_f32_e32 v153, v58, v58
	v_add_f32_e32 v152, v152, v153
	v_add_f32_e32 v151, v152, v151
	v_mov_b32_e32 v152, v151
	s_nop 1
	v_permlane16_swap_b32_e32 v151, v152
	v_readlane_b32 s0, v253, 63
	s_waitcnt lgkmcnt(0)
	v_add_f32_e32 v152, v151, v152
	v_mov_b32_e32 v153, v152
	s_nop 1
	v_permlane32_swap_b32_e32 v152, v153
	v_add_u32_e32 v151, s0, v148
	v_add3_u32 v151, v151, v149, v150
	s_and_saveexec_b64 s[0:1], vcc
	s_cbranch_execz .LBB0_395
	s_waitcnt lgkmcnt(0)
	v_add_f32_e32 v152, v152, v153
	ds_write_b32 v151, v152
.LBB0_395:
	s_or_b64 exec, exec, s[0:1]
	v_mul_f32_e32 v152, v53, v53
	s_waitcnt lgkmcnt(0)
	v_mul_f32_e32 v153, v55, v55
	v_fmac_f32_e32 v152, v52, v52
	v_fmac_f32_e32 v153, v54, v54
	v_add_f32_e32 v152, v152, v153
	v_mul_f32_e32 v153, v49, v49
	v_mul_f32_e32 v154, v51, v51
	v_fmac_f32_e32 v153, v48, v48
	v_fmac_f32_e32 v154, v50, v50
	v_add_f32_e32 v153, v153, v154
	v_add_f32_e32 v152, v153, v152
	v_mov_b32_e32 v153, v152
	s_nop 1
	v_permlane16_swap_b32_e32 v152, v153
	v_add_f32_e32 v152, v152, v153
	v_mov_b32_e32 v153, v152
	s_nop 1
	v_permlane32_swap_b32_e32 v152, v153
	s_and_saveexec_b64 s[0:1], vcc
	s_cbranch_execz .LBB0_397
	s_waitcnt lgkmcnt(0)
	v_add_f32_e32 v152, v152, v153
	ds_write_b32 v151, v152 offset:16
.LBB0_397:
	s_or_b64 exec, exec, s[0:1]
	v_mul_f32_e32 v151, v45, v45
	v_mul_f32_e32 v152, v47, v47
	v_fmac_f32_e32 v151, v44, v44
	v_fmac_f32_e32 v152, v46, v46
	v_add_f32_e32 v151, v151, v152
	v_mul_f32_e32 v152, v41, v41
	s_waitcnt lgkmcnt(0)
	v_mul_f32_e32 v153, v43, v43
	v_fmac_f32_e32 v152, v40, v40
	v_fmac_f32_e32 v153, v42, v42
	v_add_f32_e32 v152, v152, v153
	v_add_f32_e32 v151, v152, v151
	v_mov_b32_e32 v152, v151
	s_nop 1
	v_permlane16_swap_b32_e32 v151, v152
	v_readlane_b32 s0, v254, 0
	s_waitcnt lgkmcnt(0)
	v_add_f32_e32 v152, v151, v152
	v_mov_b32_e32 v153, v152
	s_nop 1
	v_permlane32_swap_b32_e32 v152, v153
	v_add_u32_e32 v151, s0, v148
	v_add3_u32 v151, v151, v149, v150
	s_and_saveexec_b64 s[0:1], vcc
	s_cbranch_execz .LBB0_399
	s_waitcnt lgkmcnt(0)
	v_add_f32_e32 v152, v152, v153
	ds_write_b32 v151, v152
.LBB0_399:
	s_or_b64 exec, exec, s[0:1]
	v_mul_f32_e32 v152, v37, v37
	s_waitcnt lgkmcnt(0)
	v_mul_f32_e32 v153, v39, v39
	v_fmac_f32_e32 v152, v36, v36
	v_fmac_f32_e32 v153, v38, v38
	v_add_f32_e32 v152, v152, v153
	v_mul_f32_e32 v153, v33, v33
	v_mul_f32_e32 v154, v35, v35
	v_fmac_f32_e32 v153, v32, v32
	v_fmac_f32_e32 v154, v34, v34
	v_add_f32_e32 v153, v153, v154
	v_add_f32_e32 v152, v153, v152
	v_mov_b32_e32 v153, v152
	s_nop 1
	v_permlane16_swap_b32_e32 v152, v153
	v_add_f32_e32 v152, v152, v153
	v_mov_b32_e32 v153, v152
	s_nop 1
	v_permlane32_swap_b32_e32 v152, v153
	s_and_saveexec_b64 s[0:1], vcc
	s_cbranch_execz .LBB0_401
	s_waitcnt lgkmcnt(0)
	v_add_f32_e32 v152, v152, v153
	ds_write_b32 v151, v152 offset:16
.LBB0_401:
	s_or_b64 exec, exec, s[0:1]
	v_mul_f32_e32 v151, v29, v29
	v_mul_f32_e32 v152, v31, v31
	v_fmac_f32_e32 v151, v28, v28
	v_fmac_f32_e32 v152, v30, v30
	v_add_f32_e32 v151, v151, v152
	v_mul_f32_e32 v152, v25, v25
	s_waitcnt lgkmcnt(0)
	v_mul_f32_e32 v153, v27, v27
	v_fmac_f32_e32 v152, v24, v24
	v_fmac_f32_e32 v153, v26, v26
	v_add_f32_e32 v152, v152, v153
	v_add_f32_e32 v151, v152, v151
	v_mov_b32_e32 v152, v151
	s_nop 1
	v_permlane16_swap_b32_e32 v151, v152
	v_readlane_b32 s0, v254, 1
	s_waitcnt lgkmcnt(0)
	v_add_f32_e32 v152, v151, v152
	v_mov_b32_e32 v153, v152
	s_nop 1
	v_permlane32_swap_b32_e32 v152, v153
	v_add_u32_e32 v151, s0, v148
	v_add3_u32 v151, v151, v149, v150
	s_and_saveexec_b64 s[0:1], vcc
	s_cbranch_execz .LBB0_403
	s_waitcnt lgkmcnt(0)
	v_add_f32_e32 v152, v152, v153
	ds_write_b32 v151, v152
.LBB0_403:
	s_or_b64 exec, exec, s[0:1]
	v_mul_f32_e32 v152, v21, v21
	s_waitcnt lgkmcnt(0)
	v_mul_f32_e32 v153, v23, v23
	v_fmac_f32_e32 v152, v20, v20
	v_fmac_f32_e32 v153, v22, v22
	v_add_f32_e32 v152, v152, v153
	v_mul_f32_e32 v153, v17, v17
	v_mul_f32_e32 v154, v19, v19
	v_fmac_f32_e32 v153, v16, v16
	v_fmac_f32_e32 v154, v18, v18
	v_add_f32_e32 v153, v153, v154
	v_add_f32_e32 v152, v153, v152
	v_mov_b32_e32 v153, v152
	s_nop 1
	v_permlane16_swap_b32_e32 v152, v153
	v_add_f32_e32 v152, v152, v153
	v_mov_b32_e32 v153, v152
	s_nop 1
	v_permlane32_swap_b32_e32 v152, v153
	s_and_saveexec_b64 s[0:1], vcc
	s_cbranch_execz .LBB0_405
	s_waitcnt lgkmcnt(0)
	v_add_f32_e32 v152, v152, v153
	ds_write_b32 v151, v152 offset:16
.LBB0_405:
	s_or_b64 exec, exec, s[0:1]
	v_readlane_b32 s0, v254, 2
	v_mul_f32_e32 v151, v11, v11
	v_fmac_f32_e32 v151, v10, v10
	v_add_u32_e32 v148, s0, v148
	v_add3_u32 v148, v148, v149, v150
	v_mul_f32_e32 v149, v13, v13
	v_mul_f32_e32 v150, v15, v15
	v_fmac_f32_e32 v149, v12, v12
	v_fmac_f32_e32 v150, v14, v14
	v_add_f32_e32 v149, v149, v150
	v_mul_f32_e32 v150, v9, v9
	v_fmac_f32_e32 v150, v8, v8
	v_add_f32_e32 v150, v150, v151
	v_add_f32_e32 v149, v150, v149
	v_mov_b32_e32 v150, v149
	s_nop 1
	v_permlane16_swap_b32_e32 v149, v150
	v_add_f32_e32 v149, v149, v150
	v_mov_b32_e32 v150, v149
	s_nop 1
	v_permlane32_swap_b32_e32 v149, v150
	s_and_saveexec_b64 s[0:1], vcc
	s_cbranch_execz .LBB0_407
	s_waitcnt lgkmcnt(0)
	v_add_f32_e32 v149, v149, v150
	ds_write_b32 v148, v149
.LBB0_407:
	s_or_b64 exec, exec, s[0:1]
	v_mul_f32_e32 v149, v5, v5
	s_waitcnt lgkmcnt(0)
	v_mul_f32_e32 v150, v7, v7
	v_fmac_f32_e32 v149, v4, v4
	v_fmac_f32_e32 v150, v6, v6
	v_add_f32_e32 v149, v149, v150
	v_mul_f32_e32 v150, v1, v1
	v_mul_f32_e32 v151, v3, v3
	v_fmac_f32_e32 v150, v0, v0
	v_fmac_f32_e32 v151, v2, v2
	v_add_f32_e32 v150, v150, v151
	v_add_f32_e32 v149, v150, v149
	v_mov_b32_e32 v146, v149
	s_nop 1
	v_permlane16_swap_b32_e32 v149, v146
	v_add_f32_e32 v146, v149, v146
	v_mov_b32_e32 v147, v146
	s_nop 1
	v_permlane32_swap_b32_e32 v146, v147
	s_and_saveexec_b64 s[0:1], vcc
	s_cbranch_execz .LBB0_409
	s_waitcnt lgkmcnt(0)
	v_add_f32_e32 v146, v146, v147
	ds_write_b32 v148, v146 offset:16

; __device__ __forceinline__ unsigned cvt_pk_bf16(float lo, float hi) { unsigned r; asm volatile("v_cvt_pk_bf16_f32 %0, %1, %2" : "=v"(r) : "v"(lo), "v"(hi)); return r; }
;     __device__ __forceinline__ void operator()(const f32x4 (&acc)[2][2][4][2], const Unit& u, int wr_, int wc_, int fr_, int fq_) const {
;     ...
;                 for (int m = 0; m < 4; ++m) { int rl = ai * HALF + wr * 64 + m * 16 + fr; asm volatile("" : "+v"(rl)); float s = 0.f;
; #pragma unroll
;                     for (int bj = 0; bj < 2; ++bj)
; #pragma unroll
;                         for (int n = 0; n < 2; ++n) { const f32x4 x = acc[ai][bj][m][n]; s += (x[0] * x[0] + x[1] * x[1]) + (x[2] * x[2] + x[3] * x[3]); }
;                     s += __shfl_xor(s, 16); s += __shfl_xor(s, 32);
;                     const float rr = 1.0f / sqrtf(s * (1.0f / 64.0f) + RMS_EPS_F);
;                     const size_t t = (size_t)u.pm * BM + rl;
;                     bf16_t* qrow = Q + ((size_t)(b * 4 + wc) * 8192 + s0 + rl) * 192 + 128;
;                     u32x4 wa, wb;
; #pragma unroll
;                     for (int n = 0; n < 2; ++n) { const int j0 = 8 * fq + 4 * n;
;                         const f32x4 c4 = *(const f32x4*)(cosT + t * 32 + j0), s4 = *(const f32x4*)(sinT + t * 32 + j0);
;                         const f32x4 g1 = *(const f32x4*)(gn_rope + j0), g2 = *(const f32x4*)(gn_rope + 32 + j0);
;                         const f32x4 y1 = acc[ai][0][m][n] * rr * g1, y2 = acc[ai][1][m][n] * rr * g2;
;                         const f32x4 o1 = y1 * c4 - y2 * s4, o2 = y2 * c4 + y1 * s4;
;                         wa[2 * n] = cvt_pk_bf16(o1[0], o1[1]); wa[2 * n + 1] = cvt_pk_bf16(o1[2], o1[3]); wb[2 * n] = cvt_pk_bf16(o2[0], o2[1]); wb[2 * n + 1] = cvt_pk_bf16(o2[2], o2[3]); }
;                     *(u32x4*)(qrow + 8 * fq) = wa; *(u32x4*)(qrow + 32 + 8 * fq) = wb;
.LBB0_432:
	v_mov_b32_e32 v130, v190
	s_movk_i32 s1, 0xffc0
	v_and_b32_e32 v128, 15, v130
	v_ashrrev_i32_e32 v131, 2, v130
	v_lshrrev_b32_e32 v129, 6, v130
	v_and_or_b32 v166, v131, s1, v128
	s_ashr_i32 s1, s24, 3
	v_bfi_b32 v128, 3, v129, s1
	v_ashrrev_i32_e32 v129, 31, v128
	v_lshlrev_b64 v[144:145], 13, v[128:129]
	v_lshrrev_b32_e32 v128, 1, v130
	v_pk_mul_f32 v[130:131], v[126:127], v[126:127]
	v_pk_mul_f32 v[132:133], v[124:125], v[124:125]
	v_cmp_lt_i32_e32 vcc, v200, v192
	v_pk_mov_b32 v[134:135], v[132:133], v[130:131] op_sel:[1,0]
	v_mov_b32_e32 v133, v131
	v_pk_add_f32 v[130:131], v[134:135], v[132:133]
	v_pk_mul_f32 v[132:133], v[118:119], v[118:119]
	v_pk_add_f32 v[130:131], v[130:131], v[130:131] op_sel_hi:[0,1]
	v_pk_mul_f32 v[134:135], v[116:117], v[116:117]
	v_mul_f32_e32 v130, v120, v120
	v_pk_mov_b32 v[146:147], v[134:135], v[132:133] op_sel:[1,0]
	v_mov_b32_e32 v135, v133
	v_pk_add_f32 v[132:133], v[146:147], v[134:135]
	v_pk_fma_f32 v[134:135], v[120:121], v[120:121], v[130:131] op_sel_hi:[1,1,0]
	v_mul_f32_e32 v130, v122, v122
	v_pk_add_f32 v[132:133], v[132:133], v[132:133] op_sel_hi:[0,1]
	v_pk_fma_f32 v[146:147], v[122:123], v[122:123], v[130:131] op_sel_hi:[1,1,0]
	v_mul_f32_e32 v134, v112, v112
	v_mul_f32_e32 v146, v113, v113
	v_mul_f32_e32 v132, v114, v114
	v_mul_f32_e32 v130, v115, v115
	v_pk_add_f32 v[134:135], v[134:135], v[146:147]
	v_pk_add_f32 v[130:131], v[132:133], v[130:131]
	s_mov_b32 s19, 0xf800000
	v_pk_add_f32 v[130:131], v[134:135], v[130:131]
	s_lshl_b32 s0, s24, 8
	v_add_f32_e32 v129, v130, v131
	v_cndmask_b32_e32 v130, v191, v200, vcc
	v_lshlrev_b32_e32 v158, 2, v130
	v_mov_b32_e32 v130, v129
	s_nop 1
	v_permlane16_swap_b32_e32 v129, v130
	v_cmp_lt_i32_e32 vcc, v198, v192
	s_and_b32 s0, s0, 0x1f00
	v_or_b32_e32 v144, s0, v144
	v_and_b32_e32 v149, 24, v128
	s_waitcnt lgkmcnt(0)
	v_add_f32_e32 v129, v129, v130
	v_cndmask_b32_e32 v130, v191, v198, vcc
	v_lshlrev_b32_e32 v159, 2, v130
	v_mov_b32_e32 v130, v129
	s_nop 1
	v_permlane32_swap_b32_e32 v129, v130
	v_mov_b32_e32 v128, v166
	s_ashr_i32 s25, s24, 31
	s_lshl_b64 s[24:25], s[24:25], 13
	s_waitcnt lgkmcnt(0)
	v_add_f32_e32 v129, v129, v130
	v_fmamk_f32 v129, v129, 0x3c800000, v199
	v_cmp_gt_f32_e32 vcc, s19, v129
	v_mul_f32_e32 v130, 0x4f800000, v129
	v_readlane_b32 s26, v252, 19
	v_cndmask_b32_e32 v129, v129, v130, vcc
	v_sqrt_f32_e32 v130, v129
	v_readlane_b32 s42, v252, 21
	v_readlane_b32 s27, v252, 20
	v_readlane_b32 s43, v252, 22
	v_add_u32_e32 v131, -1, v130
	v_fma_f32 v132, -v131, v130, v129
	v_cmp_ge_f32_e64 s[0:1], 0, v132
	v_add_u32_e32 v132, 1, v130
	v_mov_b64_e32 v[146:147], s[62:63]
	v_cndmask_b32_e64 v131, v130, v131, s[0:1]
	v_fma_f32 v130, -v132, v130, v129
	v_cmp_lt_f32_e64 s[0:1], 0, v130
	v_lshlrev_b32_e32 v160, 2, v149
	s_nop 0
	v_cndmask_b32_e64 v130, v131, v132, s[0:1]
	v_mul_f32_e32 v131, 0x37800000, v130
	v_cndmask_b32_e32 v130, v130, v131, vcc
	v_cmp_class_f32_e32 vcc, v129, v201
	s_nop 1
	v_cndmask_b32_e32 v129, v130, v129, vcc
	v_div_scale_f32 v130, s[0:1], v129, v129, 1.0
	v_rcp_f32_e32 v131, v130
	s_nop 0
	v_fma_f32 v132, -v130, v131, 1.0
	v_fmac_f32_e32 v131, v132, v131
	v_div_scale_f32 v132, vcc, 1.0, v129, 1.0
	v_mul_f32_e32 v133, v132, v131
	v_fma_f32 v134, -v130, v133, v132
	v_fmac_f32_e32 v133, v134, v131
	v_fma_f32 v130, -v130, v133, v132
	v_div_fmas_f32 v130, v130, v131, v133
	v_div_fixup_f32 v148, v130, v129, 1.0
	v_ashrrev_i32_e32 v129, 31, v128
	v_lshl_add_u64 v[130:131], v[144:145], 0, v[128:129]
	v_lshlrev_b64 v[128:129], 5, v[128:129]
	v_lshl_add_u64 v[128:129], v[128:129], 0, s[24:25]
	v_lshlrev_b64 v[132:133], 2, v[128:129]
	v_lshl_add_u64 v[128:129], s[26:27], 0, v[132:133]
	v_lshl_add_u64 v[132:133], s[42:43], 0, v[132:133]
	v_mad_u64_u32 v[150:151], s[0:1], v130, s67, v[146:147]
	v_lshl_add_u64 v[152:153], v[128:129], 0, v[160:161]
	v_lshl_add_u64 v[154:155], v[132:133], 0, v[160:161]
	v_mad_i32_i24 v151, v131, s67, v151
	global_load_dwordx4 v[128:131], v[152:153], off
	global_load_dwordx4 v[132:135], v[154:155], off
	global_load_dwordx4 v[162:165], v160, s[6:7]
	global_load_dwordx4 v[168:171], v160, s[6:7] offset:128
	global_load_dwordx4 v[230:233], v[152:153], off offset:16
	global_load_dwordx4 v[234:237], v[154:155], off offset:16
	global_load_dwordx4 v[238:241], v160, s[6:7] offset:16
	global_load_dwordx4 v[242:245], v160, s[6:7] offset:144
	v_pk_mul_f32 v[120:121], v[120:121], v[148:149] op_sel_hi:[1,0]
	v_pk_mul_f32 v[122:123], v[122:123], v[148:149] op_sel_hi:[1,0]
	v_pk_mul_f32 v[126:127], v[126:127], v[148:149] op_sel_hi:[1,0]
	v_pk_mul_f32 v[124:125], v[124:125], v[148:149] op_sel_hi:[1,0]
	v_pk_mul_f32 v[112:113], v[112:113], v[148:149] op_sel_hi:[1,0]
	v_pk_mul_f32 v[114:115], v[114:115], v[148:149] op_sel_hi:[1,0]
	v_pk_mul_f32 v[118:119], v[118:119], v[148:149] op_sel_hi:[1,0]
	v_pk_mul_f32 v[116:117], v[116:117], v[148:149] op_sel_hi:[1,0]
	s_waitcnt vmcnt(4)
	v_pk_mul_f32 v[124:125], v[162:163], v[124:125]
	v_pk_mul_f32 v[122:123], v[170:171], v[122:123]
	v_pk_mul_f32 v[120:121], v[168:169], v[120:121]
	v_pk_mul_f32 v[126:127], v[164:165], v[126:127]
	v_pk_mul_f32 v[162:163], v[132:133], v[120:121]
	v_pk_mul_f32 v[164:165], v[134:135], v[122:123]
	v_pk_mul_f32 v[120:121], v[128:129], v[120:121]
	v_pk_fma_f32 v[164:165], v[130:131], v[126:127], v[164:165] neg_lo:[0,0,1] neg_hi:[0,0,1]
	v_pk_fma_f32 v[162:163], v[128:129], v[124:125], v[162:163] neg_lo:[0,0,1] neg_hi:[0,0,1]
	v_pk_mul_f32 v[122:123], v[130:131], v[122:123]
	v_pk_fma_f32 v[124:125], v[132:133], v[124:125], v[120:121]
	v_pk_fma_f32 v[122:123], v[134:135], v[126:127], v[122:123]
	v_cvt_pk_bf16_f32 v120, v162, v163
	v_cvt_pk_bf16_f32 v121, v164, v165
	v_cvt_pk_bf16_f32 v124, v124, v125
	s_nop 0
	v_cvt_pk_bf16_f32 v125, v122, v123
	s_nop 0
	s_waitcnt vmcnt(1)
; __device__ __forceinline__ unsigned cvt_pk_bf16(float lo, float hi) { unsigned r; asm volatile("v_cvt_pk_bf16_f32 %0, %1, %2" : "=v"(r) : "v"(lo), "v"(hi)); return r; }
;     __device__ __forceinline__ void operator()(const f32x4 (&acc)[2][2][4][2], const Unit& u, int wr_, int wc_, int fr_, int fq_) const {
;     ...
;                 for (int m = 0; m < 4; ++m) { int rl = ai * HALF + wr * 64 + m * 16 + fr; asm volatile("" : "+v"(rl)); float s = 0.f;
; #pragma unroll
;                     for (int bj = 0; bj < 2; ++bj)
; #pragma unroll
;                         for (int n = 0; n < 2; ++n) { const f32x4 x = acc[ai][bj][m][n]; s += (x[0] * x[0] + x[1] * x[1]) + (x[2] * x[2] + x[3] * x[3]); }
;                     s += __shfl_xor(s, 16); s += __shfl_xor(s, 32);
;                     const float rr = 1.0f / sqrtf(s * (1.0f / 64.0f) + RMS_EPS_F);
;                     const size_t t = (size_t)u.pm * BM + rl;
;                     bf16_t* qrow = Q + ((size_t)(b * 4 + wc) * 8192 + s0 + rl) * 192 + 128;
;                     u32x4 wa, wb;
; #pragma unroll
;                     for (int n = 0; n < 2; ++n) { const int j0 = 8 * fq + 4 * n;
;                         const f32x4 c4 = *(const f32x4*)(cosT + t * 32 + j0), s4 = *(const f32x4*)(sinT + t * 32 + j0);
;                         const f32x4 g1 = *(const f32x4*)(gn_rope + j0), g2 = *(const f32x4*)(gn_rope + 32 + j0);
;                         const f32x4 y1 = acc[ai][0][m][n] * rr * g1, y2 = acc[ai][1][m][n] * rr * g2;
;                         const f32x4 o1 = y1 * c4 - y2 * s4, o2 = y2 * c4 + y1 * s4;
;                         wa[2 * n] = cvt_pk_bf16(o1[0], o1[1]); wa[2 * n + 1] = cvt_pk_bf16(o1[2], o1[3]); wb[2 * n] = cvt_pk_bf16(o2[0], o2[1]); wb[2 * n + 1] = cvt_pk_bf16(o2[2], o2[3]); }
;                     *(u32x4*)(qrow + 8 * fq) = wa; *(u32x4*)(qrow + 32 + 8 * fq) = wb;
;                     asm volatile("" ::: "memory"); }
	v_pk_mul_f32 v[116:117], v[116:117], v[238:239]
	s_waitcnt vmcnt(0)
	v_pk_mul_f32 v[114:115], v[114:115], v[244:245]
	v_pk_mul_f32 v[112:113], v[112:113], v[242:243]
	v_pk_mul_f32 v[118:119], v[118:119], v[240:241]
	v_pk_mul_f32 v[122:123], v[234:235], v[112:113]
	v_pk_mul_f32 v[134:135], v[236:237], v[114:115]
	v_pk_mul_f32 v[114:115], v[232:233], v[114:115]
	v_pk_fma_f32 v[122:123], v[230:231], v[116:117], v[122:123] neg_lo:[0,0,1] neg_hi:[0,0,1]
	v_pk_mul_f32 v[112:113], v[230:231], v[112:113]
	v_pk_fma_f32 v[114:115], v[236:237], v[118:119], v[114:115]
	v_pk_fma_f32 v[134:135], v[232:233], v[118:119], v[134:135] neg_lo:[0,0,1] neg_hi:[0,0,1]
	v_pk_fma_f32 v[112:113], v[234:235], v[116:117], v[112:113]
	v_cvt_pk_bf16_f32 v122, v122, v123
	v_cvt_pk_bf16_f32 v123, v134, v135
	v_pk_mul_f32 v[116:117], v[108:109], v[108:109]
	v_cvt_pk_bf16_f32 v126, v112, v113
	v_cvt_pk_bf16_f32 v127, v114, v115
	v_pk_mul_f32 v[114:115], v[110:111], v[110:111]
	v_lshlrev_b32_e32 v128, 1, v149
	v_pk_mov_b32 v[118:119], v[116:117], v[114:115] op_sel:[1,0]
	v_mov_b32_e32 v117, v115
	v_mov_b32_e32 v129, v161
	v_pk_add_f32 v[114:115], v[118:119], v[116:117]
	v_lshl_add_u64 v[112:113], v[150:151], 0, v[128:129]
	v_pk_add_f32 v[114:115], v[114:115], v[114:115] op_sel_hi:[0,1]
	v_pk_mul_f32 v[116:117], v[102:103], v[102:103]
	v_pk_mul_f32 v[118:119], v[100:101], v[100:101]
	global_store_dwordx4 v[112:113], v[120:123], off offset:256
	global_store_dwordx4 v[112:113], v[124:127], off offset:320
	v_mul_f32_e32 v114, v104, v104
	v_pk_mov_b32 v[120:121], v[118:119], v[116:117] op_sel:[1,0]
	v_mov_b32_e32 v119, v117
	v_pk_add_f32 v[116:117], v[120:121], v[118:119]
	v_pk_fma_f32 v[118:119], v[104:105], v[104:105], v[114:115] op_sel_hi:[1,1,0]
	v_mul_f32_e32 v114, v106, v106
	v_pk_add_f32 v[116:117], v[116:117], v[116:117] op_sel_hi:[0,1]
	v_pk_fma_f32 v[120:121], v[106:107], v[106:107], v[114:115] op_sel_hi:[1,1,0]
	v_mul_f32_e32 v118, v96, v96
	v_mul_f32_e32 v120, v97, v97
	v_mul_f32_e32 v116, v98, v98
	v_mul_f32_e32 v114, v99, v99
	v_pk_add_f32 v[118:119], v[118:119], v[120:121]
	v_pk_add_f32 v[114:115], v[116:117], v[114:115]
	v_or_b32_e32 v112, 16, v166
	v_pk_add_f32 v[114:115], v[118:119], v[114:115]
	s_nop 0
	v_add_f32_e32 v113, v114, v115
	v_mov_b32_e32 v114, v113
	s_nop 1
	v_permlane16_swap_b32_e32 v113, v114
	v_add_f32_e32 v113, v113, v114
	v_mov_b32_e32 v114, v113
	s_nop 1
	v_permlane32_swap_b32_e32 v113, v114
	v_add_f32_e32 v113, v113, v114
	v_fmamk_f32 v113, v113, 0x3c800000, v199
	v_cmp_gt_f32_e32 vcc, s19, v113
	v_mul_f32_e32 v114, 0x4f800000, v113
	s_nop 0
	v_cndmask_b32_e32 v113, v113, v114, vcc
	v_sqrt_f32_e32 v114, v113
	s_nop 0
	v_add_u32_e32 v115, -1, v114
	v_fma_f32 v116, -v115, v114, v113
	v_cmp_ge_f32_e64 s[0:1], 0, v116
	v_add_u32_e32 v116, 1, v114
	s_nop 0
	v_cndmask_b32_e64 v115, v114, v115, s[0:1]
	v_fma_f32 v114, -v116, v114, v113
	v_cmp_lt_f32_e64 s[0:1], 0, v114
	s_nop 1
	v_cndmask_b32_e64 v114, v115, v116, s[0:1]
	v_mul_f32_e32 v115, 0x37800000, v114
	v_cndmask_b32_e32 v114, v114, v115, vcc
	v_cmp_class_f32_e32 vcc, v113, v201
	s_nop 1
	v_cndmask_b32_e32 v113, v114, v113, vcc
	v_div_scale_f32 v114, s[0:1], v113, v113, 1.0
	v_rcp_f32_e32 v115, v114
	s_nop 0
	v_fma_f32 v116, -v114, v115, 1.0
	v_fmac_f32_e32 v115, v116, v115
	v_div_scale_f32 v116, vcc, 1.0, v113, 1.0
	v_mul_f32_e32 v117, v116, v115
	v_fma_f32 v118, -v114, v117, v116
	v_fmac_f32_e32 v117, v118, v115
	v_fma_f32 v114, -v114, v117, v116
	v_div_fmas_f32 v114, v114, v115, v117
	v_div_fixup_f32 v132, v114, v113, 1.0
	v_ashrrev_i32_e32 v113, 31, v112
	v_lshl_add_u64 v[114:115], v[144:145], 0, v[112:113]
	v_lshlrev_b64 v[112:113], 5, v[112:113]
	v_lshl_add_u64 v[112:113], v[112:113], 0, s[24:25]
	v_mad_u64_u32 v[130:131], s[0:1], v114, s67, v[146:147]
	v_lshlrev_b64 v[112:113], 2, v[112:113]
	v_mad_i32_i24 v131, v115, s67, v131
	v_lshl_add_u64 v[114:115], s[26:27], 0, v[112:113]
	v_lshl_add_u64 v[112:113], s[42:43], 0, v[112:113]
	v_lshl_add_u64 v[134:135], v[114:115], 0, v[160:161]
	v_lshl_add_u64 v[148:149], v[112:113], 0, v[160:161]
	global_load_dwordx4 v[116:119], v[134:135], off
	global_load_dwordx4 v[112:115], v[148:149], off
	global_load_dwordx4 v[124:127], v160, s[6:7]
	global_load_dwordx4 v[120:123], v160, s[6:7] offset:128
	global_load_dwordx4 v[230:233], v[134:135], off offset:16
	global_load_dwordx4 v[234:237], v[148:149], off offset:16
	global_load_dwordx4 v[238:241], v160, s[6:7] offset:16
	global_load_dwordx4 v[242:245], v160, s[6:7] offset:144
	v_pk_mul_f32 v[104:105], v[104:105], v[132:133] op_sel_hi:[1,0]
	v_pk_mul_f32 v[106:107], v[106:107], v[132:133] op_sel_hi:[1,0]
	v_pk_mul_f32 v[110:111], v[110:111], v[132:133] op_sel_hi:[1,0]
	v_pk_mul_f32 v[108:109], v[108:109], v[132:133] op_sel_hi:[1,0]
	v_pk_mul_f32 v[96:97], v[96:97], v[132:133] op_sel_hi:[1,0]
	v_pk_mul_f32 v[98:99], v[98:99], v[132:133] op_sel_hi:[1,0]
	v_pk_mul_f32 v[102:103], v[102:103], v[132:133] op_sel_hi:[1,0]
	v_pk_mul_f32 v[100:101], v[100:101], v[132:133] op_sel_hi:[1,0]
	s_waitcnt vmcnt(5)
	v_pk_mul_f32 v[108:109], v[124:125], v[108:109]
	s_waitcnt vmcnt(4)
	v_pk_mul_f32 v[106:107], v[122:123], v[106:107]
	v_pk_mul_f32 v[104:105], v[120:121], v[104:105]
	v_pk_mul_f32 v[110:111], v[126:127], v[110:111]
	v_pk_mul_f32 v[120:121], v[112:113], v[104:105]
	v_pk_mul_f32 v[122:123], v[114:115], v[106:107]
	v_pk_mul_f32 v[104:105], v[116:117], v[104:105]
	v_pk_fma_f32 v[122:123], v[118:119], v[110:111], v[122:123] neg_lo:[0,0,1] neg_hi:[0,0,1]
	v_pk_fma_f32 v[120:121], v[116:117], v[108:109], v[120:121] neg_lo:[0,0,1] neg_hi:[0,0,1]
	v_pk_mul_f32 v[106:107], v[118:119], v[106:107]
	v_pk_fma_f32 v[108:109], v[112:113], v[108:109], v[104:105]
	v_pk_fma_f32 v[106:107], v[114:115], v[110:111], v[106:107]
	v_cvt_pk_bf16_f32 v104, v120, v121
	v_cvt_pk_bf16_f32 v105, v122, v123
	v_cvt_pk_bf16_f32 v108, v108, v109
	s_nop 0
	v_cvt_pk_bf16_f32 v109, v106, v107
	s_waitcnt vmcnt(1)
; __device__ __forceinline__ unsigned cvt_pk_bf16(float lo, float hi) { unsigned r; asm volatile("v_cvt_pk_bf16_f32 %0, %1, %2" : "=v"(r) : "v"(lo), "v"(hi)); return r; }
;     __device__ __forceinline__ void operator()(const f32x4 (&acc)[2][2][4][2], const Unit& u, int wr_, int wc_, int fr_, int fq_) const {
;     ...
;                 for (int m = 0; m < 4; ++m) { int rl = ai * HALF + wr * 64 + m * 16 + fr; asm volatile("" : "+v"(rl)); float s = 0.f;
; #pragma unroll
;                     for (int bj = 0; bj < 2; ++bj)
; #pragma unroll
;                         for (int n = 0; n < 2; ++n) { const f32x4 x = acc[ai][bj][m][n]; s += (x[0] * x[0] + x[1] * x[1]) + (x[2] * x[2] + x[3] * x[3]); }
;                     s += __shfl_xor(s, 16); s += __shfl_xor(s, 32);
;                     const float rr = 1.0f / sqrtf(s * (1.0f / 64.0f) + RMS_EPS_F);
;                     const size_t t = (size_t)u.pm * BM + rl;
;                     bf16_t* qrow = Q + ((size_t)(b * 4 + wc) * 8192 + s0 + rl) * 192 + 128;
;                     u32x4 wa, wb;
; #pragma unroll
;                     for (int n = 0; n < 2; ++n) { const int j0 = 8 * fq + 4 * n;
;                         const f32x4 c4 = *(const f32x4*)(cosT + t * 32 + j0), s4 = *(const f32x4*)(sinT + t * 32 + j0);
;                         const f32x4 g1 = *(const f32x4*)(gn_rope + j0), g2 = *(const f32x4*)(gn_rope + 32 + j0);
;                         const f32x4 y1 = acc[ai][0][m][n] * rr * g1, y2 = acc[ai][1][m][n] * rr * g2;
;                         const f32x4 o1 = y1 * c4 - y2 * s4, o2 = y2 * c4 + y1 * s4;
;                         wa[2 * n] = cvt_pk_bf16(o1[0], o1[1]); wa[2 * n + 1] = cvt_pk_bf16(o1[2], o1[3]); wb[2 * n] = cvt_pk_bf16(o2[0], o2[1]); wb[2 * n + 1] = cvt_pk_bf16(o2[2], o2[3]); }
;                     *(u32x4*)(qrow + 8 * fq) = wa; *(u32x4*)(qrow + 32 + 8 * fq) = wb;
;                     asm volatile("" ::: "memory"); }
	v_pk_mul_f32 v[100:101], v[100:101], v[238:239]
	s_waitcnt vmcnt(0)
	v_pk_mul_f32 v[98:99], v[98:99], v[244:245]
	v_pk_mul_f32 v[96:97], v[96:97], v[242:243]
	v_pk_mul_f32 v[102:103], v[102:103], v[240:241]
	v_pk_mul_f32 v[106:107], v[234:235], v[96:97]
	v_pk_mul_f32 v[118:119], v[236:237], v[98:99]
	v_pk_mul_f32 v[98:99], v[232:233], v[98:99]
	v_pk_fma_f32 v[106:107], v[230:231], v[100:101], v[106:107] neg_lo:[0,0,1] neg_hi:[0,0,1]
	v_pk_mul_f32 v[96:97], v[230:231], v[96:97]
	v_pk_fma_f32 v[98:99], v[236:237], v[102:103], v[98:99]
	v_pk_fma_f32 v[118:119], v[232:233], v[102:103], v[118:119] neg_lo:[0,0,1] neg_hi:[0,0,1]
	v_pk_fma_f32 v[96:97], v[234:235], v[100:101], v[96:97]
	v_cvt_pk_bf16_f32 v106, v106, v107
	v_cvt_pk_bf16_f32 v107, v118, v119
	v_pk_mul_f32 v[100:101], v[92:93], v[92:93]
	v_cvt_pk_bf16_f32 v110, v96, v97
	v_cvt_pk_bf16_f32 v111, v98, v99
	v_pk_mul_f32 v[98:99], v[94:95], v[94:95]
	v_lshl_add_u64 v[96:97], v[130:131], 0, v[128:129]
	v_pk_mov_b32 v[102:103], v[100:101], v[98:99] op_sel:[1,0]
	v_mov_b32_e32 v101, v99
	v_pk_add_f32 v[98:99], v[102:103], v[100:101]
	v_pk_mul_f32 v[100:101], v[86:87], v[86:87]
	v_pk_add_f32 v[98:99], v[98:99], v[98:99] op_sel_hi:[0,1]
	v_pk_mul_f32 v[102:103], v[84:85], v[84:85]
	global_store_dwordx4 v[96:97], v[104:107], off offset:256
	global_store_dwordx4 v[96:97], v[108:111], off offset:320
	v_mul_f32_e32 v98, v88, v88
	v_pk_mov_b32 v[104:105], v[102:103], v[100:101] op_sel:[1,0]
	v_mov_b32_e32 v103, v101
	v_pk_add_f32 v[100:101], v[104:105], v[102:103]
	v_pk_fma_f32 v[102:103], v[88:89], v[88:89], v[98:99] op_sel_hi:[1,1,0]
	v_mul_f32_e32 v98, v90, v90
	v_pk_add_f32 v[100:101], v[100:101], v[100:101] op_sel_hi:[0,1]
	v_pk_fma_f32 v[104:105], v[90:91], v[90:91], v[98:99] op_sel_hi:[1,1,0]
	v_mul_f32_e32 v102, v80, v80
	v_mul_f32_e32 v104, v81, v81
	v_mul_f32_e32 v100, v82, v82
	v_mul_f32_e32 v98, v83, v83
	v_pk_add_f32 v[102:103], v[102:103], v[104:105]
	v_pk_add_f32 v[98:99], v[100:101], v[98:99]
	v_or_b32_e32 v96, 32, v166
	v_pk_add_f32 v[98:99], v[102:103], v[98:99]
	s_nop 0
	v_add_f32_e32 v97, v98, v99
	v_mov_b32_e32 v98, v97
	s_nop 1
	v_permlane16_swap_b32_e32 v97, v98
	v_add_f32_e32 v97, v97, v98
	v_mov_b32_e32 v98, v97
	s_nop 1
	v_permlane32_swap_b32_e32 v97, v98
	v_add_f32_e32 v97, v97, v98
	v_fmamk_f32 v97, v97, 0x3c800000, v199
	v_cmp_gt_f32_e32 vcc, s19, v97
	v_mul_f32_e32 v98, 0x4f800000, v97
	s_nop 0
	v_cndmask_b32_e32 v97, v97, v98, vcc
	v_sqrt_f32_e32 v98, v97
	s_nop 0
	v_add_u32_e32 v99, -1, v98
	v_fma_f32 v100, -v99, v98, v97
	v_cmp_ge_f32_e64 s[0:1], 0, v100
	v_add_u32_e32 v100, 1, v98
	s_nop 0
	v_cndmask_b32_e64 v99, v98, v99, s[0:1]
	v_fma_f32 v98, -v100, v98, v97
	v_cmp_lt_f32_e64 s[0:1], 0, v98
	s_nop 1
	v_cndmask_b32_e64 v98, v99, v100, s[0:1]
	v_mul_f32_e32 v99, 0x37800000, v98
	v_cndmask_b32_e32 v98, v98, v99, vcc
	v_cmp_class_f32_e32 vcc, v97, v201
	s_nop 1
	v_cndmask_b32_e32 v97, v98, v97, vcc
	v_div_scale_f32 v98, s[0:1], v97, v97, 1.0
	v_rcp_f32_e32 v99, v98
	s_nop 0
	v_fma_f32 v100, -v98, v99, 1.0
	v_fmac_f32_e32 v99, v100, v99
	v_div_scale_f32 v100, vcc, 1.0, v97, 1.0
	v_mul_f32_e32 v101, v100, v99
	v_fma_f32 v102, -v98, v101, v100
	v_fmac_f32_e32 v101, v102, v99
	v_fma_f32 v98, -v98, v101, v100
	v_div_fmas_f32 v98, v98, v99, v101
	v_div_fixup_f32 v114, v98, v97, 1.0
	v_ashrrev_i32_e32 v97, 31, v96
	v_lshl_add_u64 v[98:99], v[144:145], 0, v[96:97]
	v_lshlrev_b64 v[96:97], 5, v[96:97]
	v_lshl_add_u64 v[96:97], v[96:97], 0, s[24:25]
	v_mad_u64_u32 v[112:113], s[0:1], v98, s67, v[146:147]
	v_lshlrev_b64 v[96:97], 2, v[96:97]
	v_mad_i32_i24 v113, v99, s67, v113
	v_lshl_add_u64 v[98:99], s[26:27], 0, v[96:97]
	v_lshl_add_u64 v[96:97], s[42:43], 0, v[96:97]
	v_lshl_add_u64 v[116:117], v[98:99], 0, v[160:161]
	v_lshl_add_u64 v[118:119], v[96:97], 0, v[160:161]
	global_load_dwordx4 v[100:103], v[116:117], off
	global_load_dwordx4 v[96:99], v[118:119], off
	global_load_dwordx4 v[108:111], v160, s[6:7]
	global_load_dwordx4 v[104:107], v160, s[6:7] offset:128
	global_load_dwordx4 v[230:233], v[116:117], off offset:16
	global_load_dwordx4 v[234:237], v[118:119], off offset:16
	global_load_dwordx4 v[238:241], v160, s[6:7] offset:16
	global_load_dwordx4 v[242:245], v160, s[6:7] offset:144
	v_pk_mul_f32 v[88:89], v[88:89], v[114:115] op_sel_hi:[1,0]
	v_pk_mul_f32 v[90:91], v[90:91], v[114:115] op_sel_hi:[1,0]
	v_pk_mul_f32 v[94:95], v[94:95], v[114:115] op_sel_hi:[1,0]
	v_pk_mul_f32 v[92:93], v[92:93], v[114:115] op_sel_hi:[1,0]
	v_pk_mul_f32 v[80:81], v[80:81], v[114:115] op_sel_hi:[1,0]
	v_pk_mul_f32 v[82:83], v[82:83], v[114:115] op_sel_hi:[1,0]
	v_pk_mul_f32 v[86:87], v[86:87], v[114:115] op_sel_hi:[1,0]
	v_pk_mul_f32 v[84:85], v[84:85], v[114:115] op_sel_hi:[1,0]
	s_waitcnt vmcnt(5)
	v_pk_mul_f32 v[92:93], v[108:109], v[92:93]
	s_waitcnt vmcnt(4)
	v_pk_mul_f32 v[90:91], v[106:107], v[90:91]
	v_pk_mul_f32 v[88:89], v[104:105], v[88:89]
	v_pk_mul_f32 v[94:95], v[110:111], v[94:95]
	v_pk_mul_f32 v[104:105], v[96:97], v[88:89]
	v_pk_mul_f32 v[106:107], v[98:99], v[90:91]
	v_pk_mul_f32 v[88:89], v[100:101], v[88:89]
	v_pk_fma_f32 v[106:107], v[102:103], v[94:95], v[106:107] neg_lo:[0,0,1] neg_hi:[0,0,1]
	v_pk_fma_f32 v[104:105], v[100:101], v[92:93], v[104:105] neg_lo:[0,0,1] neg_hi:[0,0,1]
	v_pk_mul_f32 v[90:91], v[102:103], v[90:91]
	v_pk_fma_f32 v[92:93], v[96:97], v[92:93], v[88:89]
	v_pk_fma_f32 v[90:91], v[98:99], v[94:95], v[90:91]
	v_cvt_pk_bf16_f32 v88, v104, v105
	v_cvt_pk_bf16_f32 v89, v106, v107
	v_cvt_pk_bf16_f32 v92, v92, v93
	s_nop 0
	v_cvt_pk_bf16_f32 v93, v90, v91
	s_waitcnt vmcnt(1)
	v_pk_mul_f32 v[84:85], v[84:85], v[238:239]
	s_waitcnt vmcnt(0)
; __device__ __forceinline__ unsigned cvt_pk_bf16(float lo, float hi) { unsigned r; asm volatile("v_cvt_pk_bf16_f32 %0, %1, %2" : "=v"(r) : "v"(lo), "v"(hi)); return r; }
;     __device__ __forceinline__ void operator()(const f32x4 (&acc)[2][2][4][2], const Unit& u, int wr_, int wc_, int fr_, int fq_) const {
;     ...
;                 for (int m = 0; m < 4; ++m) { int rl = ai * HALF + wr * 64 + m * 16 + fr; asm volatile("" : "+v"(rl)); float s = 0.f;
; #pragma unroll
;                     for (int bj = 0; bj < 2; ++bj)
; #pragma unroll
;                         for (int n = 0; n < 2; ++n) { const f32x4 x = acc[ai][bj][m][n]; s += (x[0] * x[0] + x[1] * x[1]) + (x[2] * x[2] + x[3] * x[3]); }
;                     s += __shfl_xor(s, 16); s += __shfl_xor(s, 32);
;                     const float rr = 1.0f / sqrtf(s * (1.0f / 64.0f) + RMS_EPS_F);
;                     const size_t t = (size_t)u.pm * BM + rl;
;                     bf16_t* qrow = Q + ((size_t)(b * 4 + wc) * 8192 + s0 + rl) * 192 + 128;
;                     u32x4 wa, wb;
; #pragma unroll
;                     for (int n = 0; n < 2; ++n) { const int j0 = 8 * fq + 4 * n;
;                         const f32x4 c4 = *(const f32x4*)(cosT + t * 32 + j0), s4 = *(const f32x4*)(sinT + t * 32 + j0);
;                         const f32x4 g1 = *(const f32x4*)(gn_rope + j0), g2 = *(const f32x4*)(gn_rope + 32 + j0);
;                         const f32x4 y1 = acc[ai][0][m][n] * rr * g1, y2 = acc[ai][1][m][n] * rr * g2;
;                         const f32x4 o1 = y1 * c4 - y2 * s4, o2 = y2 * c4 + y1 * s4;
;                         wa[2 * n] = cvt_pk_bf16(o1[0], o1[1]); wa[2 * n + 1] = cvt_pk_bf16(o1[2], o1[3]); wb[2 * n] = cvt_pk_bf16(o2[0], o2[1]); wb[2 * n + 1] = cvt_pk_bf16(o2[2], o2[3]); }
;                     *(u32x4*)(qrow + 8 * fq) = wa; *(u32x4*)(qrow + 32 + 8 * fq) = wb;
;                     asm volatile("" ::: "memory"); }
	v_pk_mul_f32 v[82:83], v[82:83], v[244:245]
	v_pk_mul_f32 v[80:81], v[80:81], v[242:243]
	v_pk_mul_f32 v[86:87], v[86:87], v[240:241]
	v_pk_mul_f32 v[90:91], v[234:235], v[80:81]
	v_pk_mul_f32 v[102:103], v[236:237], v[82:83]
	v_pk_mul_f32 v[82:83], v[232:233], v[82:83]
	v_pk_fma_f32 v[90:91], v[230:231], v[84:85], v[90:91] neg_lo:[0,0,1] neg_hi:[0,0,1]
	v_pk_mul_f32 v[80:81], v[230:231], v[80:81]
	v_pk_fma_f32 v[82:83], v[236:237], v[86:87], v[82:83]
	v_pk_fma_f32 v[102:103], v[232:233], v[86:87], v[102:103] neg_lo:[0,0,1] neg_hi:[0,0,1]
	v_pk_fma_f32 v[80:81], v[234:235], v[84:85], v[80:81]
	v_cvt_pk_bf16_f32 v90, v90, v91
	v_cvt_pk_bf16_f32 v91, v102, v103
	v_pk_mul_f32 v[84:85], v[76:77], v[76:77]
	v_cvt_pk_bf16_f32 v94, v80, v81
	v_cvt_pk_bf16_f32 v95, v82, v83
	v_pk_mul_f32 v[82:83], v[78:79], v[78:79]
	v_lshl_add_u64 v[80:81], v[112:113], 0, v[128:129]
	v_pk_mov_b32 v[86:87], v[84:85], v[82:83] op_sel:[1,0]
	v_mov_b32_e32 v85, v83
	v_pk_add_f32 v[82:83], v[86:87], v[84:85]
	v_pk_mul_f32 v[84:85], v[70:71], v[70:71]
	v_pk_add_f32 v[82:83], v[82:83], v[82:83] op_sel_hi:[0,1]
	v_pk_mul_f32 v[86:87], v[68:69], v[68:69]
	global_store_dwordx4 v[80:81], v[88:91], off offset:256
	global_store_dwordx4 v[80:81], v[92:95], off offset:320
	v_mul_f32_e32 v82, v72, v72
	v_pk_mov_b32 v[88:89], v[86:87], v[84:85] op_sel:[1,0]
	v_mov_b32_e32 v87, v85
	v_pk_add_f32 v[84:85], v[88:89], v[86:87]
	v_pk_fma_f32 v[86:87], v[72:73], v[72:73], v[82:83] op_sel_hi:[1,1,0]
	v_mul_f32_e32 v82, v74, v74
	v_pk_add_f32 v[84:85], v[84:85], v[84:85] op_sel_hi:[0,1]
	v_pk_fma_f32 v[88:89], v[74:75], v[74:75], v[82:83] op_sel_hi:[1,1,0]
	v_mul_f32_e32 v86, v64, v64
	v_mul_f32_e32 v88, v65, v65
	v_mul_f32_e32 v84, v66, v66
	v_mul_f32_e32 v82, v67, v67
	v_pk_add_f32 v[86:87], v[86:87], v[88:89]
	v_pk_add_f32 v[82:83], v[84:85], v[82:83]
	v_or_b32_e32 v80, 48, v166
	v_pk_add_f32 v[82:83], v[86:87], v[82:83]
	s_nop 0
	v_add_f32_e32 v81, v82, v83
	v_mov_b32_e32 v82, v81
	s_nop 1
	v_permlane16_swap_b32_e32 v81, v82
	v_add_f32_e32 v81, v81, v82
	v_mov_b32_e32 v82, v81
	s_nop 1
	v_permlane32_swap_b32_e32 v81, v82
	v_add_f32_e32 v81, v81, v82
	v_fmamk_f32 v81, v81, 0x3c800000, v199
	v_cmp_gt_f32_e32 vcc, s19, v81
	v_mul_f32_e32 v82, 0x4f800000, v81
	s_nop 0
	v_cndmask_b32_e32 v81, v81, v82, vcc
	v_sqrt_f32_e32 v82, v81
	s_nop 0
	v_add_u32_e32 v83, -1, v82
	v_fma_f32 v84, -v83, v82, v81
	v_cmp_ge_f32_e64 s[0:1], 0, v84
	v_add_u32_e32 v84, 1, v82
	s_nop 0
	v_cndmask_b32_e64 v83, v82, v83, s[0:1]
	v_fma_f32 v82, -v84, v82, v81
	v_cmp_lt_f32_e64 s[0:1], 0, v82
	s_nop 1
	v_cndmask_b32_e64 v82, v83, v84, s[0:1]
	v_mul_f32_e32 v83, 0x37800000, v82
	v_cndmask_b32_e32 v82, v82, v83, vcc
	v_cmp_class_f32_e32 vcc, v81, v201
	s_nop 1
	v_cndmask_b32_e32 v81, v82, v81, vcc
	v_div_scale_f32 v82, s[0:1], v81, v81, 1.0
	v_rcp_f32_e32 v83, v82
	s_nop 0
	v_fma_f32 v84, -v82, v83, 1.0
	v_fmac_f32_e32 v83, v84, v83
	v_div_scale_f32 v84, vcc, 1.0, v81, 1.0
	v_mul_f32_e32 v85, v84, v83
	v_fma_f32 v86, -v82, v85, v84
	v_fmac_f32_e32 v85, v86, v83
	v_fma_f32 v82, -v82, v85, v84
	v_div_fmas_f32 v82, v82, v83, v85
	v_div_fixup_f32 v98, v82, v81, 1.0
	v_ashrrev_i32_e32 v81, 31, v80
	v_lshl_add_u64 v[82:83], v[144:145], 0, v[80:81]
	v_lshlrev_b64 v[80:81], 5, v[80:81]
	v_lshl_add_u64 v[80:81], v[80:81], 0, s[24:25]
	v_mad_u64_u32 v[96:97], s[0:1], v82, s67, v[146:147]
	v_lshlrev_b64 v[80:81], 2, v[80:81]
	v_mad_i32_i24 v97, v83, s67, v97
	v_lshl_add_u64 v[82:83], s[26:27], 0, v[80:81]
	v_lshl_add_u64 v[80:81], s[42:43], 0, v[80:81]
	v_lshl_add_u64 v[100:101], v[82:83], 0, v[160:161]
	v_lshl_add_u64 v[102:103], v[80:81], 0, v[160:161]
	global_load_dwordx4 v[84:87], v[100:101], off
	global_load_dwordx4 v[80:83], v[102:103], off
	global_load_dwordx4 v[92:95], v160, s[6:7]
	global_load_dwordx4 v[88:91], v160, s[6:7] offset:128
	global_load_dwordx4 v[230:233], v[100:101], off offset:16
	global_load_dwordx4 v[234:237], v[102:103], off offset:16
	global_load_dwordx4 v[238:241], v160, s[6:7] offset:16
	global_load_dwordx4 v[242:245], v160, s[6:7] offset:144
	v_pk_mul_f32 v[72:73], v[72:73], v[98:99] op_sel_hi:[1,0]
	v_pk_mul_f32 v[74:75], v[74:75], v[98:99] op_sel_hi:[1,0]
	v_pk_mul_f32 v[78:79], v[78:79], v[98:99] op_sel_hi:[1,0]
	v_pk_mul_f32 v[76:77], v[76:77], v[98:99] op_sel_hi:[1,0]
	v_pk_mul_f32 v[64:65], v[64:65], v[98:99] op_sel_hi:[1,0]
	v_pk_mul_f32 v[66:67], v[66:67], v[98:99] op_sel_hi:[1,0]
	v_pk_mul_f32 v[70:71], v[70:71], v[98:99] op_sel_hi:[1,0]
	v_pk_mul_f32 v[68:69], v[68:69], v[98:99] op_sel_hi:[1,0]
	s_waitcnt vmcnt(5)
	v_pk_mul_f32 v[76:77], v[92:93], v[76:77]
	s_waitcnt vmcnt(4)
	v_pk_mul_f32 v[74:75], v[90:91], v[74:75]
	v_pk_mul_f32 v[72:73], v[88:89], v[72:73]
	v_pk_mul_f32 v[78:79], v[94:95], v[78:79]
	v_pk_mul_f32 v[88:89], v[80:81], v[72:73]
	v_pk_mul_f32 v[90:91], v[82:83], v[74:75]
	v_pk_mul_f32 v[72:73], v[84:85], v[72:73]
	v_pk_fma_f32 v[90:91], v[86:87], v[78:79], v[90:91] neg_lo:[0,0,1] neg_hi:[0,0,1]
	v_pk_fma_f32 v[88:89], v[84:85], v[76:77], v[88:89] neg_lo:[0,0,1] neg_hi:[0,0,1]
	v_pk_mul_f32 v[74:75], v[86:87], v[74:75]
	v_pk_fma_f32 v[76:77], v[80:81], v[76:77], v[72:73]
	v_pk_fma_f32 v[74:75], v[82:83], v[78:79], v[74:75]
	v_cvt_pk_bf16_f32 v72, v88, v89
	v_cvt_pk_bf16_f32 v73, v90, v91
	v_cvt_pk_bf16_f32 v76, v76, v77
	s_nop 0
	v_cvt_pk_bf16_f32 v77, v74, v75
	s_waitcnt vmcnt(1)
	v_pk_mul_f32 v[68:69], v[68:69], v[238:239]
	s_waitcnt vmcnt(0)
; __device__ __forceinline__ unsigned cvt_pk_bf16(float lo, float hi) { unsigned r; asm volatile("v_cvt_pk_bf16_f32 %0, %1, %2" : "=v"(r) : "v"(lo), "v"(hi)); return r; }
;     __device__ __forceinline__ void operator()(const f32x4 (&acc)[2][2][4][2], const Unit& u, int wr_, int wc_, int fr_, int fq_) const {
;     ...
;                 for (int m = 0; m < 4; ++m) { int rl = ai * HALF + wr * 64 + m * 16 + fr; asm volatile("" : "+v"(rl)); float s = 0.f;
; #pragma unroll
;                     for (int bj = 0; bj < 2; ++bj)
; #pragma unroll
;                         for (int n = 0; n < 2; ++n) { const f32x4 x = acc[ai][bj][m][n]; s += (x[0] * x[0] + x[1] * x[1]) + (x[2] * x[2] + x[3] * x[3]); }
;                     s += __shfl_xor(s, 16); s += __shfl_xor(s, 32);
;                     const float rr = 1.0f / sqrtf(s * (1.0f / 64.0f) + RMS_EPS_F);
;                     const size_t t = (size_t)u.pm * BM + rl;
;                     bf16_t* qrow = Q + ((size_t)(b * 4 + wc) * 8192 + s0 + rl) * 192 + 128;
;                     u32x4 wa, wb;
; #pragma unroll
;                     for (int n = 0; n < 2; ++n) { const int j0 = 8 * fq + 4 * n;
;                         const f32x4 c4 = *(const f32x4*)(cosT + t * 32 + j0), s4 = *(const f32x4*)(sinT + t * 32 + j0);
;                         const f32x4 g1 = *(const f32x4*)(gn_rope + j0), g2 = *(const f32x4*)(gn_rope + 32 + j0);
;                         const f32x4 y1 = acc[ai][0][m][n] * rr * g1, y2 = acc[ai][1][m][n] * rr * g2;
;                         const f32x4 o1 = y1 * c4 - y2 * s4, o2 = y2 * c4 + y1 * s4;
;                         wa[2 * n] = cvt_pk_bf16(o1[0], o1[1]); wa[2 * n + 1] = cvt_pk_bf16(o1[2], o1[3]); wb[2 * n] = cvt_pk_bf16(o2[0], o2[1]); wb[2 * n + 1] = cvt_pk_bf16(o2[2], o2[3]); }
;                     *(u32x4*)(qrow + 8 * fq) = wa; *(u32x4*)(qrow + 32 + 8 * fq) = wb;
;                     asm volatile("" ::: "memory"); }
	v_pk_mul_f32 v[66:67], v[66:67], v[244:245]
	v_pk_mul_f32 v[64:65], v[64:65], v[242:243]
	v_pk_mul_f32 v[70:71], v[70:71], v[240:241]
	v_pk_mul_f32 v[74:75], v[234:235], v[64:65]
	v_pk_mul_f32 v[86:87], v[236:237], v[66:67]
	v_pk_mul_f32 v[66:67], v[232:233], v[66:67]
	v_pk_fma_f32 v[74:75], v[230:231], v[68:69], v[74:75] neg_lo:[0,0,1] neg_hi:[0,0,1]
	v_pk_mul_f32 v[64:65], v[230:231], v[64:65]
	v_pk_fma_f32 v[66:67], v[236:237], v[70:71], v[66:67]
	v_pk_fma_f32 v[86:87], v[232:233], v[70:71], v[86:87] neg_lo:[0,0,1] neg_hi:[0,0,1]
	v_pk_fma_f32 v[64:65], v[234:235], v[68:69], v[64:65]
	v_cvt_pk_bf16_f32 v74, v74, v75
	v_cvt_pk_bf16_f32 v75, v86, v87
	v_pk_mul_f32 v[68:69], v[60:61], v[60:61]
	v_cvt_pk_bf16_f32 v78, v64, v65
	v_cvt_pk_bf16_f32 v79, v66, v67
	v_pk_mul_f32 v[66:67], v[62:63], v[62:63]
	v_lshl_add_u64 v[64:65], v[96:97], 0, v[128:129]
	v_pk_mov_b32 v[70:71], v[68:69], v[66:67] op_sel:[1,0]
	v_mov_b32_e32 v69, v67
	v_pk_add_f32 v[66:67], v[70:71], v[68:69]
	v_pk_mul_f32 v[68:69], v[54:55], v[54:55]
	v_pk_add_f32 v[66:67], v[66:67], v[66:67] op_sel_hi:[0,1]
	v_pk_mul_f32 v[70:71], v[52:53], v[52:53]
	global_store_dwordx4 v[64:65], v[72:75], off offset:256
	global_store_dwordx4 v[64:65], v[76:79], off offset:320
	v_mul_f32_e32 v66, v56, v56
	v_pk_mov_b32 v[72:73], v[70:71], v[68:69] op_sel:[1,0]
	v_mov_b32_e32 v71, v69
	v_pk_add_f32 v[68:69], v[72:73], v[70:71]
	v_pk_fma_f32 v[70:71], v[56:57], v[56:57], v[66:67] op_sel_hi:[1,1,0]
	v_mul_f32_e32 v66, v58, v58
	v_pk_add_f32 v[68:69], v[68:69], v[68:69] op_sel_hi:[0,1]
	v_pk_fma_f32 v[72:73], v[58:59], v[58:59], v[66:67] op_sel_hi:[1,1,0]
	v_mul_f32_e32 v70, v48, v48
	v_mul_f32_e32 v72, v49, v49
	v_mul_f32_e32 v68, v50, v50
	v_mul_f32_e32 v66, v51, v51
	v_pk_add_f32 v[70:71], v[70:71], v[72:73]
	v_pk_add_f32 v[66:67], v[68:69], v[66:67]
	v_add_u32_e32 v64, 0x80, v166
	v_pk_add_f32 v[66:67], v[70:71], v[66:67]
	s_nop 0
	v_add_f32_e32 v65, v66, v67
	v_mov_b32_e32 v66, v65
	s_nop 1
	v_permlane16_swap_b32_e32 v65, v66
	v_add_f32_e32 v65, v65, v66
	v_mov_b32_e32 v66, v65
	s_nop 1
	v_permlane32_swap_b32_e32 v65, v66
	v_add_f32_e32 v65, v65, v66
	v_fmamk_f32 v65, v65, 0x3c800000, v199
	v_cmp_gt_f32_e32 vcc, s19, v65
	v_mul_f32_e32 v66, 0x4f800000, v65
	s_nop 0
	v_cndmask_b32_e32 v65, v65, v66, vcc
	v_sqrt_f32_e32 v66, v65
	s_nop 0
	v_add_u32_e32 v67, -1, v66
	v_fma_f32 v68, -v67, v66, v65
	v_cmp_ge_f32_e64 s[0:1], 0, v68
	v_add_u32_e32 v68, 1, v66
	s_nop 0
	v_cndmask_b32_e64 v67, v66, v67, s[0:1]
	v_fma_f32 v66, -v68, v66, v65
	v_cmp_lt_f32_e64 s[0:1], 0, v66
	s_nop 1
	v_cndmask_b32_e64 v66, v67, v68, s[0:1]
	v_mul_f32_e32 v67, 0x37800000, v66
	v_cndmask_b32_e32 v66, v66, v67, vcc
	v_cmp_class_f32_e32 vcc, v65, v201
	s_nop 1
	v_cndmask_b32_e32 v65, v66, v65, vcc
	v_div_scale_f32 v66, s[0:1], v65, v65, 1.0
	v_rcp_f32_e32 v67, v66
	s_nop 0
	v_fma_f32 v68, -v66, v67, 1.0
	v_fmac_f32_e32 v67, v68, v67
	v_div_scale_f32 v68, vcc, 1.0, v65, 1.0
	v_mul_f32_e32 v69, v68, v67
	v_fma_f32 v70, -v66, v69, v68
	v_fmac_f32_e32 v69, v70, v67
	v_fma_f32 v66, -v66, v69, v68
	v_div_fmas_f32 v66, v66, v67, v69
	v_div_fixup_f32 v82, v66, v65, 1.0
	v_ashrrev_i32_e32 v65, 31, v64
	v_lshl_add_u64 v[66:67], v[144:145], 0, v[64:65]
	v_lshlrev_b64 v[64:65], 5, v[64:65]
	v_lshl_add_u64 v[64:65], v[64:65], 0, s[24:25]
	v_mad_u64_u32 v[80:81], s[0:1], v66, s67, v[146:147]
	v_lshlrev_b64 v[64:65], 2, v[64:65]
	v_mad_i32_i24 v81, v67, s67, v81
	v_lshl_add_u64 v[66:67], s[26:27], 0, v[64:65]
	v_lshl_add_u64 v[64:65], s[42:43], 0, v[64:65]
	v_lshl_add_u64 v[84:85], v[66:67], 0, v[160:161]
	v_lshl_add_u64 v[86:87], v[64:65], 0, v[160:161]
	global_load_dwordx4 v[68:71], v[84:85], off
	global_load_dwordx4 v[64:67], v[86:87], off
	global_load_dwordx4 v[76:79], v160, s[6:7]
	global_load_dwordx4 v[72:75], v160, s[6:7] offset:128
	global_load_dwordx4 v[230:233], v[84:85], off offset:16
	global_load_dwordx4 v[234:237], v[86:87], off offset:16
	global_load_dwordx4 v[238:241], v160, s[6:7] offset:16
	global_load_dwordx4 v[242:245], v160, s[6:7] offset:144
	v_pk_mul_f32 v[56:57], v[56:57], v[82:83] op_sel_hi:[1,0]
	v_pk_mul_f32 v[58:59], v[58:59], v[82:83] op_sel_hi:[1,0]
	v_pk_mul_f32 v[62:63], v[62:63], v[82:83] op_sel_hi:[1,0]
	v_pk_mul_f32 v[60:61], v[60:61], v[82:83] op_sel_hi:[1,0]
	v_pk_mul_f32 v[48:49], v[48:49], v[82:83] op_sel_hi:[1,0]
	v_pk_mul_f32 v[50:51], v[50:51], v[82:83] op_sel_hi:[1,0]
	v_pk_mul_f32 v[54:55], v[54:55], v[82:83] op_sel_hi:[1,0]
	v_pk_mul_f32 v[52:53], v[52:53], v[82:83] op_sel_hi:[1,0]
	s_waitcnt vmcnt(5)
	v_pk_mul_f32 v[60:61], v[76:77], v[60:61]
	s_waitcnt vmcnt(4)
	v_pk_mul_f32 v[58:59], v[74:75], v[58:59]
	v_pk_mul_f32 v[56:57], v[72:73], v[56:57]
	v_pk_mul_f32 v[62:63], v[78:79], v[62:63]
	v_pk_mul_f32 v[72:73], v[64:65], v[56:57]
	v_pk_mul_f32 v[74:75], v[66:67], v[58:59]
	v_pk_mul_f32 v[56:57], v[68:69], v[56:57]
	v_pk_fma_f32 v[74:75], v[70:71], v[62:63], v[74:75] neg_lo:[0,0,1] neg_hi:[0,0,1]
	v_pk_fma_f32 v[72:73], v[68:69], v[60:61], v[72:73] neg_lo:[0,0,1] neg_hi:[0,0,1]
	v_pk_mul_f32 v[58:59], v[70:71], v[58:59]
	v_pk_fma_f32 v[60:61], v[64:65], v[60:61], v[56:57]
	v_pk_fma_f32 v[58:59], v[66:67], v[62:63], v[58:59]
	v_cvt_pk_bf16_f32 v56, v72, v73
	v_cvt_pk_bf16_f32 v57, v74, v75
	v_cvt_pk_bf16_f32 v60, v60, v61
	s_nop 0
	v_cvt_pk_bf16_f32 v61, v58, v59
	s_waitcnt vmcnt(1)
	v_pk_mul_f32 v[52:53], v[52:53], v[238:239]
	s_waitcnt vmcnt(0)
; __device__ __forceinline__ unsigned cvt_pk_bf16(float lo, float hi) { unsigned r; asm volatile("v_cvt_pk_bf16_f32 %0, %1, %2" : "=v"(r) : "v"(lo), "v"(hi)); return r; }
;     __device__ __forceinline__ void operator()(const f32x4 (&acc)[2][2][4][2], const Unit& u, int wr_, int wc_, int fr_, int fq_) const {
;     ...
;                 for (int m = 0; m < 4; ++m) { int rl = ai * HALF + wr * 64 + m * 16 + fr; asm volatile("" : "+v"(rl)); float s = 0.f;
; #pragma unroll
;                     for (int bj = 0; bj < 2; ++bj)
; #pragma unroll
;                         for (int n = 0; n < 2; ++n) { const f32x4 x = acc[ai][bj][m][n]; s += (x[0] * x[0] + x[1] * x[1]) + (x[2] * x[2] + x[3] * x[3]); }
;                     s += __shfl_xor(s, 16); s += __shfl_xor(s, 32);
;                     const float rr = 1.0f / sqrtf(s * (1.0f / 64.0f) + RMS_EPS_F);
;                     const size_t t = (size_t)u.pm * BM + rl;
;                     bf16_t* qrow = Q + ((size_t)(b * 4 + wc) * 8192 + s0 + rl) * 192 + 128;
;                     u32x4 wa, wb;
; #pragma unroll
;                     for (int n = 0; n < 2; ++n) { const int j0 = 8 * fq + 4 * n;
;                         const f32x4 c4 = *(const f32x4*)(cosT + t * 32 + j0), s4 = *(const f32x4*)(sinT + t * 32 + j0);
;                         const f32x4 g1 = *(const f32x4*)(gn_rope + j0), g2 = *(const f32x4*)(gn_rope + 32 + j0);
;                         const f32x4 y1 = acc[ai][0][m][n] * rr * g1, y2 = acc[ai][1][m][n] * rr * g2;
;                         const f32x4 o1 = y1 * c4 - y2 * s4, o2 = y2 * c4 + y1 * s4;
;                         wa[2 * n] = cvt_pk_bf16(o1[0], o1[1]); wa[2 * n + 1] = cvt_pk_bf16(o1[2], o1[3]); wb[2 * n] = cvt_pk_bf16(o2[0], o2[1]); wb[2 * n + 1] = cvt_pk_bf16(o2[2], o2[3]); }
;                     *(u32x4*)(qrow + 8 * fq) = wa; *(u32x4*)(qrow + 32 + 8 * fq) = wb;
;                     asm volatile("" ::: "memory"); }
	v_pk_mul_f32 v[50:51], v[50:51], v[244:245]
	v_pk_mul_f32 v[48:49], v[48:49], v[242:243]
	v_pk_mul_f32 v[54:55], v[54:55], v[240:241]
	v_pk_mul_f32 v[58:59], v[234:235], v[48:49]
	v_pk_mul_f32 v[70:71], v[236:237], v[50:51]
	v_pk_mul_f32 v[50:51], v[232:233], v[50:51]
	v_pk_fma_f32 v[58:59], v[230:231], v[52:53], v[58:59] neg_lo:[0,0,1] neg_hi:[0,0,1]
	v_pk_mul_f32 v[48:49], v[230:231], v[48:49]
	v_pk_fma_f32 v[50:51], v[236:237], v[54:55], v[50:51]
	v_pk_fma_f32 v[70:71], v[232:233], v[54:55], v[70:71] neg_lo:[0,0,1] neg_hi:[0,0,1]
	v_pk_fma_f32 v[48:49], v[234:235], v[52:53], v[48:49]
	v_cvt_pk_bf16_f32 v58, v58, v59
	v_cvt_pk_bf16_f32 v59, v70, v71
	v_pk_mul_f32 v[52:53], v[44:45], v[44:45]
	v_cvt_pk_bf16_f32 v62, v48, v49
	v_cvt_pk_bf16_f32 v63, v50, v51
	v_pk_mul_f32 v[50:51], v[46:47], v[46:47]
	v_lshl_add_u64 v[48:49], v[80:81], 0, v[128:129]
	v_pk_mov_b32 v[54:55], v[52:53], v[50:51] op_sel:[1,0]
	v_mov_b32_e32 v53, v51
	v_pk_add_f32 v[50:51], v[54:55], v[52:53]
	v_pk_mul_f32 v[52:53], v[38:39], v[38:39]
	v_pk_add_f32 v[50:51], v[50:51], v[50:51] op_sel_hi:[0,1]
	v_pk_mul_f32 v[54:55], v[36:37], v[36:37]
	global_store_dwordx4 v[48:49], v[56:59], off offset:256
	global_store_dwordx4 v[48:49], v[60:63], off offset:320
	v_mul_f32_e32 v50, v40, v40
	v_pk_mov_b32 v[56:57], v[54:55], v[52:53] op_sel:[1,0]
	v_mov_b32_e32 v55, v53
	v_pk_add_f32 v[52:53], v[56:57], v[54:55]
	v_pk_fma_f32 v[54:55], v[40:41], v[40:41], v[50:51] op_sel_hi:[1,1,0]
	v_mul_f32_e32 v50, v42, v42
	v_pk_add_f32 v[52:53], v[52:53], v[52:53] op_sel_hi:[0,1]
	v_pk_fma_f32 v[56:57], v[42:43], v[42:43], v[50:51] op_sel_hi:[1,1,0]
	v_mul_f32_e32 v54, v32, v32
	v_mul_f32_e32 v56, v33, v33
	v_mul_f32_e32 v52, v34, v34
	v_mul_f32_e32 v50, v35, v35
	v_pk_add_f32 v[54:55], v[54:55], v[56:57]
	v_pk_add_f32 v[50:51], v[52:53], v[50:51]
	v_add_u32_e32 v48, 0x90, v166
	v_pk_add_f32 v[50:51], v[54:55], v[50:51]
	s_nop 0
	v_add_f32_e32 v49, v50, v51
	v_mov_b32_e32 v50, v49
	s_nop 1
	v_permlane16_swap_b32_e32 v49, v50
	v_add_f32_e32 v49, v49, v50
	v_mov_b32_e32 v50, v49
	s_nop 1
	v_permlane32_swap_b32_e32 v49, v50
	v_add_f32_e32 v49, v49, v50
	v_fmamk_f32 v49, v49, 0x3c800000, v199
	v_cmp_gt_f32_e32 vcc, s19, v49
	v_mul_f32_e32 v50, 0x4f800000, v49
	s_nop 0
	v_cndmask_b32_e32 v49, v49, v50, vcc
	v_sqrt_f32_e32 v50, v49
	s_nop 0
	v_add_u32_e32 v51, -1, v50
	v_fma_f32 v52, -v51, v50, v49
	v_cmp_ge_f32_e64 s[0:1], 0, v52
	v_add_u32_e32 v52, 1, v50
	s_nop 0
	v_cndmask_b32_e64 v51, v50, v51, s[0:1]
	v_fma_f32 v50, -v52, v50, v49
	v_cmp_lt_f32_e64 s[0:1], 0, v50
	s_nop 1
	v_cndmask_b32_e64 v50, v51, v52, s[0:1]
	v_mul_f32_e32 v51, 0x37800000, v50
	v_cndmask_b32_e32 v50, v50, v51, vcc
	v_cmp_class_f32_e32 vcc, v49, v201
	s_nop 1
	v_cndmask_b32_e32 v49, v50, v49, vcc
	v_div_scale_f32 v50, s[0:1], v49, v49, 1.0
	v_rcp_f32_e32 v51, v50
	s_nop 0
	v_fma_f32 v52, -v50, v51, 1.0
	v_fmac_f32_e32 v51, v52, v51
	v_div_scale_f32 v52, vcc, 1.0, v49, 1.0
	v_mul_f32_e32 v53, v52, v51
	v_fma_f32 v54, -v50, v53, v52
	v_fmac_f32_e32 v53, v54, v51
	v_fma_f32 v50, -v50, v53, v52
	v_div_fmas_f32 v50, v50, v51, v53
	v_div_fixup_f32 v66, v50, v49, 1.0
	v_ashrrev_i32_e32 v49, 31, v48
	v_lshl_add_u64 v[50:51], v[144:145], 0, v[48:49]
	v_lshlrev_b64 v[48:49], 5, v[48:49]
	v_lshl_add_u64 v[48:49], v[48:49], 0, s[24:25]
	v_mad_u64_u32 v[64:65], s[0:1], v50, s67, v[146:147]
	v_lshlrev_b64 v[48:49], 2, v[48:49]
	v_mad_i32_i24 v65, v51, s67, v65
	v_lshl_add_u64 v[50:51], s[26:27], 0, v[48:49]
	v_lshl_add_u64 v[48:49], s[42:43], 0, v[48:49]
	v_lshl_add_u64 v[68:69], v[50:51], 0, v[160:161]
	v_lshl_add_u64 v[70:71], v[48:49], 0, v[160:161]
	global_load_dwordx4 v[52:55], v[68:69], off
	global_load_dwordx4 v[48:51], v[70:71], off
	global_load_dwordx4 v[60:63], v160, s[6:7]
	global_load_dwordx4 v[56:59], v160, s[6:7] offset:128
	global_load_dwordx4 v[230:233], v[68:69], off offset:16
	global_load_dwordx4 v[234:237], v[70:71], off offset:16
	global_load_dwordx4 v[238:241], v160, s[6:7] offset:16
	global_load_dwordx4 v[242:245], v160, s[6:7] offset:144
	v_pk_mul_f32 v[40:41], v[40:41], v[66:67] op_sel_hi:[1,0]
	v_pk_mul_f32 v[42:43], v[42:43], v[66:67] op_sel_hi:[1,0]
	v_pk_mul_f32 v[46:47], v[46:47], v[66:67] op_sel_hi:[1,0]
	v_pk_mul_f32 v[44:45], v[44:45], v[66:67] op_sel_hi:[1,0]
	v_pk_mul_f32 v[32:33], v[32:33], v[66:67] op_sel_hi:[1,0]
	v_pk_mul_f32 v[34:35], v[34:35], v[66:67] op_sel_hi:[1,0]
	v_pk_mul_f32 v[38:39], v[38:39], v[66:67] op_sel_hi:[1,0]
	v_pk_mul_f32 v[36:37], v[36:37], v[66:67] op_sel_hi:[1,0]
	s_waitcnt vmcnt(5)
	v_pk_mul_f32 v[44:45], v[60:61], v[44:45]
	s_waitcnt vmcnt(4)
	v_pk_mul_f32 v[42:43], v[58:59], v[42:43]
	v_pk_mul_f32 v[40:41], v[56:57], v[40:41]
	v_pk_mul_f32 v[46:47], v[62:63], v[46:47]
	v_pk_mul_f32 v[56:57], v[48:49], v[40:41]
	v_pk_mul_f32 v[58:59], v[50:51], v[42:43]
	v_pk_mul_f32 v[40:41], v[52:53], v[40:41]
	v_pk_fma_f32 v[58:59], v[54:55], v[46:47], v[58:59] neg_lo:[0,0,1] neg_hi:[0,0,1]
	v_pk_fma_f32 v[56:57], v[52:53], v[44:45], v[56:57] neg_lo:[0,0,1] neg_hi:[0,0,1]
	v_pk_mul_f32 v[42:43], v[54:55], v[42:43]
	v_pk_fma_f32 v[44:45], v[48:49], v[44:45], v[40:41]
	v_pk_fma_f32 v[42:43], v[50:51], v[46:47], v[42:43]
	v_cvt_pk_bf16_f32 v40, v56, v57
	v_cvt_pk_bf16_f32 v41, v58, v59
	v_cvt_pk_bf16_f32 v44, v44, v45
	s_nop 0
	v_cvt_pk_bf16_f32 v45, v42, v43
	s_waitcnt vmcnt(1)
	v_pk_mul_f32 v[36:37], v[36:37], v[238:239]
	s_waitcnt vmcnt(0)
; __device__ __forceinline__ unsigned cvt_pk_bf16(float lo, float hi) { unsigned r; asm volatile("v_cvt_pk_bf16_f32 %0, %1, %2" : "=v"(r) : "v"(lo), "v"(hi)); return r; }
;     __device__ __forceinline__ void operator()(const f32x4 (&acc)[2][2][4][2], const Unit& u, int wr_, int wc_, int fr_, int fq_) const {
;     ...
;                 for (int m = 0; m < 4; ++m) { int rl = ai * HALF + wr * 64 + m * 16 + fr; asm volatile("" : "+v"(rl)); float s = 0.f;
; #pragma unroll
;                     for (int bj = 0; bj < 2; ++bj)
; #pragma unroll
;                         for (int n = 0; n < 2; ++n) { const f32x4 x = acc[ai][bj][m][n]; s += (x[0] * x[0] + x[1] * x[1]) + (x[2] * x[2] + x[3] * x[3]); }
;                     s += __shfl_xor(s, 16); s += __shfl_xor(s, 32);
;                     const float rr = 1.0f / sqrtf(s * (1.0f / 64.0f) + RMS_EPS_F);
;                     const size_t t = (size_t)u.pm * BM + rl;
;                     bf16_t* qrow = Q + ((size_t)(b * 4 + wc) * 8192 + s0 + rl) * 192 + 128;
;                     u32x4 wa, wb;
; #pragma unroll
;                     for (int n = 0; n < 2; ++n) { const int j0 = 8 * fq + 4 * n;
;                         const f32x4 c4 = *(const f32x4*)(cosT + t * 32 + j0), s4 = *(const f32x4*)(sinT + t * 32 + j0);
;                         const f32x4 g1 = *(const f32x4*)(gn_rope + j0), g2 = *(const f32x4*)(gn_rope + 32 + j0);
;                         const f32x4 y1 = acc[ai][0][m][n] * rr * g1, y2 = acc[ai][1][m][n] * rr * g2;
;                         const f32x4 o1 = y1 * c4 - y2 * s4, o2 = y2 * c4 + y1 * s4;
;                         wa[2 * n] = cvt_pk_bf16(o1[0], o1[1]); wa[2 * n + 1] = cvt_pk_bf16(o1[2], o1[3]); wb[2 * n] = cvt_pk_bf16(o2[0], o2[1]); wb[2 * n + 1] = cvt_pk_bf16(o2[2], o2[3]); }
;                     *(u32x4*)(qrow + 8 * fq) = wa; *(u32x4*)(qrow + 32 + 8 * fq) = wb;
;                     asm volatile("" ::: "memory"); }
	v_pk_mul_f32 v[34:35], v[34:35], v[244:245]
	v_pk_mul_f32 v[32:33], v[32:33], v[242:243]
	v_pk_mul_f32 v[38:39], v[38:39], v[240:241]
	v_pk_mul_f32 v[42:43], v[234:235], v[32:33]
	v_pk_mul_f32 v[54:55], v[236:237], v[34:35]
	v_pk_mul_f32 v[34:35], v[232:233], v[34:35]
	v_pk_fma_f32 v[42:43], v[230:231], v[36:37], v[42:43] neg_lo:[0,0,1] neg_hi:[0,0,1]
	v_pk_mul_f32 v[32:33], v[230:231], v[32:33]
	v_pk_fma_f32 v[34:35], v[236:237], v[38:39], v[34:35]
	v_pk_fma_f32 v[54:55], v[232:233], v[38:39], v[54:55] neg_lo:[0,0,1] neg_hi:[0,0,1]
	v_pk_fma_f32 v[32:33], v[234:235], v[36:37], v[32:33]
	v_cvt_pk_bf16_f32 v42, v42, v43
	v_cvt_pk_bf16_f32 v43, v54, v55
	v_pk_mul_f32 v[36:37], v[28:29], v[28:29]
	v_cvt_pk_bf16_f32 v46, v32, v33
	v_cvt_pk_bf16_f32 v47, v34, v35
	v_pk_mul_f32 v[34:35], v[30:31], v[30:31]
	v_lshl_add_u64 v[32:33], v[64:65], 0, v[128:129]
	v_pk_mov_b32 v[38:39], v[36:37], v[34:35] op_sel:[1,0]
	v_mov_b32_e32 v37, v35
	v_pk_add_f32 v[34:35], v[38:39], v[36:37]
	v_pk_mul_f32 v[36:37], v[22:23], v[22:23]
	v_pk_add_f32 v[34:35], v[34:35], v[34:35] op_sel_hi:[0,1]
	v_pk_mul_f32 v[38:39], v[20:21], v[20:21]
	global_store_dwordx4 v[32:33], v[40:43], off offset:256
	global_store_dwordx4 v[32:33], v[44:47], off offset:320
	v_mul_f32_e32 v34, v24, v24
	v_pk_mov_b32 v[40:41], v[38:39], v[36:37] op_sel:[1,0]
	v_mov_b32_e32 v39, v37
	v_pk_add_f32 v[36:37], v[40:41], v[38:39]
	v_pk_fma_f32 v[38:39], v[24:25], v[24:25], v[34:35] op_sel_hi:[1,1,0]
	v_mul_f32_e32 v34, v26, v26
	v_pk_add_f32 v[36:37], v[36:37], v[36:37] op_sel_hi:[0,1]
	v_pk_fma_f32 v[40:41], v[26:27], v[26:27], v[34:35] op_sel_hi:[1,1,0]
	v_mul_f32_e32 v38, v16, v16
	v_mul_f32_e32 v40, v17, v17
	v_mul_f32_e32 v36, v18, v18
	v_mul_f32_e32 v34, v19, v19
	v_pk_add_f32 v[38:39], v[38:39], v[40:41]
	v_pk_add_f32 v[34:35], v[36:37], v[34:35]
	v_add_u32_e32 v32, 0xa0, v166
	v_pk_add_f32 v[34:35], v[38:39], v[34:35]
	s_nop 0
	v_add_f32_e32 v33, v34, v35
	v_mov_b32_e32 v34, v33
	s_nop 1
	v_permlane16_swap_b32_e32 v33, v34
	v_add_f32_e32 v33, v33, v34
	v_mov_b32_e32 v34, v33
	s_nop 1
	v_permlane32_swap_b32_e32 v33, v34
	v_add_f32_e32 v33, v33, v34
	v_fmamk_f32 v33, v33, 0x3c800000, v199
	v_cmp_gt_f32_e32 vcc, s19, v33
	v_mul_f32_e32 v34, 0x4f800000, v33
	s_nop 0
	v_cndmask_b32_e32 v33, v33, v34, vcc
	v_sqrt_f32_e32 v34, v33
	s_nop 0
	v_add_u32_e32 v35, -1, v34
	v_fma_f32 v36, -v35, v34, v33
	v_cmp_ge_f32_e64 s[0:1], 0, v36
	v_add_u32_e32 v36, 1, v34
	s_nop 0
	v_cndmask_b32_e64 v35, v34, v35, s[0:1]
	v_fma_f32 v34, -v36, v34, v33
	v_cmp_lt_f32_e64 s[0:1], 0, v34
	s_nop 1
	v_cndmask_b32_e64 v34, v35, v36, s[0:1]
	v_mul_f32_e32 v35, 0x37800000, v34
	v_cndmask_b32_e32 v34, v34, v35, vcc
	v_cmp_class_f32_e32 vcc, v33, v201
	s_nop 1
	v_cndmask_b32_e32 v33, v34, v33, vcc
	v_div_scale_f32 v34, s[0:1], v33, v33, 1.0
	v_rcp_f32_e32 v35, v34
	s_nop 0
	v_fma_f32 v36, -v34, v35, 1.0
	v_fmac_f32_e32 v35, v36, v35
	v_div_scale_f32 v36, vcc, 1.0, v33, 1.0
	v_mul_f32_e32 v37, v36, v35
	v_fma_f32 v38, -v34, v37, v36
	v_fmac_f32_e32 v37, v38, v35
	v_fma_f32 v34, -v34, v37, v36
	v_div_fmas_f32 v34, v34, v35, v37
	v_div_fixup_f32 v50, v34, v33, 1.0
	v_ashrrev_i32_e32 v33, 31, v32
	v_lshl_add_u64 v[34:35], v[144:145], 0, v[32:33]
	v_lshlrev_b64 v[32:33], 5, v[32:33]
	v_lshl_add_u64 v[32:33], v[32:33], 0, s[24:25]
	v_mad_u64_u32 v[48:49], s[0:1], v34, s67, v[146:147]
	v_lshlrev_b64 v[32:33], 2, v[32:33]
	v_mad_i32_i24 v49, v35, s67, v49
	v_lshl_add_u64 v[34:35], s[26:27], 0, v[32:33]
	v_lshl_add_u64 v[32:33], s[42:43], 0, v[32:33]
	v_lshl_add_u64 v[52:53], v[34:35], 0, v[160:161]
	v_lshl_add_u64 v[54:55], v[32:33], 0, v[160:161]
	global_load_dwordx4 v[36:39], v[52:53], off
	global_load_dwordx4 v[32:35], v[54:55], off
	global_load_dwordx4 v[44:47], v160, s[6:7]
	global_load_dwordx4 v[40:43], v160, s[6:7] offset:128
	global_load_dwordx4 v[230:233], v[52:53], off offset:16
	global_load_dwordx4 v[234:237], v[54:55], off offset:16
	global_load_dwordx4 v[238:241], v160, s[6:7] offset:16
	global_load_dwordx4 v[242:245], v160, s[6:7] offset:144
	v_pk_mul_f32 v[24:25], v[24:25], v[50:51] op_sel_hi:[1,0]
	v_pk_mul_f32 v[26:27], v[26:27], v[50:51] op_sel_hi:[1,0]
	v_pk_mul_f32 v[30:31], v[30:31], v[50:51] op_sel_hi:[1,0]
	v_pk_mul_f32 v[28:29], v[28:29], v[50:51] op_sel_hi:[1,0]
	v_pk_mul_f32 v[16:17], v[16:17], v[50:51] op_sel_hi:[1,0]
	v_pk_mul_f32 v[18:19], v[18:19], v[50:51] op_sel_hi:[1,0]
	v_pk_mul_f32 v[22:23], v[22:23], v[50:51] op_sel_hi:[1,0]
	v_pk_mul_f32 v[20:21], v[20:21], v[50:51] op_sel_hi:[1,0]
	s_waitcnt vmcnt(5)
	v_pk_mul_f32 v[28:29], v[44:45], v[28:29]
	s_waitcnt vmcnt(4)
	v_pk_mul_f32 v[26:27], v[42:43], v[26:27]
	v_pk_mul_f32 v[24:25], v[40:41], v[24:25]
	v_pk_mul_f32 v[30:31], v[46:47], v[30:31]
	v_pk_mul_f32 v[40:41], v[32:33], v[24:25]
	v_pk_mul_f32 v[42:43], v[34:35], v[26:27]
	v_pk_mul_f32 v[24:25], v[36:37], v[24:25]
	v_pk_fma_f32 v[42:43], v[38:39], v[30:31], v[42:43] neg_lo:[0,0,1] neg_hi:[0,0,1]
	v_pk_fma_f32 v[40:41], v[36:37], v[28:29], v[40:41] neg_lo:[0,0,1] neg_hi:[0,0,1]
	v_pk_mul_f32 v[26:27], v[38:39], v[26:27]
	v_pk_fma_f32 v[28:29], v[32:33], v[28:29], v[24:25]
	v_pk_fma_f32 v[26:27], v[34:35], v[30:31], v[26:27]
	v_cvt_pk_bf16_f32 v24, v40, v41
	v_cvt_pk_bf16_f32 v25, v42, v43
	v_cvt_pk_bf16_f32 v28, v28, v29
	s_nop 0
	v_cvt_pk_bf16_f32 v29, v26, v27
	s_waitcnt vmcnt(1)
	v_pk_mul_f32 v[20:21], v[20:21], v[238:239]
	s_waitcnt vmcnt(0)
; __device__ __forceinline__ unsigned cvt_pk_bf16(float lo, float hi) { unsigned r; asm volatile("v_cvt_pk_bf16_f32 %0, %1, %2" : "=v"(r) : "v"(lo), "v"(hi)); return r; }
;     __device__ __forceinline__ void operator()(const f32x4 (&acc)[2][2][4][2], const Unit& u, int wr_, int wc_, int fr_, int fq_) const {
;     ...
;                 for (int m = 0; m < 4; ++m) { int rl = ai * HALF + wr * 64 + m * 16 + fr; asm volatile("" : "+v"(rl)); float s = 0.f;
; #pragma unroll
;                     for (int bj = 0; bj < 2; ++bj)
; #pragma unroll
;                         for (int n = 0; n < 2; ++n) { const f32x4 x = acc[ai][bj][m][n]; s += (x[0] * x[0] + x[1] * x[1]) + (x[2] * x[2] + x[3] * x[3]); }
;                     s += __shfl_xor(s, 16); s += __shfl_xor(s, 32);
;                     const float rr = 1.0f / sqrtf(s * (1.0f / 64.0f) + RMS_EPS_F);
;                     const size_t t = (size_t)u.pm * BM + rl;
;                     bf16_t* qrow = Q + ((size_t)(b * 4 + wc) * 8192 + s0 + rl) * 192 + 128;
;                     u32x4 wa, wb;
; #pragma unroll
;                     for (int n = 0; n < 2; ++n) { const int j0 = 8 * fq + 4 * n;
;                         const f32x4 c4 = *(const f32x4*)(cosT + t * 32 + j0), s4 = *(const f32x4*)(sinT + t * 32 + j0);
;                         const f32x4 g1 = *(const f32x4*)(gn_rope + j0), g2 = *(const f32x4*)(gn_rope + 32 + j0);
;                         const f32x4 y1 = acc[ai][0][m][n] * rr * g1, y2 = acc[ai][1][m][n] * rr * g2;
;                         const f32x4 o1 = y1 * c4 - y2 * s4, o2 = y2 * c4 + y1 * s4;
;                         wa[2 * n] = cvt_pk_bf16(o1[0], o1[1]); wa[2 * n + 1] = cvt_pk_bf16(o1[2], o1[3]); wb[2 * n] = cvt_pk_bf16(o2[0], o2[1]); wb[2 * n + 1] = cvt_pk_bf16(o2[2], o2[3]); }
;                     *(u32x4*)(qrow + 8 * fq) = wa; *(u32x4*)(qrow + 32 + 8 * fq) = wb;
;                     asm volatile("" ::: "memory"); }
	v_pk_mul_f32 v[18:19], v[18:19], v[244:245]
	v_pk_mul_f32 v[16:17], v[16:17], v[242:243]
	v_pk_mul_f32 v[22:23], v[22:23], v[240:241]
	v_pk_mul_f32 v[26:27], v[234:235], v[16:17]
	v_pk_mul_f32 v[38:39], v[236:237], v[18:19]
	v_pk_mul_f32 v[18:19], v[232:233], v[18:19]
	v_pk_fma_f32 v[26:27], v[230:231], v[20:21], v[26:27] neg_lo:[0,0,1] neg_hi:[0,0,1]
	v_pk_mul_f32 v[16:17], v[230:231], v[16:17]
	v_pk_fma_f32 v[18:19], v[236:237], v[22:23], v[18:19]
	v_pk_fma_f32 v[38:39], v[232:233], v[22:23], v[38:39] neg_lo:[0,0,1] neg_hi:[0,0,1]
	v_pk_fma_f32 v[16:17], v[234:235], v[20:21], v[16:17]
	v_cvt_pk_bf16_f32 v26, v26, v27
	v_cvt_pk_bf16_f32 v27, v38, v39
	v_pk_mul_f32 v[20:21], v[12:13], v[12:13]
	v_cvt_pk_bf16_f32 v30, v16, v17
	v_cvt_pk_bf16_f32 v31, v18, v19
	v_pk_mul_f32 v[18:19], v[14:15], v[14:15]
	v_lshl_add_u64 v[16:17], v[48:49], 0, v[128:129]
	v_pk_mov_b32 v[22:23], v[20:21], v[18:19] op_sel:[1,0]
	v_mov_b32_e32 v21, v19
	v_pk_add_f32 v[18:19], v[22:23], v[20:21]
	v_pk_mul_f32 v[20:21], v[6:7], v[6:7]
	v_pk_add_f32 v[18:19], v[18:19], v[18:19] op_sel_hi:[0,1]
	v_pk_mul_f32 v[22:23], v[4:5], v[4:5]
	global_store_dwordx4 v[16:17], v[24:27], off offset:256
	global_store_dwordx4 v[16:17], v[28:31], off offset:320
	v_mul_f32_e32 v18, v8, v8
	v_pk_mov_b32 v[24:25], v[22:23], v[20:21] op_sel:[1,0]
	v_mov_b32_e32 v23, v21
	v_pk_add_f32 v[20:21], v[24:25], v[22:23]
	v_pk_fma_f32 v[22:23], v[8:9], v[8:9], v[18:19] op_sel_hi:[1,1,0]
	v_mul_f32_e32 v18, v10, v10
	v_pk_add_f32 v[20:21], v[20:21], v[20:21] op_sel_hi:[0,1]
	v_pk_fma_f32 v[24:25], v[10:11], v[10:11], v[18:19] op_sel_hi:[1,1,0]
	v_mul_f32_e32 v22, v0, v0
	v_mul_f32_e32 v24, v1, v1
	v_mul_f32_e32 v20, v2, v2
	v_mul_f32_e32 v18, v3, v3
	v_pk_add_f32 v[22:23], v[22:23], v[24:25]
	v_pk_add_f32 v[18:19], v[20:21], v[18:19]
	v_add_u32_e32 v16, 0xb0, v166
	v_pk_add_f32 v[18:19], v[22:23], v[18:19]
	s_nop 0
	v_add_f32_e32 v17, v18, v19
	v_mov_b32_e32 v18, v17
	s_nop 1
	v_permlane16_swap_b32_e32 v17, v18
	v_add_f32_e32 v17, v17, v18
	v_mov_b32_e32 v18, v17
	s_nop 1
	v_permlane32_swap_b32_e32 v17, v18
	v_add_f32_e32 v17, v17, v18
	v_fmamk_f32 v17, v17, 0x3c800000, v199
	v_cmp_gt_f32_e32 vcc, s19, v17
	v_mul_f32_e32 v18, 0x4f800000, v17
	s_nop 0
	v_cndmask_b32_e32 v17, v17, v18, vcc
	v_sqrt_f32_e32 v18, v17
	s_nop 0
	v_add_u32_e32 v19, -1, v18
	v_fma_f32 v20, -v19, v18, v17
	v_cmp_ge_f32_e64 s[0:1], 0, v20
	v_add_u32_e32 v20, 1, v18
	s_nop 0
	v_cndmask_b32_e64 v19, v18, v19, s[0:1]
	v_fma_f32 v18, -v20, v18, v17
	v_cmp_lt_f32_e64 s[0:1], 0, v18
	s_nop 1
	v_cndmask_b32_e64 v18, v19, v20, s[0:1]
	v_mul_f32_e32 v19, 0x37800000, v18
	v_cndmask_b32_e32 v18, v18, v19, vcc
	v_cmp_class_f32_e32 vcc, v17, v201
	s_nop 1
	v_cndmask_b32_e32 v17, v18, v17, vcc
	v_div_scale_f32 v18, s[0:1], v17, v17, 1.0
	v_rcp_f32_e32 v19, v18
	s_nop 0
	v_fma_f32 v20, -v18, v19, 1.0
	v_fmac_f32_e32 v19, v20, v19
	v_div_scale_f32 v20, vcc, 1.0, v17, 1.0
	v_mul_f32_e32 v21, v20, v19
	v_fma_f32 v22, -v18, v21, v20
	v_fmac_f32_e32 v21, v22, v19
	v_fma_f32 v18, -v18, v21, v20
	v_div_fmas_f32 v18, v18, v19, v21
	v_div_fixup_f32 v34, v18, v17, 1.0
	v_ashrrev_i32_e32 v17, 31, v16
	v_lshl_add_u64 v[18:19], v[144:145], 0, v[16:17]
	v_lshlrev_b64 v[16:17], 5, v[16:17]
	v_lshl_add_u64 v[16:17], v[16:17], 0, s[24:25]
	v_mad_u64_u32 v[32:33], s[0:1], v18, s67, v[146:147]
	v_lshlrev_b64 v[16:17], 2, v[16:17]
	v_mad_i32_i24 v33, v19, s67, v33
	v_lshl_add_u64 v[18:19], s[26:27], 0, v[16:17]
	v_lshl_add_u64 v[16:17], s[42:43], 0, v[16:17]
	v_lshl_add_u64 v[36:37], v[18:19], 0, v[160:161]
	v_lshl_add_u64 v[38:39], v[16:17], 0, v[160:161]
	global_load_dwordx4 v[20:23], v[36:37], off
	global_load_dwordx4 v[16:19], v[38:39], off
	global_load_dwordx4 v[28:31], v160, s[6:7]
	global_load_dwordx4 v[24:27], v160, s[6:7] offset:128
	global_load_dwordx4 v[230:233], v[36:37], off offset:16
	global_load_dwordx4 v[234:237], v[38:39], off offset:16
	global_load_dwordx4 v[238:241], v160, s[6:7] offset:16
	global_load_dwordx4 v[242:245], v160, s[6:7] offset:144
	v_pk_mul_f32 v[8:9], v[8:9], v[34:35] op_sel_hi:[1,0]
	v_pk_mul_f32 v[10:11], v[10:11], v[34:35] op_sel_hi:[1,0]
	v_pk_mul_f32 v[14:15], v[14:15], v[34:35] op_sel_hi:[1,0]
	v_pk_mul_f32 v[12:13], v[12:13], v[34:35] op_sel_hi:[1,0]
	v_pk_mul_f32 v[0:1], v[0:1], v[34:35] op_sel_hi:[1,0]
	v_pk_mul_f32 v[4:5], v[4:5], v[34:35] op_sel_hi:[1,0]
	v_pk_mul_f32 v[2:3], v[2:3], v[34:35] op_sel_hi:[1,0]
	v_pk_mul_f32 v[6:7], v[6:7], v[34:35] op_sel_hi:[1,0]
	s_mov_b64 s[0:1], -1
	s_and_b64 vcc, exec, s[2:3]
	s_waitcnt vmcnt(5)
	v_pk_mul_f32 v[12:13], v[28:29], v[12:13]
	s_waitcnt vmcnt(4)
	v_pk_mul_f32 v[10:11], v[26:27], v[10:11]
	v_pk_mul_f32 v[8:9], v[24:25], v[8:9]
	v_pk_mul_f32 v[14:15], v[30:31], v[14:15]
	v_pk_mul_f32 v[24:25], v[16:17], v[8:9]
	v_pk_mul_f32 v[26:27], v[18:19], v[10:11]
	v_pk_mul_f32 v[8:9], v[20:21], v[8:9]
	v_pk_fma_f32 v[26:27], v[22:23], v[14:15], v[26:27] neg_lo:[0,0,1] neg_hi:[0,0,1]
	v_pk_fma_f32 v[24:25], v[20:21], v[12:13], v[24:25] neg_lo:[0,0,1] neg_hi:[0,0,1]
	v_pk_mul_f32 v[10:11], v[22:23], v[10:11]
	v_pk_fma_f32 v[12:13], v[16:17], v[12:13], v[8:9]
	v_pk_fma_f32 v[10:11], v[18:19], v[14:15], v[10:11]
	v_cvt_pk_bf16_f32 v8, v24, v25
	v_cvt_pk_bf16_f32 v9, v26, v27
	v_cvt_pk_bf16_f32 v12, v12, v13
	s_nop 0
	v_cvt_pk_bf16_f32 v13, v10, v11
	s_waitcnt vmcnt(1)
	v_pk_mul_f32 v[4:5], v[4:5], v[238:239]
	s_waitcnt vmcnt(0)
	v_pk_mul_f32 v[0:1], v[0:1], v[242:243]
	v_pk_mul_f32 v[2:3], v[2:3], v[244:245]
	v_pk_mul_f32 v[10:11], v[234:235], v[0:1]
	v_pk_mul_f32 v[0:1], v[230:231], v[0:1]
	v_pk_mul_f32 v[6:7], v[6:7], v[240:241]
	v_pk_mul_f32 v[22:23], v[236:237], v[2:3]
	v_pk_fma_f32 v[10:11], v[230:231], v[4:5], v[10:11] neg_lo:[0,0,1] neg_hi:[0,0,1]
	v_pk_fma_f32 v[0:1], v[234:235], v[4:5], v[0:1]
	v_pk_fma_f32 v[22:23], v[232:233], v[6:7], v[22:23] neg_lo:[0,0,1] neg_hi:[0,0,1]
	v_pk_mul_f32 v[2:3], v[232:233], v[2:3]
	v_cvt_pk_bf16_f32 v10, v10, v11
	v_cvt_pk_bf16_f32 v11, v22, v23
	v_cvt_pk_bf16_f32 v14, v0, v1
	v_lshl_add_u64 v[0:1], v[32:33], 0, v[128:129]
	v_pk_fma_f32 v[2:3], v[236:237], v[6:7], v[2:3]
	s_nop 0
	v_cvt_pk_bf16_f32 v15, v2, v3
	global_store_dwordx4 v[0:1], v[8:11], off offset:256
	global_store_dwordx4 v[0:1], v[12:15], off offset:320
	s_cbranch_vccnz .LBB0_418
	s_andn2_b64 vcc, exec, s[14:15]
	s_cbranch_vccnz .LBB0_417
	s_barrier
	s_branch .LBB0_417

;     __device__ __forceinline__ void operator()(const f32x4 (&acc)[2][2][4][2], const Unit& u, int wr_, int wc_, int fr_, int fq_) const {
;     ...
; #pragma unroll
;         for (int ai = 0; ai < 2; ++ai)
; #pragma unroll
;             for (int m = 0; m < 4; ++m) { float s = 0.f;
; #pragma unroll
;                 for (int n = 0; n < 2; ++n) { const f32x4 x = acc[ai][0][m][n]; s += (x[0] * x[0] + x[1] * x[1]) + (x[2] * x[2] + x[3] * x[3]); }
;                 s += __shfl_xor(s, 16); s += __shfl_xor(s, 32);
;                 if (fq == 0) P[(ai * HALF + wr * 64 + m * 16 + fr) * 4 + wc] = s; }
.LBB0_457:
	v_mul_f32_e32 v143, v125, v125
	v_mul_f32_e32 v144, v127, v127
	v_fmac_f32_e32 v143, v124, v124
	v_fmac_f32_e32 v144, v126, v126
	v_add_f32_e32 v143, v143, v144
	v_mul_f32_e32 v144, v117, v117
	v_mul_f32_e32 v145, v119, v119
	v_cmp_lt_i32_e32 vcc, v200, v192
	v_fmac_f32_e32 v144, v116, v116
	v_fmac_f32_e32 v145, v118, v118
	v_cndmask_b32_e32 v142, v191, v200, vcc
	v_add_f32_e32 v144, v144, v145
	v_lshlrev_b32_e32 v142, 2, v142
	v_add_f32_e32 v144, v144, v143
	v_mov_b32_e32 v145, v144
	s_nop 1
	v_permlane16_swap_b32_e32 v144, v145
	v_cmp_lt_i32_e32 vcc, v198, v192
	v_mov_b32_e32 v141, v190
	s_add_i32 s24, 0, 0x20000
	v_cndmask_b32_e32 v143, v191, v198, vcc
	v_lshlrev_b32_e32 v143, 2, v143
	s_waitcnt lgkmcnt(0)
	v_add_f32_e32 v145, v144, v145
	v_mov_b32_e32 v146, v145
	s_nop 1
	v_permlane32_swap_b32_e32 v145, v146
	v_and_b32_e32 v140, 15, v141
	v_bfe_u32 v150, v141, 4, 2
	v_bfe_u32 v151, v141, 6, 2
	v_ashrrev_i32_e32 v141, 8, v141
	v_lshl_add_u32 v144, v151, 2, s24
	v_lshlrev_b32_e32 v149, 10, v141
	v_lshlrev_b32_e32 v152, 4, v140
	v_cmp_eq_u32_e32 vcc, 0, v150
	v_add3_u32 v144, v144, v149, v152
	s_and_saveexec_b64 s[6:7], vcc
	s_cbranch_execz .LBB0_459
	s_waitcnt lgkmcnt(0)
	v_add_f32_e32 v145, v145, v146
	ds_write_b32 v144, v145
.LBB0_459:
	s_or_b64 exec, exec, s[6:7]
	v_mul_f32_e32 v145, v109, v109
	s_waitcnt lgkmcnt(0)
	v_mul_f32_e32 v146, v111, v111
	v_fmac_f32_e32 v145, v108, v108
	v_fmac_f32_e32 v146, v110, v110
	v_add_f32_e32 v145, v145, v146
	v_mul_f32_e32 v146, v101, v101
	v_mul_f32_e32 v149, v103, v103
	v_fmac_f32_e32 v146, v100, v100
	v_fmac_f32_e32 v149, v102, v102
	v_add_f32_e32 v146, v146, v149
	v_add_f32_e32 v145, v146, v145
	v_mov_b32_e32 v146, v145
	s_nop 1
	v_permlane16_swap_b32_e32 v145, v146
	v_add_f32_e32 v145, v145, v146
	v_mov_b32_e32 v146, v145
	s_nop 1
	v_permlane32_swap_b32_e32 v145, v146
	s_and_saveexec_b64 s[6:7], vcc
	s_cbranch_execz .LBB0_461
	s_waitcnt lgkmcnt(0)
	v_add_f32_e32 v145, v145, v146
	ds_write_b32 v144, v145 offset:256
.LBB0_461:
	s_or_b64 exec, exec, s[6:7]
	v_mul_f32_e32 v145, v93, v93
	s_waitcnt lgkmcnt(0)
	v_mul_f32_e32 v146, v95, v95
	v_fmac_f32_e32 v145, v92, v92
	v_fmac_f32_e32 v146, v94, v94
	v_add_f32_e32 v145, v145, v146
	v_mul_f32_e32 v146, v85, v85
	v_mul_f32_e32 v149, v87, v87
	v_fmac_f32_e32 v146, v84, v84
	v_fmac_f32_e32 v149, v86, v86
	v_add_f32_e32 v146, v146, v149
	v_add_f32_e32 v145, v146, v145
	v_mov_b32_e32 v146, v145
	s_nop 1
	v_permlane16_swap_b32_e32 v145, v146
	v_add_f32_e32 v145, v145, v146
	v_mov_b32_e32 v146, v145
	s_nop 1
	v_permlane32_swap_b32_e32 v145, v146
	s_and_saveexec_b64 s[6:7], vcc
	s_cbranch_execz .LBB0_463
	s_waitcnt lgkmcnt(0)
	v_add_f32_e32 v145, v145, v146
	ds_write_b32 v144, v145 offset:512
.LBB0_463:
	s_or_b64 exec, exec, s[6:7]
	v_mul_f32_e32 v145, v77, v77
	s_waitcnt lgkmcnt(0)
	v_mul_f32_e32 v146, v79, v79
	v_fmac_f32_e32 v145, v76, v76
	v_fmac_f32_e32 v146, v78, v78
	v_add_f32_e32 v145, v145, v146
	v_mul_f32_e32 v146, v69, v69
	v_mul_f32_e32 v149, v71, v71
	v_fmac_f32_e32 v146, v68, v68
	v_fmac_f32_e32 v149, v70, v70
	v_add_f32_e32 v146, v146, v149
	v_add_f32_e32 v145, v146, v145
	v_mov_b32_e32 v146, v145
	s_nop 1
	v_permlane16_swap_b32_e32 v145, v146
	v_add_f32_e32 v145, v145, v146
	v_mov_b32_e32 v146, v145
	s_nop 1
	v_permlane32_swap_b32_e32 v145, v146
	s_and_saveexec_b64 s[6:7], vcc
	s_cbranch_execz .LBB0_465
	s_waitcnt lgkmcnt(0)
	v_add_f32_e32 v145, v145, v146
	ds_write_b32 v144, v145 offset:768
.LBB0_465:
	s_or_b64 exec, exec, s[6:7]
	v_mul_f32_e32 v145, v61, v61
	s_waitcnt lgkmcnt(0)
	v_mul_f32_e32 v146, v63, v63
	v_fmac_f32_e32 v145, v60, v60
	v_fmac_f32_e32 v146, v62, v62
	v_add_f32_e32 v145, v145, v146
	v_mul_f32_e32 v146, v53, v53
	v_mul_f32_e32 v149, v55, v55
	v_fmac_f32_e32 v146, v52, v52
	v_fmac_f32_e32 v149, v54, v54
	v_add_f32_e32 v146, v146, v149
	v_add_f32_e32 v145, v146, v145
	v_mov_b32_e32 v146, v145
	s_nop 1
	v_permlane16_swap_b32_e32 v145, v146
	v_add_f32_e32 v145, v145, v146
	v_mov_b32_e32 v146, v145
	s_nop 1
	v_permlane32_swap_b32_e32 v145, v146
	s_and_saveexec_b64 s[6:7], vcc
	s_cbranch_execz .LBB0_467
	s_waitcnt lgkmcnt(0)
	v_add_f32_e32 v145, v145, v146
	ds_write_b32 v144, v145 offset:2048
.LBB0_467:
	s_or_b64 exec, exec, s[6:7]
	v_mul_f32_e32 v145, v45, v45
	s_waitcnt lgkmcnt(0)
	v_mul_f32_e32 v146, v47, v47
	v_fmac_f32_e32 v145, v44, v44
	v_fmac_f32_e32 v146, v46, v46
	v_add_f32_e32 v145, v145, v146
	v_mul_f32_e32 v146, v37, v37
	v_mul_f32_e32 v149, v39, v39
	v_fmac_f32_e32 v146, v36, v36
	v_fmac_f32_e32 v149, v38, v38
	v_add_f32_e32 v146, v146, v149
	v_add_f32_e32 v145, v146, v145
	v_mov_b32_e32 v146, v145
	s_nop 1
	v_permlane16_swap_b32_e32 v145, v146
	v_add_f32_e32 v145, v145, v146
	v_mov_b32_e32 v146, v145
	s_nop 1
	v_permlane32_swap_b32_e32 v145, v146
	s_and_saveexec_b64 s[6:7], vcc
	s_cbranch_execz .LBB0_469
	s_waitcnt lgkmcnt(0)
	v_add_f32_e32 v145, v145, v146
	ds_write_b32 v144, v145 offset:2304
.LBB0_469:
	s_or_b64 exec, exec, s[6:7]
	v_mul_f32_e32 v145, v29, v29
	s_waitcnt lgkmcnt(0)
	v_mul_f32_e32 v146, v31, v31
	v_fmac_f32_e32 v145, v28, v28
	v_fmac_f32_e32 v146, v30, v30
	v_add_f32_e32 v145, v145, v146
	v_mul_f32_e32 v146, v21, v21
	v_mul_f32_e32 v149, v23, v23
	v_fmac_f32_e32 v146, v20, v20
	v_fmac_f32_e32 v149, v22, v22
	v_add_f32_e32 v146, v146, v149
	v_add_f32_e32 v145, v146, v145
	v_mov_b32_e32 v146, v145
	s_nop 1
	v_permlane16_swap_b32_e32 v145, v146
	v_add_f32_e32 v145, v145, v146
	v_mov_b32_e32 v146, v145
	s_nop 1
	v_permlane32_swap_b32_e32 v145, v146
	s_and_saveexec_b64 s[6:7], vcc
	s_cbranch_execz .LBB0_471
	s_waitcnt lgkmcnt(0)
	v_add_f32_e32 v145, v145, v146
	ds_write_b32 v144, v145 offset:2560
.LBB0_471:
	s_or_b64 exec, exec, s[6:7]
	v_mul_f32_e32 v145, v13, v13
	s_waitcnt lgkmcnt(0)
	v_mul_f32_e32 v146, v15, v15
	v_fmac_f32_e32 v145, v12, v12
	v_fmac_f32_e32 v146, v14, v14
	v_add_f32_e32 v145, v145, v146
	v_mul_f32_e32 v146, v5, v5
	v_mul_f32_e32 v149, v7, v7
	v_fmac_f32_e32 v146, v4, v4
	v_fmac_f32_e32 v149, v6, v6
	v_add_f32_e32 v146, v146, v149
	v_add_f32_e32 v145, v146, v145
	v_mov_b32_e32 v142, v145
	s_nop 1
	v_permlane16_swap_b32_e32 v145, v142
	v_add_f32_e32 v142, v145, v142
	v_mov_b32_e32 v143, v142
	s_nop 1
	v_permlane32_swap_b32_e32 v142, v143
	s_and_saveexec_b64 s[6:7], vcc
	s_cbranch_execz .LBB0_473
	s_waitcnt lgkmcnt(0)
	v_add_f32_e32 v142, v142, v143
	ds_write_b32 v144, v142 offset:2816

; #define LAS __attribute__((address_space(3)))
; __device__ __forceinline__ int crow(int r, int hi) { return (r & 3) + 8 * (r >> 2) + 4 * hi; }
; __device__ __forceinline__ float bf2f(unsigned short v) { return __uint_as_float((unsigned)v << 16); }
; __device__ __forceinline__ unsigned f2bf(float f) { return pk2(f, 0.f) & 0xffffu; }
; __device__ __forceinline__ int crow(int r, int hi) { return (r & 3) + 8 * (r >> 2) + 4 * hi; }
; __device__ __forceinline__ void gla_pass_c(LAS unsigned char* ldsl, const bf16_t* __restrict__ proj, const float* __restrict__ Btab, const float* __restrict__ Gst, const float* __restrict__ gout, bf16_t* __restrict__ mixed) {
;     ...
;         { const bf16_t* gp = proj + (row0 + 32 * tb + crw) * NIN + 1024 + h * 128 + ccl * 8; u32x4 sv[8];
; #pragma unroll
;           for (int i = 0; i < 8; ++i) sv[i] = *(const u32x4*)(gp + (size_t)(4 * i) * NIN);
; #pragma unroll
;           for (int i = 0; i < 8; ++i) *(LAS u32x4*)(Lw + (4 * i + crw) * 256 + ccl * 16) = sv[i]; }
;         float gn[4];
; #pragma unroll
;         for (int dvb = 0; dvb < 4; ++dvb) gn[dvb] = gout[32 * dvb + r];
; #pragma unroll
;         for (int i = 0; i < 16; ++i) { const int tr = crow(i, hh);
;             const float tot = half_sum32((o[0][i] * o[0][i] + o[1][i] * o[1][i]) + (o[2][i] * o[2][i] + o[3][i] * o[3][i]));
;             const float rr = __builtin_amdgcn_rsqf(tot * (1.0f / 128.0f) + EPS);
; #pragma unroll
;             for (int dvb = 0; dvb < 4; ++dvb) { const float g = bf2f(Lh[tr * 128 + 32 * dvb + r]);
;                 const float val = o[dvb][i] * rr * gn[dvb] * (g * __builtin_amdgcn_rcpf(1.0f + __expf(-g)));
;                 Lh[(32 + tr) * 128 + 32 * dvb + r] = (bf16_t)f2bf(val); } }
.LBB0_873:
	v_or3_b32 v122, s2, v110, v122
	v_lshlrev_b64 v[64:65], 12, v[122:123]
	v_lshl_add_u64 v[64:65], s[60:61], 0, v[64:65]
	v_lshlrev_b32_e32 v160, 1, v124
	v_lshl_add_u64 v[64:65], v[64:65], 0, v[160:161]
	v_mov_b32_e32 v121, v161
	v_lshl_add_u64 v[92:93], v[64:65], 0, v[120:121]
	v_add_co_u32_e32 v68, vcc, 0x4000, v92
	global_load_dwordx4 v[64:67], v[92:93], off offset:2048
	s_nop 0
	v_addc_co_u32_e32 v69, vcc, 0, v93, vcc
	v_add_co_u32_e32 v72, vcc, 0x8000, v92
	global_load_dwordx4 v[68:71], v[68:69], off offset:2048
	s_nop 0
	v_addc_co_u32_e32 v73, vcc, 0, v93, vcc
	v_add_co_u32_e32 v76, vcc, 0xc000, v92
	global_load_dwordx4 v[72:75], v[72:73], off offset:2048
	s_nop 0
	v_addc_co_u32_e32 v77, vcc, 0, v93, vcc
	v_add_co_u32_e32 v80, vcc, s51, v92
	s_mov_b32 s33, 0x18000
	s_nop 0
	v_addc_co_u32_e32 v81, vcc, 0, v93, vcc
	v_add_co_u32_e32 v84, vcc, s52, v92
	global_load_dwordx4 v[76:79], v[76:77], off offset:2048
	s_nop 0
	v_addc_co_u32_e32 v85, vcc, 0, v93, vcc
	v_add_co_u32_e32 v88, vcc, s33, v92
	global_load_dwordx4 v[80:83], v[80:81], off offset:2048
	s_nop 0
	v_addc_co_u32_e32 v89, vcc, 0, v93, vcc
	s_mov_b32 s2, 0x1c000
	global_load_dwordx4 v[84:87], v[84:85], off offset:2048
	v_add_co_u32_e32 v92, vcc, s2, v92
	global_load_dwordx4 v[88:91], v[88:89], off offset:2048
	s_nop 0
	v_addc_co_u32_e32 v93, vcc, 0, v93, vcc
	global_load_dwordx4 v[92:95], v[92:93], off offset:2048
	s_movk_i32 s2, 0x2000
	s_mov_b32 s42, 0x8000
	s_waitcnt vmcnt(7)
	ds_write_b128 v140, v[64:67]
	s_waitcnt vmcnt(6)
	ds_write_b128 v140, v[68:71] offset:1024
	s_waitcnt vmcnt(5)
	ds_write_b128 v140, v[72:75] offset:2048
	s_waitcnt vmcnt(4)
	ds_write_b128 v140, v[76:79] offset:3072
	s_waitcnt vmcnt(3)
	ds_write_b128 v140, v[80:83] offset:4096
	s_waitcnt vmcnt(2)
	ds_write_b128 v140, v[84:87] offset:5120
	s_waitcnt vmcnt(1)
	ds_write_b128 v140, v[88:91] offset:6144
	s_waitcnt vmcnt(0)
	ds_write_b128 v140, v[92:95] offset:7168
	v_mul_f32_e32 v64, v16, v16
	v_mul_f32_e32 v65, v32, v32
	v_fmac_f32_e32 v64, v0, v0
	v_fmac_f32_e32 v65, v48, v48
	v_add_f32_e32 v64, v64, v65
	ds_read_u16 v144, v138
	ds_read_u16 v145, v138 offset:64
	ds_read_u16 v146, v138 offset:128
	ds_read_u16 v147, v138 offset:192
	s_nop 1
	v_add_f32_dpp v64, v64, v64 quad_perm:[1,0,3,2] row_mask:0xf bank_mask:0xf
	s_nop 1
	v_add_f32_dpp v64, v64, v64 quad_perm:[2,3,0,1] row_mask:0xf bank_mask:0xf
	s_nop 1
	v_add_f32_dpp v64, v64, v64 row_half_mirror row_mask:0xf bank_mask:0xf
	s_nop 1
	v_add_f32_dpp v64, v64, v64 row_mirror row_mask:0xf bank_mask:0xf
	s_waitcnt lgkmcnt(0)
	v_mov_b32_e32 v65, v64
	s_nop 1
	v_permlane16_swap_b32_e32 v64, v65
	v_add_f32_e32 v64, v64, v65
	v_fmamk_f32 v64, v64, 0x3c000000, v199
	v_rsq_f32_e32 v64, v64
	v_lshlrev_b32_e32 v65, 16, v144
	v_mul_f32_e32 v66, 0xbfb8aa3b, v65
	v_exp_f32_e32 v66, v66
	v_mul_f32_e32 v0, v0, v64
	v_mul_f32_e32 v0, v113, v0
	v_mul_f32_e32 v16, v16, v64
	v_add_f32_e32 v66, 1.0, v66
	v_rcp_f32_e32 v66, v66
	v_mul_f32_e32 v16, v130, v16
	v_mul_f32_e32 v65, v66, v65
	v_mul_f32_e32 v0, v0, v65
	v_cvt_pk_bf16_f32 v0, v0, s0
	ds_write_b16 v138, v0 offset:8192
	v_lshlrev_b32_e32 v0, 16, v145
	v_mul_f32_e32 v65, 0xbfb8aa3b, v0
	v_exp_f32_e32 v65, v65
	s_nop 0
	v_add_f32_e32 v65, 1.0, v65
	v_rcp_f32_e32 v65, v65
	s_nop 0
	v_mul_f32_e32 v0, v65, v0
	v_mul_f32_e32 v0, v16, v0
	v_cvt_pk_bf16_f32 v0, v0, s0
	ds_write_b16 v138, v0 offset:8256
	v_mul_f32_e32 v16, v48, v64
	v_mul_f32_e32 v16, v131, v16
	v_lshlrev_b32_e32 v0, 16, v146
	v_mul_f32_e32 v48, 0xbfb8aa3b, v0
	v_exp_f32_e32 v48, v48
	s_nop 0
	v_add_f32_e32 v48, 1.0, v48
	v_rcp_f32_e32 v48, v48
	s_nop 0
	v_mul_f32_e32 v0, v48, v0
	v_mul_f32_e32 v0, v16, v0
	v_cvt_pk_bf16_f32 v0, v0, s0
	ds_write_b16 v138, v0 offset:8320
	v_mul_f32_e32 v16, v32, v64
	v_mul_f32_e32 v16, v132, v16
	v_lshlrev_b32_e32 v0, 16, v147
	v_mul_f32_e32 v32, 0xbfb8aa3b, v0
	v_exp_f32_e32 v32, v32
	s_nop 0
	v_add_f32_e32 v32, 1.0, v32
	v_rcp_f32_e32 v32, v32
	s_nop 0
	v_mul_f32_e32 v0, v32, v0
	v_mul_f32_e32 v0, v16, v0
	v_cvt_pk_bf16_f32 v0, v0, s0
	ds_write_b16 v138, v0 offset:8384
	v_mul_f32_e32 v0, v17, v17
	v_mul_f32_e32 v16, v33, v33
	v_fmac_f32_e32 v0, v1, v1
	v_fmac_f32_e32 v16, v49, v49
	v_add_f32_e32 v0, v0, v16
	ds_read_u16 v144, v138 offset:256
	ds_read_u16 v145, v138 offset:320
	ds_read_u16 v146, v138 offset:384
	ds_read_u16 v147, v138 offset:448
	s_nop 1
	v_add_f32_dpp v0, v0, v0 quad_perm:[1,0,3,2] row_mask:0xf bank_mask:0xf
	s_nop 1
	v_add_f32_dpp v0, v0, v0 quad_perm:[2,3,0,1] row_mask:0xf bank_mask:0xf
	s_nop 1
	v_add_f32_dpp v0, v0, v0 row_half_mirror row_mask:0xf bank_mask:0xf
	s_nop 1
	v_add_f32_dpp v0, v0, v0 row_mirror row_mask:0xf bank_mask:0xf
	s_waitcnt lgkmcnt(0)
; __device__ __forceinline__ int crow(int r, int hi) { return (r & 3) + 8 * (r >> 2) + 4 * hi; }
; __device__ __forceinline__ float bf2f(unsigned short v) { return __uint_as_float((unsigned)v << 16); }
; __device__ __forceinline__ unsigned f2bf(float f) { return pk2(f, 0.f) & 0xffffu; }
; __device__ __forceinline__ int crow(int r, int hi) { return (r & 3) + 8 * (r >> 2) + 4 * hi; }
; __device__ __forceinline__ void gla_pass_c(LAS unsigned char* ldsl, const bf16_t* __restrict__ proj, const float* __restrict__ Btab, const float* __restrict__ Gst, const float* __restrict__ gout, bf16_t* __restrict__ mixed) {
;     ...
;         for (int i = 0; i < 16; ++i) { const int tr = crow(i, hh);
;             const float tot = half_sum32((o[0][i] * o[0][i] + o[1][i] * o[1][i]) + (o[2][i] * o[2][i] + o[3][i] * o[3][i]));
;             const float rr = __builtin_amdgcn_rsqf(tot * (1.0f / 128.0f) + EPS);
; #pragma unroll
;             for (int dvb = 0; dvb < 4; ++dvb) { const float g = bf2f(Lh[tr * 128 + 32 * dvb + r]);
;                 const float val = o[dvb][i] * rr * gn[dvb] * (g * __builtin_amdgcn_rcpf(1.0f + __expf(-g)));
;                 Lh[(32 + tr) * 128 + 32 * dvb + r] = (bf16_t)f2bf(val); } }
	v_mov_b32_e32 v16, v0
	s_nop 1
	v_permlane16_swap_b32_e32 v0, v16
	v_add_f32_e32 v0, v0, v16
	v_fmamk_f32 v0, v0, 0x3c000000, v199
	v_rsq_f32_e32 v0, v0
	v_lshlrev_b32_e32 v16, 16, v144
	v_mul_f32_e32 v32, 0xbfb8aa3b, v16
	v_exp_f32_e32 v32, v32
	v_mul_f32_e32 v1, v1, v0
	v_mul_f32_e32 v1, v113, v1
	v_add_f32_e32 v32, 1.0, v32
	v_rcp_f32_e32 v32, v32
	s_nop 0
	v_mul_f32_e32 v16, v32, v16
	v_mul_f32_e32 v1, v1, v16
	v_cvt_pk_bf16_f32 v1, v1, s0
	ds_write_b16 v138, v1 offset:8448
	v_mul_f32_e32 v16, v17, v0
	v_mul_f32_e32 v16, v130, v16
	v_lshlrev_b32_e32 v1, 16, v145
	v_mul_f32_e32 v17, 0xbfb8aa3b, v1
	v_exp_f32_e32 v17, v17
	s_nop 0
	v_add_f32_e32 v17, 1.0, v17
	v_rcp_f32_e32 v17, v17
	s_nop 0
	v_mul_f32_e32 v1, v17, v1
	v_mul_f32_e32 v1, v16, v1
	v_cvt_pk_bf16_f32 v1, v1, s0
	ds_write_b16 v138, v1 offset:8512
	v_mul_f32_e32 v16, v49, v0
	v_mul_f32_e32 v16, v131, v16
	v_mul_f32_e32 v0, v33, v0
	v_mul_f32_e32 v0, v132, v0
	v_lshlrev_b32_e32 v1, 16, v146
	v_mul_f32_e32 v17, 0xbfb8aa3b, v1
	v_exp_f32_e32 v17, v17
	s_nop 0
	v_add_f32_e32 v17, 1.0, v17
	v_rcp_f32_e32 v17, v17
	s_nop 0
	v_mul_f32_e32 v1, v17, v1
	v_mul_f32_e32 v1, v16, v1
	v_cvt_pk_bf16_f32 v1, v1, s0
	ds_write_b16 v138, v1 offset:8576
	v_lshlrev_b32_e32 v1, 16, v147
	v_mul_f32_e32 v16, 0xbfb8aa3b, v1
	v_exp_f32_e32 v16, v16
	s_nop 0
	v_add_f32_e32 v16, 1.0, v16
	v_rcp_f32_e32 v16, v16
	s_nop 0
	v_mul_f32_e32 v1, v16, v1
	v_mul_f32_e32 v0, v0, v1
	v_cvt_pk_bf16_f32 v0, v0, s0
	ds_write_b16 v138, v0 offset:8640
	v_mul_f32_e32 v0, v18, v18
	v_mul_f32_e32 v1, v34, v34
	v_fmac_f32_e32 v0, v2, v2
	v_fmac_f32_e32 v1, v50, v50
	v_add_f32_e32 v0, v0, v1
	ds_read_u16 v144, v138 offset:512
	ds_read_u16 v145, v138 offset:576
	ds_read_u16 v146, v138 offset:640
	ds_read_u16 v147, v138 offset:704
	s_nop 1
	v_add_f32_dpp v0, v0, v0 quad_perm:[1,0,3,2] row_mask:0xf bank_mask:0xf
	s_nop 1
	v_add_f32_dpp v0, v0, v0 quad_perm:[2,3,0,1] row_mask:0xf bank_mask:0xf
	s_nop 1
	v_add_f32_dpp v0, v0, v0 row_half_mirror row_mask:0xf bank_mask:0xf
	s_nop 1
	v_add_f32_dpp v0, v0, v0 row_mirror row_mask:0xf bank_mask:0xf
	s_waitcnt lgkmcnt(0)
	v_mov_b32_e32 v1, v0
	s_nop 1
	v_permlane16_swap_b32_e32 v0, v1
	v_add_f32_e32 v0, v0, v1
	v_fmamk_f32 v0, v0, 0x3c000000, v199
	v_rsq_f32_e32 v0, v0
	v_lshlrev_b32_e32 v1, 16, v144
	v_mul_f32_e32 v16, 0xbfb8aa3b, v1
	v_exp_f32_e32 v16, v16
	v_mul_f32_e32 v2, v2, v0
	v_mul_f32_e32 v2, v113, v2
	v_add_f32_e32 v16, 1.0, v16
	v_rcp_f32_e32 v16, v16
	s_nop 0
	v_mul_f32_e32 v1, v16, v1
	v_mul_f32_e32 v1, v2, v1
	v_cvt_pk_bf16_f32 v1, v1, s0
	ds_write_b16 v138, v1 offset:8704
	v_mul_f32_e32 v2, v18, v0
	v_mul_f32_e32 v2, v130, v2
	v_lshlrev_b32_e32 v1, 16, v145
	v_mul_f32_e32 v16, 0xbfb8aa3b, v1
	v_exp_f32_e32 v16, v16
	s_nop 0
	v_add_f32_e32 v16, 1.0, v16
	v_rcp_f32_e32 v16, v16
	s_nop 0
	v_mul_f32_e32 v1, v16, v1
	v_mul_f32_e32 v1, v2, v1
	v_cvt_pk_bf16_f32 v1, v1, s0
	ds_write_b16 v138, v1 offset:8768
	v_mul_f32_e32 v2, v50, v0
	v_mul_f32_e32 v2, v131, v2
	v_mul_f32_e32 v0, v34, v0
	v_mul_f32_e32 v0, v132, v0
	v_lshlrev_b32_e32 v1, 16, v146
	v_mul_f32_e32 v16, 0xbfb8aa3b, v1
	v_exp_f32_e32 v16, v16
	s_nop 0
	v_add_f32_e32 v16, 1.0, v16
	v_rcp_f32_e32 v16, v16
	s_nop 0
	v_mul_f32_e32 v1, v16, v1
	v_mul_f32_e32 v1, v2, v1
	v_cvt_pk_bf16_f32 v1, v1, s0
	ds_write_b16 v138, v1 offset:8832
	v_lshlrev_b32_e32 v1, 16, v147
	v_mul_f32_e32 v2, 0xbfb8aa3b, v1
	v_exp_f32_e32 v2, v2
	s_nop 0
	v_add_f32_e32 v2, 1.0, v2
	v_rcp_f32_e32 v2, v2
	s_nop 0
	v_mul_f32_e32 v1, v2, v1
	v_mul_f32_e32 v0, v0, v1
	v_cvt_pk_bf16_f32 v0, v0, s0
	ds_write_b16 v138, v0 offset:8896
	v_mul_f32_e32 v0, v19, v19
	v_mul_f32_e32 v1, v35, v35
	v_fmac_f32_e32 v0, v3, v3
	v_fmac_f32_e32 v1, v51, v51
	v_add_f32_e32 v0, v0, v1
	ds_read_u16 v144, v138 offset:768
	ds_read_u16 v145, v138 offset:832
	ds_read_u16 v146, v138 offset:896
	ds_read_u16 v147, v138 offset:960
	s_nop 1
	v_add_f32_dpp v0, v0, v0 quad_perm:[1,0,3,2] row_mask:0xf bank_mask:0xf
	s_nop 1
	v_add_f32_dpp v0, v0, v0 quad_perm:[2,3,0,1] row_mask:0xf bank_mask:0xf
	s_nop 1
	v_add_f32_dpp v0, v0, v0 row_half_mirror row_mask:0xf bank_mask:0xf
	s_nop 1
	v_add_f32_dpp v0, v0, v0 row_mirror row_mask:0xf bank_mask:0xf
	s_waitcnt lgkmcnt(0)
	v_mov_b32_e32 v1, v0
	s_nop 1
	v_permlane16_swap_b32_e32 v0, v1
	v_add_f32_e32 v0, v0, v1
	v_fmamk_f32 v0, v0, 0x3c000000, v199
	v_rsq_f32_e32 v0, v0
	v_lshlrev_b32_e32 v1, 16, v144
	v_mul_f32_e32 v2, v3, v0
	v_mul_f32_e32 v3, 0xbfb8aa3b, v1
	v_exp_f32_e32 v3, v3
	v_mul_f32_e32 v2, v113, v2
	v_add_f32_e32 v3, 1.0, v3
	v_rcp_f32_e32 v3, v3
	s_nop 0
	v_mul_f32_e32 v1, v3, v1
	v_mul_f32_e32 v1, v2, v1
	v_cvt_pk_bf16_f32 v1, v1, s0
	ds_write_b16 v138, v1 offset:8960
	v_mul_f32_e32 v2, v19, v0
	v_mul_f32_e32 v2, v130, v2
	v_lshlrev_b32_e32 v1, 16, v145
	v_mul_f32_e32 v3, 0xbfb8aa3b, v1
	v_exp_f32_e32 v3, v3
	s_nop 0
	v_add_f32_e32 v3, 1.0, v3
	v_rcp_f32_e32 v3, v3
	s_nop 0
	v_mul_f32_e32 v1, v3, v1
	v_mul_f32_e32 v1, v2, v1
	v_cvt_pk_bf16_f32 v1, v1, s0
	ds_write_b16 v138, v1 offset:9024
	v_mul_f32_e32 v2, v51, v0
	v_mul_f32_e32 v2, v131, v2
	v_mul_f32_e32 v0, v35, v0
	v_mul_f32_e32 v0, v132, v0
	v_lshlrev_b32_e32 v1, 16, v146
	v_mul_f32_e32 v3, 0xbfb8aa3b, v1
	v_exp_f32_e32 v3, v3
	s_nop 0
	v_add_f32_e32 v3, 1.0, v3
	v_rcp_f32_e32 v3, v3
	s_nop 0
	v_mul_f32_e32 v1, v3, v1
	v_mul_f32_e32 v1, v2, v1
	v_cvt_pk_bf16_f32 v1, v1, s0
	ds_write_b16 v138, v1 offset:9088
	v_lshlrev_b32_e32 v1, 16, v147
	v_mul_f32_e32 v2, 0xbfb8aa3b, v1
	v_exp_f32_e32 v2, v2
	s_nop 0
	v_add_f32_e32 v2, 1.0, v2
	v_rcp_f32_e32 v2, v2
	s_nop 0
	v_mul_f32_e32 v1, v2, v1
	v_mul_f32_e32 v0, v0, v1
	v_cvt_pk_bf16_f32 v0, v0, s0
	ds_write_b16 v138, v0 offset:9152
	v_mul_f32_e32 v0, v20, v20
	v_mul_f32_e32 v1, v36, v36
	v_fmac_f32_e32 v0, v4, v4
	v_fmac_f32_e32 v1, v52, v52
	v_add_f32_e32 v0, v0, v1
	ds_read_u16 v144, v138 offset:2048
	ds_read_u16 v145, v138 offset:2112
	ds_read_u16 v146, v138 offset:2176
	ds_read_u16 v147, v138 offset:2240
	s_nop 1
	v_add_f32_dpp v0, v0, v0 quad_perm:[1,0,3,2] row_mask:0xf bank_mask:0xf
	s_nop 1
	v_add_f32_dpp v0, v0, v0 quad_perm:[2,3,0,1] row_mask:0xf bank_mask:0xf
	s_nop 1
	v_add_f32_dpp v0, v0, v0 row_half_mirror row_mask:0xf bank_mask:0xf
	s_nop 1
	v_add_f32_dpp v0, v0, v0 row_mirror row_mask:0xf bank_mask:0xf
	s_waitcnt lgkmcnt(0)
; __device__ __forceinline__ int crow(int r, int hi) { return (r & 3) + 8 * (r >> 2) + 4 * hi; }
; __device__ __forceinline__ float bf2f(unsigned short v) { return __uint_as_float((unsigned)v << 16); }
; __device__ __forceinline__ unsigned f2bf(float f) { return pk2(f, 0.f) & 0xffffu; }
; __device__ __forceinline__ int crow(int r, int hi) { return (r & 3) + 8 * (r >> 2) + 4 * hi; }
; __device__ __forceinline__ void gla_pass_c(LAS unsigned char* ldsl, const bf16_t* __restrict__ proj, const float* __restrict__ Btab, const float* __restrict__ Gst, const float* __restrict__ gout, bf16_t* __restrict__ mixed) {
;     ...
;         for (int i = 0; i < 16; ++i) { const int tr = crow(i, hh);
;             const float tot = half_sum32((o[0][i] * o[0][i] + o[1][i] * o[1][i]) + (o[2][i] * o[2][i] + o[3][i] * o[3][i]));
;             const float rr = __builtin_amdgcn_rsqf(tot * (1.0f / 128.0f) + EPS);
; #pragma unroll
;             for (int dvb = 0; dvb < 4; ++dvb) { const float g = bf2f(Lh[tr * 128 + 32 * dvb + r]);
;                 const float val = o[dvb][i] * rr * gn[dvb] * (g * __builtin_amdgcn_rcpf(1.0f + __expf(-g)));
;                 Lh[(32 + tr) * 128 + 32 * dvb + r] = (bf16_t)f2bf(val); } }
	v_mov_b32_e32 v1, v0
	s_nop 1
	v_permlane16_swap_b32_e32 v0, v1
	v_add_f32_e32 v0, v0, v1
	v_fmamk_f32 v0, v0, 0x3c000000, v199
	v_rsq_f32_e32 v0, v0
	v_lshlrev_b32_e32 v1, 16, v144
	v_mul_f32_e32 v3, 0xbfb8aa3b, v1
	v_exp_f32_e32 v3, v3
	v_mul_f32_e32 v2, v4, v0
	v_mul_f32_e32 v2, v113, v2
	v_add_f32_e32 v3, 1.0, v3
	v_rcp_f32_e32 v3, v3
	s_nop 0
	v_mul_f32_e32 v1, v3, v1
	v_mul_f32_e32 v1, v2, v1
	v_cvt_pk_bf16_f32 v1, v1, s0
	ds_write_b16 v138, v1 offset:10240
	v_mul_f32_e32 v2, v20, v0
	v_mul_f32_e32 v2, v130, v2
	v_lshlrev_b32_e32 v1, 16, v145
	v_mul_f32_e32 v3, 0xbfb8aa3b, v1
	v_exp_f32_e32 v3, v3
	s_nop 0
	v_add_f32_e32 v3, 1.0, v3
	v_rcp_f32_e32 v3, v3
	s_nop 0
	v_mul_f32_e32 v1, v3, v1
	v_mul_f32_e32 v1, v2, v1
	v_cvt_pk_bf16_f32 v1, v1, s0
	ds_write_b16 v138, v1 offset:10304
	v_mul_f32_e32 v2, v52, v0
	v_mul_f32_e32 v2, v131, v2
	v_mul_f32_e32 v0, v36, v0
	v_mul_f32_e32 v0, v132, v0
	v_lshlrev_b32_e32 v1, 16, v146
	v_mul_f32_e32 v3, 0xbfb8aa3b, v1
	v_exp_f32_e32 v3, v3
	s_nop 0
	v_add_f32_e32 v3, 1.0, v3
	v_rcp_f32_e32 v3, v3
	s_nop 0
	v_mul_f32_e32 v1, v3, v1
	v_mul_f32_e32 v1, v2, v1
	v_cvt_pk_bf16_f32 v1, v1, s0
	ds_write_b16 v138, v1 offset:10368
	v_lshlrev_b32_e32 v1, 16, v147
	v_mul_f32_e32 v2, 0xbfb8aa3b, v1
	v_exp_f32_e32 v2, v2
	s_nop 0
	v_add_f32_e32 v2, 1.0, v2
	v_rcp_f32_e32 v2, v2
	s_nop 0
	v_mul_f32_e32 v1, v2, v1
	v_mul_f32_e32 v0, v0, v1
	v_cvt_pk_bf16_f32 v0, v0, s0
	ds_write_b16 v138, v0 offset:10432
	v_mul_f32_e32 v0, v21, v21
	v_mul_f32_e32 v1, v37, v37
	v_fmac_f32_e32 v0, v5, v5
	v_fmac_f32_e32 v1, v53, v53
	v_add_f32_e32 v0, v0, v1
	ds_read_u16 v144, v138 offset:2304
	ds_read_u16 v145, v138 offset:2368
	ds_read_u16 v146, v138 offset:2432
	ds_read_u16 v147, v138 offset:2496
	s_nop 1
	v_add_f32_dpp v0, v0, v0 quad_perm:[1,0,3,2] row_mask:0xf bank_mask:0xf
	s_nop 1
	v_add_f32_dpp v0, v0, v0 quad_perm:[2,3,0,1] row_mask:0xf bank_mask:0xf
	s_nop 1
	v_add_f32_dpp v0, v0, v0 row_half_mirror row_mask:0xf bank_mask:0xf
	s_nop 1
	v_add_f32_dpp v0, v0, v0 row_mirror row_mask:0xf bank_mask:0xf
	s_waitcnt lgkmcnt(0)
	v_mov_b32_e32 v1, v0
	s_nop 1
	v_permlane16_swap_b32_e32 v0, v1
	v_add_f32_e32 v0, v0, v1
	v_fmamk_f32 v0, v0, 0x3c000000, v199
	v_rsq_f32_e32 v0, v0
	v_lshlrev_b32_e32 v1, 16, v144
	v_mul_f32_e32 v3, 0xbfb8aa3b, v1
	v_exp_f32_e32 v3, v3
	v_mul_f32_e32 v2, v5, v0
	v_mul_f32_e32 v2, v113, v2
	v_add_f32_e32 v3, 1.0, v3
	v_rcp_f32_e32 v3, v3
	s_nop 0
	v_mul_f32_e32 v1, v3, v1
	v_mul_f32_e32 v1, v2, v1
	v_cvt_pk_bf16_f32 v1, v1, s0
	ds_write_b16 v138, v1 offset:10496
	v_mul_f32_e32 v2, v21, v0
	v_mul_f32_e32 v2, v130, v2
	v_lshlrev_b32_e32 v1, 16, v145
	v_mul_f32_e32 v3, 0xbfb8aa3b, v1
	v_exp_f32_e32 v3, v3
	s_nop 0
	v_add_f32_e32 v3, 1.0, v3
	v_rcp_f32_e32 v3, v3
	s_nop 0
	v_mul_f32_e32 v1, v3, v1
	v_mul_f32_e32 v1, v2, v1
	v_cvt_pk_bf16_f32 v1, v1, s0
	ds_write_b16 v138, v1 offset:10560
	v_mul_f32_e32 v2, v53, v0
	v_mul_f32_e32 v2, v131, v2
	v_mul_f32_e32 v0, v37, v0
	v_mul_f32_e32 v0, v132, v0
	v_lshlrev_b32_e32 v1, 16, v146
	v_mul_f32_e32 v3, 0xbfb8aa3b, v1
	v_exp_f32_e32 v3, v3
	s_nop 0
	v_add_f32_e32 v3, 1.0, v3
	v_rcp_f32_e32 v3, v3
	s_nop 0
	v_mul_f32_e32 v1, v3, v1
	v_mul_f32_e32 v1, v2, v1
	v_cvt_pk_bf16_f32 v1, v1, s0
	ds_write_b16 v138, v1 offset:10624
	v_lshlrev_b32_e32 v1, 16, v147
	v_mul_f32_e32 v2, 0xbfb8aa3b, v1
	v_exp_f32_e32 v2, v2
	s_nop 0
	v_add_f32_e32 v2, 1.0, v2
	v_rcp_f32_e32 v2, v2
	s_nop 0
	v_mul_f32_e32 v1, v2, v1
	v_mul_f32_e32 v0, v0, v1
	v_cvt_pk_bf16_f32 v0, v0, s0
	ds_write_b16 v138, v0 offset:10688
	v_mul_f32_e32 v0, v22, v22
	v_mul_f32_e32 v1, v38, v38
	v_fmac_f32_e32 v0, v6, v6
	v_fmac_f32_e32 v1, v54, v54
	v_add_f32_e32 v0, v0, v1
	ds_read_u16 v144, v138 offset:2560
	ds_read_u16 v145, v138 offset:2624
	ds_read_u16 v146, v138 offset:2688
	ds_read_u16 v147, v138 offset:2752
	s_nop 1
	v_add_f32_dpp v0, v0, v0 quad_perm:[1,0,3,2] row_mask:0xf bank_mask:0xf
	s_nop 1
	v_add_f32_dpp v0, v0, v0 quad_perm:[2,3,0,1] row_mask:0xf bank_mask:0xf
	s_nop 1
	v_add_f32_dpp v0, v0, v0 row_half_mirror row_mask:0xf bank_mask:0xf
	s_nop 1
	v_add_f32_dpp v0, v0, v0 row_mirror row_mask:0xf bank_mask:0xf
	s_waitcnt lgkmcnt(0)
	v_mov_b32_e32 v1, v0
	s_nop 1
	v_permlane16_swap_b32_e32 v0, v1
	v_add_f32_e32 v0, v0, v1
	v_fmamk_f32 v0, v0, 0x3c000000, v199
	v_rsq_f32_e32 v0, v0
	v_lshlrev_b32_e32 v1, 16, v144
	v_mul_f32_e32 v3, 0xbfb8aa3b, v1
	v_exp_f32_e32 v3, v3
	v_mul_f32_e32 v2, v6, v0
	v_mul_f32_e32 v2, v113, v2
	v_add_f32_e32 v3, 1.0, v3
	v_rcp_f32_e32 v3, v3
	s_nop 0
	v_mul_f32_e32 v1, v3, v1
	v_mul_f32_e32 v1, v2, v1
	v_cvt_pk_bf16_f32 v1, v1, s0
	ds_write_b16 v138, v1 offset:10752
	v_mul_f32_e32 v2, v22, v0
	v_mul_f32_e32 v2, v130, v2
	v_lshlrev_b32_e32 v1, 16, v145
	v_mul_f32_e32 v3, 0xbfb8aa3b, v1
	v_exp_f32_e32 v3, v3
	s_nop 0
	v_add_f32_e32 v3, 1.0, v3
	v_rcp_f32_e32 v3, v3
	s_nop 0
	v_mul_f32_e32 v1, v3, v1
	v_mul_f32_e32 v1, v2, v1
	v_cvt_pk_bf16_f32 v1, v1, s0
	ds_write_b16 v138, v1 offset:10816
	v_mul_f32_e32 v2, v54, v0
	v_mul_f32_e32 v2, v131, v2
	v_mul_f32_e32 v0, v38, v0
	v_mul_f32_e32 v0, v132, v0
	v_lshlrev_b32_e32 v1, 16, v146
	v_mul_f32_e32 v3, 0xbfb8aa3b, v1
	v_exp_f32_e32 v3, v3
	s_nop 0
	v_add_f32_e32 v3, 1.0, v3
	v_rcp_f32_e32 v3, v3
	s_nop 0
	v_mul_f32_e32 v1, v3, v1
	v_mul_f32_e32 v1, v2, v1
	v_cvt_pk_bf16_f32 v1, v1, s0
	ds_write_b16 v138, v1 offset:10880
	v_lshlrev_b32_e32 v1, 16, v147
	v_mul_f32_e32 v2, 0xbfb8aa3b, v1
	v_exp_f32_e32 v2, v2
	s_nop 0
	v_add_f32_e32 v2, 1.0, v2
	v_rcp_f32_e32 v2, v2
	s_nop 0
	v_mul_f32_e32 v1, v2, v1
	v_mul_f32_e32 v0, v0, v1
	v_cvt_pk_bf16_f32 v0, v0, s0
	ds_write_b16 v138, v0 offset:10944
	v_mul_f32_e32 v0, v23, v23
	v_mul_f32_e32 v1, v39, v39
	v_fmac_f32_e32 v0, v7, v7
	v_fmac_f32_e32 v1, v55, v55
	v_add_f32_e32 v0, v0, v1
	ds_read_u16 v144, v138 offset:2816
	ds_read_u16 v145, v138 offset:2880
	ds_read_u16 v146, v138 offset:2944
	ds_read_u16 v147, v138 offset:3008
	s_nop 1
	v_add_f32_dpp v0, v0, v0 quad_perm:[1,0,3,2] row_mask:0xf bank_mask:0xf
	s_nop 1
	v_add_f32_dpp v0, v0, v0 quad_perm:[2,3,0,1] row_mask:0xf bank_mask:0xf
	s_nop 1
	v_add_f32_dpp v0, v0, v0 row_half_mirror row_mask:0xf bank_mask:0xf
	s_nop 1
	v_add_f32_dpp v0, v0, v0 row_mirror row_mask:0xf bank_mask:0xf
	s_waitcnt lgkmcnt(0)
; __device__ __forceinline__ int crow(int r, int hi) { return (r & 3) + 8 * (r >> 2) + 4 * hi; }
; __device__ __forceinline__ float bf2f(unsigned short v) { return __uint_as_float((unsigned)v << 16); }
; __device__ __forceinline__ unsigned f2bf(float f) { return pk2(f, 0.f) & 0xffffu; }
; __device__ __forceinline__ int crow(int r, int hi) { return (r & 3) + 8 * (r >> 2) + 4 * hi; }
; __device__ __forceinline__ void gla_pass_c(LAS unsigned char* ldsl, const bf16_t* __restrict__ proj, const float* __restrict__ Btab, const float* __restrict__ Gst, const float* __restrict__ gout, bf16_t* __restrict__ mixed) {
;     ...
;         for (int i = 0; i < 16; ++i) { const int tr = crow(i, hh);
;             const float tot = half_sum32((o[0][i] * o[0][i] + o[1][i] * o[1][i]) + (o[2][i] * o[2][i] + o[3][i] * o[3][i]));
;             const float rr = __builtin_amdgcn_rsqf(tot * (1.0f / 128.0f) + EPS);
; #pragma unroll
;             for (int dvb = 0; dvb < 4; ++dvb) { const float g = bf2f(Lh[tr * 128 + 32 * dvb + r]);
;                 const float val = o[dvb][i] * rr * gn[dvb] * (g * __builtin_amdgcn_rcpf(1.0f + __expf(-g)));
;                 Lh[(32 + tr) * 128 + 32 * dvb + r] = (bf16_t)f2bf(val); } }
	v_mov_b32_e32 v1, v0
	s_nop 1
	v_permlane16_swap_b32_e32 v0, v1
	v_add_f32_e32 v0, v0, v1
	v_fmamk_f32 v0, v0, 0x3c000000, v199
	v_rsq_f32_e32 v0, v0
	v_lshlrev_b32_e32 v1, 16, v144
	v_mul_f32_e32 v3, 0xbfb8aa3b, v1
	v_exp_f32_e32 v3, v3
	v_mul_f32_e32 v2, v7, v0
	v_mul_f32_e32 v2, v113, v2
	v_add_f32_e32 v3, 1.0, v3
	v_rcp_f32_e32 v3, v3
	s_nop 0
	v_mul_f32_e32 v1, v3, v1
	v_mul_f32_e32 v1, v2, v1
	v_cvt_pk_bf16_f32 v1, v1, s0
	ds_write_b16 v138, v1 offset:11008
	v_mul_f32_e32 v2, v23, v0
	v_mul_f32_e32 v2, v130, v2
	v_lshlrev_b32_e32 v1, 16, v145
	v_mul_f32_e32 v3, 0xbfb8aa3b, v1
	v_exp_f32_e32 v3, v3
	s_nop 0
	v_add_f32_e32 v3, 1.0, v3
	v_rcp_f32_e32 v3, v3
	s_nop 0
	v_mul_f32_e32 v1, v3, v1
	v_mul_f32_e32 v1, v2, v1
	v_cvt_pk_bf16_f32 v1, v1, s0
	ds_write_b16 v138, v1 offset:11072
	v_mul_f32_e32 v2, v55, v0
	v_mul_f32_e32 v2, v131, v2
	v_mul_f32_e32 v0, v39, v0
	v_mul_f32_e32 v0, v132, v0
	v_lshlrev_b32_e32 v1, 16, v146
	v_mul_f32_e32 v3, 0xbfb8aa3b, v1
	v_exp_f32_e32 v3, v3
	s_nop 0
	v_add_f32_e32 v3, 1.0, v3
	v_rcp_f32_e32 v3, v3
	s_nop 0
	v_mul_f32_e32 v1, v3, v1
	v_mul_f32_e32 v1, v2, v1
	v_cvt_pk_bf16_f32 v1, v1, s0
	ds_write_b16 v138, v1 offset:11136
	v_lshlrev_b32_e32 v1, 16, v147
	v_mul_f32_e32 v2, 0xbfb8aa3b, v1
	v_exp_f32_e32 v2, v2
	s_nop 0
	v_add_f32_e32 v2, 1.0, v2
	v_rcp_f32_e32 v2, v2
	s_nop 0
	v_mul_f32_e32 v1, v2, v1
	v_mul_f32_e32 v0, v0, v1
	v_cvt_pk_bf16_f32 v0, v0, s0
	ds_write_b16 v138, v0 offset:11200
	v_mul_f32_e32 v0, v24, v24
	v_mul_f32_e32 v1, v40, v40
	v_fmac_f32_e32 v0, v8, v8
	v_fmac_f32_e32 v1, v56, v56
	v_add_f32_e32 v0, v0, v1
	ds_read_u16 v144, v138 offset:4096
	ds_read_u16 v145, v138 offset:4160
	ds_read_u16 v146, v138 offset:4224
	ds_read_u16 v147, v138 offset:4288
	s_nop 1
	v_add_f32_dpp v0, v0, v0 quad_perm:[1,0,3,2] row_mask:0xf bank_mask:0xf
	s_nop 1
	v_add_f32_dpp v0, v0, v0 quad_perm:[2,3,0,1] row_mask:0xf bank_mask:0xf
	s_nop 1
	v_add_f32_dpp v0, v0, v0 row_half_mirror row_mask:0xf bank_mask:0xf
	s_nop 1
	v_add_f32_dpp v0, v0, v0 row_mirror row_mask:0xf bank_mask:0xf
	s_waitcnt lgkmcnt(0)
	v_mov_b32_e32 v1, v0
	s_nop 1
	v_permlane16_swap_b32_e32 v0, v1
	v_add_f32_e32 v0, v0, v1
	v_fmamk_f32 v0, v0, 0x3c000000, v199
	v_rsq_f32_e32 v0, v0
	v_lshlrev_b32_e32 v1, 16, v144
	v_mul_f32_e32 v3, 0xbfb8aa3b, v1
	v_exp_f32_e32 v3, v3
	v_mul_f32_e32 v2, v8, v0
	v_mul_f32_e32 v2, v113, v2
	v_add_f32_e32 v3, 1.0, v3
	v_rcp_f32_e32 v3, v3
	s_nop 0
	v_mul_f32_e32 v1, v3, v1
	v_mul_f32_e32 v1, v2, v1
	v_cvt_pk_bf16_f32 v1, v1, s0
	ds_write_b16 v138, v1 offset:12288
	v_mul_f32_e32 v2, v24, v0
	v_mul_f32_e32 v2, v130, v2
	v_lshlrev_b32_e32 v1, 16, v145
	v_mul_f32_e32 v3, 0xbfb8aa3b, v1
	v_exp_f32_e32 v3, v3
	s_nop 0
	v_add_f32_e32 v3, 1.0, v3
	v_rcp_f32_e32 v3, v3
	s_nop 0
	v_mul_f32_e32 v1, v3, v1
	v_mul_f32_e32 v1, v2, v1
	v_cvt_pk_bf16_f32 v1, v1, s0
	ds_write_b16 v138, v1 offset:12352
	v_mul_f32_e32 v2, v56, v0
	v_mul_f32_e32 v2, v131, v2
	v_mul_f32_e32 v0, v40, v0
	v_mul_f32_e32 v0, v132, v0
	v_lshlrev_b32_e32 v1, 16, v146
	v_mul_f32_e32 v3, 0xbfb8aa3b, v1
	v_exp_f32_e32 v3, v3
	s_nop 0
	v_add_f32_e32 v3, 1.0, v3
	v_rcp_f32_e32 v3, v3
	s_nop 0
	v_mul_f32_e32 v1, v3, v1
	v_mul_f32_e32 v1, v2, v1
	v_cvt_pk_bf16_f32 v1, v1, s0
	ds_write_b16 v138, v1 offset:12416
	v_lshlrev_b32_e32 v1, 16, v147
	v_mul_f32_e32 v2, 0xbfb8aa3b, v1
	v_exp_f32_e32 v2, v2
	s_nop 0
	v_add_f32_e32 v2, 1.0, v2
	v_rcp_f32_e32 v2, v2
	s_nop 0
	v_mul_f32_e32 v1, v2, v1
	v_mul_f32_e32 v0, v0, v1
	v_cvt_pk_bf16_f32 v0, v0, s0
	ds_write_b16 v138, v0 offset:12480
	v_mul_f32_e32 v0, v25, v25
	v_mul_f32_e32 v1, v41, v41
	v_fmac_f32_e32 v0, v9, v9
	v_fmac_f32_e32 v1, v57, v57
	v_add_f32_e32 v0, v0, v1
	ds_read_u16 v144, v138 offset:4352
	ds_read_u16 v145, v138 offset:4416
	ds_read_u16 v146, v138 offset:4480
	ds_read_u16 v147, v138 offset:4544
	s_nop 1
	v_add_f32_dpp v0, v0, v0 quad_perm:[1,0,3,2] row_mask:0xf bank_mask:0xf
	s_nop 1
	v_add_f32_dpp v0, v0, v0 quad_perm:[2,3,0,1] row_mask:0xf bank_mask:0xf
	s_nop 1
	v_add_f32_dpp v0, v0, v0 row_half_mirror row_mask:0xf bank_mask:0xf
	s_nop 1
	v_add_f32_dpp v0, v0, v0 row_mirror row_mask:0xf bank_mask:0xf
	s_waitcnt lgkmcnt(0)
	v_mov_b32_e32 v1, v0
	s_nop 1
	v_permlane16_swap_b32_e32 v0, v1
	v_add_f32_e32 v0, v0, v1
	v_fmamk_f32 v0, v0, 0x3c000000, v199
	v_rsq_f32_e32 v0, v0
	v_lshlrev_b32_e32 v1, 16, v144
	v_mul_f32_e32 v3, 0xbfb8aa3b, v1
	v_exp_f32_e32 v3, v3
	v_mul_f32_e32 v2, v9, v0
	v_mul_f32_e32 v2, v113, v2
	v_add_f32_e32 v3, 1.0, v3
	v_rcp_f32_e32 v3, v3
	s_nop 0
	v_mul_f32_e32 v1, v3, v1
	v_mul_f32_e32 v1, v2, v1
	v_cvt_pk_bf16_f32 v1, v1, s0
	ds_write_b16 v138, v1 offset:12544
	v_mul_f32_e32 v2, v25, v0
	v_mul_f32_e32 v2, v130, v2
	v_lshlrev_b32_e32 v1, 16, v145
	v_mul_f32_e32 v3, 0xbfb8aa3b, v1
	v_exp_f32_e32 v3, v3
	s_nop 0
	v_add_f32_e32 v3, 1.0, v3
	v_rcp_f32_e32 v3, v3
	s_nop 0
	v_mul_f32_e32 v1, v3, v1
	v_mul_f32_e32 v1, v2, v1
	v_cvt_pk_bf16_f32 v1, v1, s0
	ds_write_b16 v138, v1 offset:12608
	v_mul_f32_e32 v2, v57, v0
	v_mul_f32_e32 v2, v131, v2
	v_mul_f32_e32 v0, v41, v0
	v_mul_f32_e32 v0, v132, v0
	v_lshlrev_b32_e32 v1, 16, v146
	v_mul_f32_e32 v3, 0xbfb8aa3b, v1
	v_exp_f32_e32 v3, v3
	s_nop 0
	v_add_f32_e32 v3, 1.0, v3
	v_rcp_f32_e32 v3, v3
	s_nop 0
	v_mul_f32_e32 v1, v3, v1
	v_mul_f32_e32 v1, v2, v1
	v_cvt_pk_bf16_f32 v1, v1, s0
	ds_write_b16 v138, v1 offset:12672
	v_lshlrev_b32_e32 v1, 16, v147
	v_mul_f32_e32 v2, 0xbfb8aa3b, v1
	v_exp_f32_e32 v2, v2
	s_nop 0
	v_add_f32_e32 v2, 1.0, v2
	v_rcp_f32_e32 v2, v2
	s_nop 0
	v_mul_f32_e32 v1, v2, v1
	v_mul_f32_e32 v0, v0, v1
	v_cvt_pk_bf16_f32 v0, v0, s0
	ds_write_b16 v138, v0 offset:12736
	v_mul_f32_e32 v0, v26, v26
	v_mul_f32_e32 v1, v42, v42
	v_fmac_f32_e32 v0, v10, v10
	v_fmac_f32_e32 v1, v58, v58
	v_add_f32_e32 v0, v0, v1
	ds_read_u16 v144, v138 offset:4608
	ds_read_u16 v145, v138 offset:4672
	ds_read_u16 v146, v138 offset:4736
	ds_read_u16 v147, v138 offset:4800
	s_nop 1
	v_add_f32_dpp v0, v0, v0 quad_perm:[1,0,3,2] row_mask:0xf bank_mask:0xf
	s_nop 1
	v_add_f32_dpp v0, v0, v0 quad_perm:[2,3,0,1] row_mask:0xf bank_mask:0xf
	s_nop 1
	v_add_f32_dpp v0, v0, v0 row_half_mirror row_mask:0xf bank_mask:0xf
	s_nop 1
	v_add_f32_dpp v0, v0, v0 row_mirror row_mask:0xf bank_mask:0xf
	s_waitcnt lgkmcnt(0)
; __device__ __forceinline__ int crow(int r, int hi) { return (r & 3) + 8 * (r >> 2) + 4 * hi; }
; __device__ __forceinline__ float bf2f(unsigned short v) { return __uint_as_float((unsigned)v << 16); }
; __device__ __forceinline__ unsigned f2bf(float f) { return pk2(f, 0.f) & 0xffffu; }
; __device__ __forceinline__ int crow(int r, int hi) { return (r & 3) + 8 * (r >> 2) + 4 * hi; }
; __device__ __forceinline__ void gla_pass_c(LAS unsigned char* ldsl, const bf16_t* __restrict__ proj, const float* __restrict__ Btab, const float* __restrict__ Gst, const float* __restrict__ gout, bf16_t* __restrict__ mixed) {
;     ...
;         for (int i = 0; i < 16; ++i) { const int tr = crow(i, hh);
;             const float tot = half_sum32((o[0][i] * o[0][i] + o[1][i] * o[1][i]) + (o[2][i] * o[2][i] + o[3][i] * o[3][i]));
;             const float rr = __builtin_amdgcn_rsqf(tot * (1.0f / 128.0f) + EPS);
; #pragma unroll
;             for (int dvb = 0; dvb < 4; ++dvb) { const float g = bf2f(Lh[tr * 128 + 32 * dvb + r]);
;                 const float val = o[dvb][i] * rr * gn[dvb] * (g * __builtin_amdgcn_rcpf(1.0f + __expf(-g)));
;                 Lh[(32 + tr) * 128 + 32 * dvb + r] = (bf16_t)f2bf(val); } }
	v_mov_b32_e32 v1, v0
	s_nop 1
	v_permlane16_swap_b32_e32 v0, v1
	v_add_f32_e32 v0, v0, v1
	v_fmamk_f32 v0, v0, 0x3c000000, v199
	v_rsq_f32_e32 v0, v0
	v_lshlrev_b32_e32 v1, 16, v144
	v_mul_f32_e32 v3, 0xbfb8aa3b, v1
	v_exp_f32_e32 v3, v3
	v_mul_f32_e32 v2, v10, v0
	v_mul_f32_e32 v2, v113, v2
	v_add_f32_e32 v3, 1.0, v3
	v_rcp_f32_e32 v3, v3
	s_nop 0
	v_mul_f32_e32 v1, v3, v1
	v_mul_f32_e32 v1, v2, v1
	v_cvt_pk_bf16_f32 v1, v1, s0
	ds_write_b16 v138, v1 offset:12800
	v_mul_f32_e32 v2, v26, v0
	v_mul_f32_e32 v2, v130, v2
	v_lshlrev_b32_e32 v1, 16, v145
	v_mul_f32_e32 v3, 0xbfb8aa3b, v1
	v_exp_f32_e32 v3, v3
	s_nop 0
	v_add_f32_e32 v3, 1.0, v3
	v_rcp_f32_e32 v3, v3
	s_nop 0
	v_mul_f32_e32 v1, v3, v1
	v_mul_f32_e32 v1, v2, v1
	v_cvt_pk_bf16_f32 v1, v1, s0
	ds_write_b16 v138, v1 offset:12864
	v_mul_f32_e32 v2, v58, v0
	v_mul_f32_e32 v2, v131, v2
	v_mul_f32_e32 v0, v42, v0
	v_mul_f32_e32 v0, v132, v0
	v_lshlrev_b32_e32 v1, 16, v146
	v_mul_f32_e32 v3, 0xbfb8aa3b, v1
	v_exp_f32_e32 v3, v3
	s_nop 0
	v_add_f32_e32 v3, 1.0, v3
	v_rcp_f32_e32 v3, v3
	s_nop 0
	v_mul_f32_e32 v1, v3, v1
	v_mul_f32_e32 v1, v2, v1
	v_cvt_pk_bf16_f32 v1, v1, s0
	ds_write_b16 v138, v1 offset:12928
	v_lshlrev_b32_e32 v1, 16, v147
	v_mul_f32_e32 v2, 0xbfb8aa3b, v1
	v_exp_f32_e32 v2, v2
	s_nop 0
	v_add_f32_e32 v2, 1.0, v2
	v_rcp_f32_e32 v2, v2
	s_nop 0
	v_mul_f32_e32 v1, v2, v1
	v_mul_f32_e32 v0, v0, v1
	v_cvt_pk_bf16_f32 v0, v0, s0
	ds_write_b16 v138, v0 offset:12992
	v_mul_f32_e32 v0, v27, v27
	v_mul_f32_e32 v1, v43, v43
	v_fmac_f32_e32 v0, v11, v11
	v_fmac_f32_e32 v1, v59, v59
	v_add_f32_e32 v0, v0, v1
	ds_read_u16 v144, v138 offset:4864
	ds_read_u16 v145, v138 offset:4928
	ds_read_u16 v146, v138 offset:4992
	ds_read_u16 v147, v138 offset:5056
	s_nop 1
	v_add_f32_dpp v0, v0, v0 quad_perm:[1,0,3,2] row_mask:0xf bank_mask:0xf
	s_nop 1
	v_add_f32_dpp v0, v0, v0 quad_perm:[2,3,0,1] row_mask:0xf bank_mask:0xf
	s_nop 1
	v_add_f32_dpp v0, v0, v0 row_half_mirror row_mask:0xf bank_mask:0xf
	s_nop 1
	v_add_f32_dpp v0, v0, v0 row_mirror row_mask:0xf bank_mask:0xf
	s_waitcnt lgkmcnt(0)
	v_mov_b32_e32 v1, v0
	s_nop 1
	v_permlane16_swap_b32_e32 v0, v1
	v_add_f32_e32 v0, v0, v1
	v_fmamk_f32 v0, v0, 0x3c000000, v199
	v_rsq_f32_e32 v0, v0
	v_lshlrev_b32_e32 v1, 16, v144
	v_mul_f32_e32 v3, 0xbfb8aa3b, v1
	v_exp_f32_e32 v3, v3
	v_mul_f32_e32 v2, v11, v0
	v_mul_f32_e32 v2, v113, v2
	v_add_f32_e32 v3, 1.0, v3
	v_rcp_f32_e32 v3, v3
	s_nop 0
	v_mul_f32_e32 v1, v3, v1
	v_mul_f32_e32 v1, v2, v1
	v_cvt_pk_bf16_f32 v1, v1, s0
	ds_write_b16 v138, v1 offset:13056
	v_mul_f32_e32 v2, v27, v0
	v_mul_f32_e32 v2, v130, v2
	v_lshlrev_b32_e32 v1, 16, v145
	v_mul_f32_e32 v3, 0xbfb8aa3b, v1
	v_exp_f32_e32 v3, v3
	s_nop 0
	v_add_f32_e32 v3, 1.0, v3
	v_rcp_f32_e32 v3, v3
	s_nop 0
	v_mul_f32_e32 v1, v3, v1
	v_mul_f32_e32 v1, v2, v1
	v_cvt_pk_bf16_f32 v1, v1, s0
	ds_write_b16 v138, v1 offset:13120
	v_mul_f32_e32 v2, v59, v0
	v_mul_f32_e32 v2, v131, v2
	v_mul_f32_e32 v0, v43, v0
	v_mul_f32_e32 v0, v132, v0
	v_lshlrev_b32_e32 v1, 16, v146
	v_mul_f32_e32 v3, 0xbfb8aa3b, v1
	v_exp_f32_e32 v3, v3
	s_nop 0
	v_add_f32_e32 v3, 1.0, v3
	v_rcp_f32_e32 v3, v3
	s_nop 0
	v_mul_f32_e32 v1, v3, v1
	v_mul_f32_e32 v1, v2, v1
	v_cvt_pk_bf16_f32 v1, v1, s0
	ds_write_b16 v138, v1 offset:13184
	v_lshlrev_b32_e32 v1, 16, v147
	v_mul_f32_e32 v2, 0xbfb8aa3b, v1
	v_exp_f32_e32 v2, v2
	s_nop 0
	v_add_f32_e32 v2, 1.0, v2
	v_rcp_f32_e32 v2, v2
	s_nop 0
	v_mul_f32_e32 v1, v2, v1
	v_mul_f32_e32 v0, v0, v1
	v_cvt_pk_bf16_f32 v0, v0, s0
	ds_write_b16 v138, v0 offset:13248
	v_mul_f32_e32 v0, v28, v28
	v_mul_f32_e32 v1, v44, v44
	v_fmac_f32_e32 v0, v12, v12
	v_fmac_f32_e32 v1, v60, v60
	v_add_f32_e32 v0, v0, v1
	ds_read_u16 v144, v138 offset:6144
	ds_read_u16 v145, v138 offset:6208
	ds_read_u16 v146, v138 offset:6272
	ds_read_u16 v147, v138 offset:6336
	s_nop 1
	v_add_f32_dpp v0, v0, v0 quad_perm:[1,0,3,2] row_mask:0xf bank_mask:0xf
	s_nop 1
	v_add_f32_dpp v0, v0, v0 quad_perm:[2,3,0,1] row_mask:0xf bank_mask:0xf
	s_nop 1
	v_add_f32_dpp v0, v0, v0 row_half_mirror row_mask:0xf bank_mask:0xf
	s_nop 1
	v_add_f32_dpp v0, v0, v0 row_mirror row_mask:0xf bank_mask:0xf
	s_waitcnt lgkmcnt(0)
	v_mov_b32_e32 v1, v0
	s_nop 1
	v_permlane16_swap_b32_e32 v0, v1
	v_add_f32_e32 v0, v0, v1
	v_fmamk_f32 v0, v0, 0x3c000000, v199
	v_rsq_f32_e32 v0, v0
	v_lshlrev_b32_e32 v1, 16, v144
	v_mul_f32_e32 v3, 0xbfb8aa3b, v1
	v_exp_f32_e32 v3, v3
	v_mul_f32_e32 v2, v12, v0
	v_mul_f32_e32 v2, v113, v2
	v_add_f32_e32 v3, 1.0, v3
	v_rcp_f32_e32 v3, v3
	s_nop 0
	v_mul_f32_e32 v1, v3, v1
	v_mul_f32_e32 v1, v2, v1
	v_cvt_pk_bf16_f32 v1, v1, s0
	ds_write_b16 v138, v1 offset:14336
	v_mul_f32_e32 v2, v28, v0
	v_mul_f32_e32 v2, v130, v2
	v_lshlrev_b32_e32 v1, 16, v145
	v_mul_f32_e32 v3, 0xbfb8aa3b, v1
	v_exp_f32_e32 v3, v3
	s_nop 0
	v_add_f32_e32 v3, 1.0, v3
	v_rcp_f32_e32 v3, v3
	s_nop 0
	v_mul_f32_e32 v1, v3, v1
	v_mul_f32_e32 v1, v2, v1
	v_cvt_pk_bf16_f32 v1, v1, s0
	ds_write_b16 v138, v1 offset:14400
	v_mul_f32_e32 v2, v60, v0
	v_mul_f32_e32 v2, v131, v2
	v_mul_f32_e32 v0, v44, v0
	v_mul_f32_e32 v0, v132, v0
	v_lshlrev_b32_e32 v1, 16, v146
	v_mul_f32_e32 v3, 0xbfb8aa3b, v1
	v_exp_f32_e32 v3, v3
	s_nop 0
	v_add_f32_e32 v3, 1.0, v3
	v_rcp_f32_e32 v3, v3
	s_nop 0
	v_mul_f32_e32 v1, v3, v1
	v_mul_f32_e32 v1, v2, v1
	v_cvt_pk_bf16_f32 v1, v1, s0
	ds_write_b16 v138, v1 offset:14464
	v_lshlrev_b32_e32 v1, 16, v147
	v_mul_f32_e32 v2, 0xbfb8aa3b, v1
	v_exp_f32_e32 v2, v2
	s_nop 0
	v_add_f32_e32 v2, 1.0, v2
	v_rcp_f32_e32 v2, v2
	s_nop 0
	v_mul_f32_e32 v1, v2, v1
	v_mul_f32_e32 v0, v0, v1
	v_cvt_pk_bf16_f32 v0, v0, s0
	ds_write_b16 v138, v0 offset:14528
	v_mul_f32_e32 v0, v29, v29
	v_mul_f32_e32 v1, v45, v45
	v_fmac_f32_e32 v0, v13, v13
	v_fmac_f32_e32 v1, v61, v61
	v_add_f32_e32 v0, v0, v1
	ds_read_u16 v144, v138 offset:6400
	ds_read_u16 v145, v138 offset:6464
	ds_read_u16 v146, v138 offset:6528
	ds_read_u16 v147, v138 offset:6592
	s_nop 1
	v_add_f32_dpp v0, v0, v0 quad_perm:[1,0,3,2] row_mask:0xf bank_mask:0xf
	s_nop 1
	v_add_f32_dpp v0, v0, v0 quad_perm:[2,3,0,1] row_mask:0xf bank_mask:0xf
	s_nop 1
	v_add_f32_dpp v0, v0, v0 row_half_mirror row_mask:0xf bank_mask:0xf
	s_nop 1
	v_add_f32_dpp v0, v0, v0 row_mirror row_mask:0xf bank_mask:0xf
	s_waitcnt lgkmcnt(0)
; __device__ __forceinline__ int crow(int r, int hi) { return (r & 3) + 8 * (r >> 2) + 4 * hi; }
; __device__ __forceinline__ float bf2f(unsigned short v) { return __uint_as_float((unsigned)v << 16); }
; __device__ __forceinline__ unsigned f2bf(float f) { return pk2(f, 0.f) & 0xffffu; }
; __device__ __forceinline__ int crow(int r, int hi) { return (r & 3) + 8 * (r >> 2) + 4 * hi; }
; __device__ __forceinline__ void gla_pass_c(LAS unsigned char* ldsl, const bf16_t* __restrict__ proj, const float* __restrict__ Btab, const float* __restrict__ Gst, const float* __restrict__ gout, bf16_t* __restrict__ mixed) {
;     ...
;         for (int i = 0; i < 16; ++i) { const int tr = crow(i, hh);
;             const float tot = half_sum32((o[0][i] * o[0][i] + o[1][i] * o[1][i]) + (o[2][i] * o[2][i] + o[3][i] * o[3][i]));
;             const float rr = __builtin_amdgcn_rsqf(tot * (1.0f / 128.0f) + EPS);
; #pragma unroll
;             for (int dvb = 0; dvb < 4; ++dvb) { const float g = bf2f(Lh[tr * 128 + 32 * dvb + r]);
;                 const float val = o[dvb][i] * rr * gn[dvb] * (g * __builtin_amdgcn_rcpf(1.0f + __expf(-g)));
;                 Lh[(32 + tr) * 128 + 32 * dvb + r] = (bf16_t)f2bf(val); } }
	v_mov_b32_e32 v1, v0
	s_nop 1
	v_permlane16_swap_b32_e32 v0, v1
	v_add_f32_e32 v0, v0, v1
	v_fmamk_f32 v0, v0, 0x3c000000, v199
	v_rsq_f32_e32 v0, v0
	v_lshlrev_b32_e32 v1, 16, v144
	v_mul_f32_e32 v3, 0xbfb8aa3b, v1
	v_exp_f32_e32 v3, v3
	v_mul_f32_e32 v2, v13, v0
	v_mul_f32_e32 v2, v113, v2
	v_add_f32_e32 v3, 1.0, v3
	v_rcp_f32_e32 v3, v3
	s_nop 0
	v_mul_f32_e32 v1, v3, v1
	v_mul_f32_e32 v1, v2, v1
	v_cvt_pk_bf16_f32 v1, v1, s0
	ds_write_b16 v138, v1 offset:14592
	v_mul_f32_e32 v2, v29, v0
	v_mul_f32_e32 v2, v130, v2
	v_lshlrev_b32_e32 v1, 16, v145
	v_mul_f32_e32 v3, 0xbfb8aa3b, v1
	v_exp_f32_e32 v3, v3
	s_nop 0
	v_add_f32_e32 v3, 1.0, v3
	v_rcp_f32_e32 v3, v3
	s_nop 0
	v_mul_f32_e32 v1, v3, v1
	v_mul_f32_e32 v1, v2, v1
	v_cvt_pk_bf16_f32 v1, v1, s0
	ds_write_b16 v138, v1 offset:14656
	v_mul_f32_e32 v2, v61, v0
	v_mul_f32_e32 v2, v131, v2
	v_mul_f32_e32 v0, v45, v0
	v_mul_f32_e32 v0, v132, v0
	v_lshlrev_b32_e32 v1, 16, v146
	v_mul_f32_e32 v3, 0xbfb8aa3b, v1
	v_exp_f32_e32 v3, v3
	s_nop 0
	v_add_f32_e32 v3, 1.0, v3
	v_rcp_f32_e32 v3, v3
	s_nop 0
	v_mul_f32_e32 v1, v3, v1
	v_mul_f32_e32 v1, v2, v1
	v_cvt_pk_bf16_f32 v1, v1, s0
	ds_write_b16 v138, v1 offset:14720
	v_lshlrev_b32_e32 v1, 16, v147
	v_mul_f32_e32 v2, 0xbfb8aa3b, v1
	v_exp_f32_e32 v2, v2
	s_nop 0
	v_add_f32_e32 v2, 1.0, v2
	v_rcp_f32_e32 v2, v2
	s_nop 0
	v_mul_f32_e32 v1, v2, v1
	v_mul_f32_e32 v0, v0, v1
	v_cvt_pk_bf16_f32 v0, v0, s0
	ds_write_b16 v138, v0 offset:14784
	v_mul_f32_e32 v0, v30, v30
	v_mul_f32_e32 v1, v46, v46
	v_fmac_f32_e32 v0, v14, v14
	v_fmac_f32_e32 v1, v62, v62
	v_add_f32_e32 v0, v0, v1
	ds_read_u16 v144, v138 offset:6656
	ds_read_u16 v145, v138 offset:6720
	ds_read_u16 v146, v138 offset:6784
	ds_read_u16 v147, v138 offset:6848
	s_nop 1
	v_add_f32_dpp v0, v0, v0 quad_perm:[1,0,3,2] row_mask:0xf bank_mask:0xf
	s_nop 1
	v_add_f32_dpp v0, v0, v0 quad_perm:[2,3,0,1] row_mask:0xf bank_mask:0xf
	s_nop 1
	v_add_f32_dpp v0, v0, v0 row_half_mirror row_mask:0xf bank_mask:0xf
	s_nop 1
	v_add_f32_dpp v0, v0, v0 row_mirror row_mask:0xf bank_mask:0xf
	s_waitcnt lgkmcnt(0)
	v_mov_b32_e32 v1, v0
	s_nop 1
	v_permlane16_swap_b32_e32 v0, v1
	v_add_f32_e32 v0, v0, v1
	v_fmamk_f32 v0, v0, 0x3c000000, v199
	v_rsq_f32_e32 v0, v0
	v_lshlrev_b32_e32 v1, 16, v144
	v_mul_f32_e32 v3, 0xbfb8aa3b, v1
	v_exp_f32_e32 v3, v3
	v_mul_f32_e32 v2, v14, v0
	v_mul_f32_e32 v2, v113, v2
	v_add_f32_e32 v3, 1.0, v3
	v_rcp_f32_e32 v3, v3
	s_nop 0
	v_mul_f32_e32 v1, v3, v1
	v_mul_f32_e32 v1, v2, v1
	v_cvt_pk_bf16_f32 v1, v1, s0
	ds_write_b16 v138, v1 offset:14848
	v_mul_f32_e32 v2, v30, v0
	v_mul_f32_e32 v2, v130, v2
	v_lshlrev_b32_e32 v1, 16, v145
	v_mul_f32_e32 v3, 0xbfb8aa3b, v1
	v_exp_f32_e32 v3, v3
	s_nop 0
	v_add_f32_e32 v3, 1.0, v3
	v_rcp_f32_e32 v3, v3
	s_nop 0
	v_mul_f32_e32 v1, v3, v1
	v_mul_f32_e32 v1, v2, v1
	v_cvt_pk_bf16_f32 v1, v1, s0
	ds_write_b16 v138, v1 offset:14912
	v_mul_f32_e32 v2, v62, v0
	v_mul_f32_e32 v2, v131, v2
	v_mul_f32_e32 v0, v46, v0
	v_mul_f32_e32 v0, v132, v0
	v_lshlrev_b32_e32 v1, 16, v146
	v_mul_f32_e32 v3, 0xbfb8aa3b, v1
	v_exp_f32_e32 v3, v3
	s_nop 0
	v_add_f32_e32 v3, 1.0, v3
	v_rcp_f32_e32 v3, v3
	s_nop 0
	v_mul_f32_e32 v1, v3, v1
	v_mul_f32_e32 v1, v2, v1
	v_cvt_pk_bf16_f32 v1, v1, s0
	ds_write_b16 v138, v1 offset:14976
	v_lshlrev_b32_e32 v1, 16, v147
	v_mul_f32_e32 v2, 0xbfb8aa3b, v1
	v_exp_f32_e32 v2, v2
	s_nop 0
	v_add_f32_e32 v2, 1.0, v2
	v_rcp_f32_e32 v2, v2
	s_nop 0
	v_mul_f32_e32 v1, v2, v1
	v_mul_f32_e32 v0, v0, v1
	v_cvt_pk_bf16_f32 v0, v0, s0
	ds_write_b16 v138, v0 offset:15040
	v_mul_f32_e32 v0, v31, v31
	v_mul_f32_e32 v1, v47, v47
	v_fmac_f32_e32 v0, v15, v15
	v_fmac_f32_e32 v1, v63, v63
	v_add_f32_e32 v0, v0, v1
	ds_read_u16 v144, v138 offset:6912
	ds_read_u16 v145, v138 offset:6976
	ds_read_u16 v146, v138 offset:7040
	ds_read_u16 v147, v138 offset:7104
	s_nop 1
	v_add_f32_dpp v0, v0, v0 quad_perm:[1,0,3,2] row_mask:0xf bank_mask:0xf
	s_nop 1
	v_add_f32_dpp v0, v0, v0 quad_perm:[2,3,0,1] row_mask:0xf bank_mask:0xf
	s_nop 1
	v_add_f32_dpp v0, v0, v0 row_half_mirror row_mask:0xf bank_mask:0xf
	s_nop 1
	v_add_f32_dpp v0, v0, v0 row_mirror row_mask:0xf bank_mask:0xf
	s_waitcnt lgkmcnt(0)
; #define LAS __attribute__((address_space(3)))
; __device__ __forceinline__ int crow(int r, int hi) { return (r & 3) + 8 * (r >> 2) + 4 * hi; }
; __device__ __forceinline__ float bf2f(unsigned short v) { return __uint_as_float((unsigned)v << 16); }
; __device__ __forceinline__ unsigned f2bf(float f) { return pk2(f, 0.f) & 0xffffu; }
; __device__ __forceinline__ int crow(int r, int hi) { return (r & 3) + 8 * (r >> 2) + 4 * hi; }
; __device__ __forceinline__ void gla_pass_c(LAS unsigned char* ldsl, const bf16_t* __restrict__ proj, const float* __restrict__ Btab, const float* __restrict__ Gst, const float* __restrict__ gout, bf16_t* __restrict__ mixed) {
;     ...
;         for (int i = 0; i < 16; ++i) { const int tr = crow(i, hh);
;             const float tot = half_sum32((o[0][i] * o[0][i] + o[1][i] * o[1][i]) + (o[2][i] * o[2][i] + o[3][i] * o[3][i]));
;             const float rr = __builtin_amdgcn_rsqf(tot * (1.0f / 128.0f) + EPS);
; #pragma unroll
;             for (int dvb = 0; dvb < 4; ++dvb) { const float g = bf2f(Lh[tr * 128 + 32 * dvb + r]);
;                 const float val = o[dvb][i] * rr * gn[dvb] * (g * __builtin_amdgcn_rcpf(1.0f + __expf(-g)));
;                 Lh[(32 + tr) * 128 + 32 * dvb + r] = (bf16_t)f2bf(val); } }
;         { bf16_t* mp = mixed + (row0 + 32 * tb + crw) * DM + h * 128 + ccl * 8;
; #pragma unroll
;           for (int i = 0; i < 8; ++i) *(u32x4*)(mp + (size_t)(4 * i) * DM) = *(const LAS u32x4*)(Lw + (32 + 4 * i + crw) * 256 + ccl * 16); }
	v_mov_b32_e32 v1, v0
	s_nop 1
	v_permlane16_swap_b32_e32 v0, v1
	v_add_f32_e32 v0, v0, v1
	v_fmamk_f32 v0, v0, 0x3c000000, v199
	v_rsq_f32_e32 v0, v0
	v_lshlrev_b32_e32 v1, 16, v144
	v_mul_f32_e32 v3, 0xbfb8aa3b, v1
	v_exp_f32_e32 v3, v3
	v_mul_f32_e32 v2, v15, v0
	v_mul_f32_e32 v2, v113, v2
	v_add_f32_e32 v3, 1.0, v3
	v_rcp_f32_e32 v3, v3
	s_nop 0
	v_mul_f32_e32 v1, v3, v1
	v_mul_f32_e32 v1, v2, v1
	v_cvt_pk_bf16_f32 v1, v1, s0
	ds_write_b16 v138, v1 offset:15104
	v_mul_f32_e32 v2, v31, v0
	v_mul_f32_e32 v2, v130, v2
	v_lshlrev_b32_e32 v1, 16, v145
	v_mul_f32_e32 v3, 0xbfb8aa3b, v1
	v_exp_f32_e32 v3, v3
	s_nop 0
	v_add_f32_e32 v3, 1.0, v3
	v_rcp_f32_e32 v3, v3
	s_nop 0
	v_mul_f32_e32 v1, v3, v1
	v_mul_f32_e32 v1, v2, v1
	v_cvt_pk_bf16_f32 v1, v1, s0
	ds_write_b16 v138, v1 offset:15168
	v_mul_f32_e32 v2, v63, v0
	v_mul_f32_e32 v2, v131, v2
	v_mul_f32_e32 v0, v47, v0
	v_mul_f32_e32 v0, v132, v0
	v_lshlrev_b32_e32 v1, 16, v146
	v_mul_f32_e32 v3, 0xbfb8aa3b, v1
	v_exp_f32_e32 v3, v3
	s_nop 0
	v_add_f32_e32 v3, 1.0, v3
	v_rcp_f32_e32 v3, v3
	s_nop 0
	v_mul_f32_e32 v1, v3, v1
	v_mul_f32_e32 v1, v2, v1
	v_cvt_pk_bf16_f32 v1, v1, s0
	ds_write_b16 v138, v1 offset:15232
	v_lshlrev_b32_e32 v1, 16, v147
	v_mul_f32_e32 v2, 0xbfb8aa3b, v1
	v_exp_f32_e32 v2, v2
	s_nop 0
	v_add_f32_e32 v2, 1.0, v2
	v_rcp_f32_e32 v2, v2
	s_nop 0
	v_mul_f32_e32 v1, v2, v1
	v_mul_f32_e32 v0, v0, v1
	v_cvt_pk_bf16_f32 v0, v0, s0
	ds_write_b16 v138, v0 offset:15296
	v_lshlrev_b64 v[0:1], 11, v[122:123]
	v_lshl_add_u64 v[0:1], s[54:55], 0, v[0:1]
	v_lshl_add_u64 v[0:1], v[0:1], 0, v[160:161]
	v_lshl_add_u64 v[4:5], v[0:1], 0, v[120:121]
	ds_read_b128 v[0:3], v140 offset:8192
	v_add_co_u32_e32 v6, vcc, s2, v4
	s_movk_i32 s2, 0x6000
	s_nop 0
	v_addc_co_u32_e32 v7, vcc, 0, v5, vcc
	s_waitcnt lgkmcnt(0)
	global_store_dwordx4 v[4:5], v[0:3], off
	ds_read_b128 v[0:3], v140 offset:9216
	s_waitcnt lgkmcnt(0)
	global_store_dwordx4 v[6:7], v[0:3], off
	ds_read_b128 v[0:3], v140 offset:10240
	v_add_co_u32_e32 v6, vcc, s49, v4
	s_nop 1
	v_addc_co_u32_e32 v7, vcc, 0, v5, vcc
	s_waitcnt lgkmcnt(0)
	global_store_dwordx4 v[6:7], v[0:3], off
	ds_read_b128 v[0:3], v140 offset:11264
	v_add_co_u32_e32 v6, vcc, s2, v4
	s_mov_b32 s2, 0xa000
	s_nop 0
	v_addc_co_u32_e32 v7, vcc, 0, v5, vcc
	s_waitcnt lgkmcnt(0)
	global_store_dwordx4 v[6:7], v[0:3], off
	ds_read_b128 v[0:3], v140 offset:12288
	v_add_co_u32_e32 v6, vcc, s42, v4
	s_nop 1
	v_addc_co_u32_e32 v7, vcc, 0, v5, vcc
	s_waitcnt lgkmcnt(0)
	global_store_dwordx4 v[6:7], v[0:3], off
	ds_read_b128 v[0:3], v140 offset:13312
	v_add_co_u32_e32 v6, vcc, s2, v4
	s_movk_i32 s2, 0x7ff
	s_nop 0
	v_addc_co_u32_e32 v7, vcc, 0, v5, vcc
	s_waitcnt lgkmcnt(0)
	global_store_dwordx4 v[6:7], v[0:3], off
	ds_read_b128 v[0:3], v140 offset:14336
	v_add_co_u32_e32 v6, vcc, 0xc000, v4
	s_nop 1
	v_addc_co_u32_e32 v7, vcc, 0, v5, vcc
	s_waitcnt lgkmcnt(0)
	global_store_dwordx4 v[6:7], v[0:3], off
	ds_read_b128 v[0:3], v140 offset:15360
	v_add_co_u32_e32 v4, vcc, 0xe000, v4
	s_nop 1
	v_addc_co_u32_e32 v5, vcc, 0, v5, vcc
	s_waitcnt lgkmcnt(0)
	global_store_dwordx4 v[4:5], v[0:3], off
	v_cmp_lt_i32_e32 vcc, s2, v111
	s_or_b64 s[40:41], vcc, s[40:41]
	v_add_u32_e32 v0, 0x800, v111
	v_mov_b32_e32 v111, v0
	s_andn2_b64 exec, exec, s[40:41]
	s_cbranch_execz .LBB0_880
